# hand-written P6 conv+gelu epilogue (fused DPP taps, scalar gelu, 16B ACT stores) on top of P4/P5/P7a 16B epilogues
# speedup vs baseline: 1.0491x; 1.0491x over previous
.LBB0_724:
	v_mov_b32_e32 v134, v224
	v_mov_b32_e32 v135, v225
	s_lshl_b32 s11, s47, 8
	s_add_i32 s11, s11, s37
	v_add_u32_e32 v134, s11, v134
	s_lshl_b32 s11, s46, 8
	s_or_b32 s11, s11, s38
	s_cmp_lg_u32 s45, 0
	v_lshl_add_u32 v136, v135, 2, s11
	s_cselect_b64 s[20:21], -1, 0
	v_ashrrev_i32_e32 v137, 31, v136
	s_and_b64 vcc, exec, s[20:21]
	v_ashrrev_i32_e32 v135, 31, v134
	s_cbranch_vccz .LBB0_732
	v_and_b32_e32 v213, 1, v225
	v_lshlrev_b32_e32 v212, 1, v136
	v_mad_u32_u24 v212, v213, 24, v212
	v_lshlrev_b32_e32 v214, 12, v134
	v_add_u32_e32 v214, 0x800, v214
	v_add_u32_e32 v214, v214, v212
	v_mov_b32_e32 v215, 0
	v_lshl_add_u64 v[208:209], v[214:215], 0, s[4:5]
	v_lshlrev_b32_e32 v214, 11, v134
	v_add_u32_e32 v214, v214, v212
	v_lshl_add_u64 v[210:211], v[214:215], 0, s[6:7]
	s_mov_b32 s23, 0
	global_load_dwordx4 v[140:143], v[208:209], off
	global_load_dwordx4 v[144:147], v[208:209], off offset:256
	s_mov_b32 s22, 0x10000
	v_lshl_add_u64 v[208:209], v[208:209], 0, s[22:23]
	global_load_dwordx4 v[148:151], v[208:209], off
	global_load_dwordx4 v[152:155], v[208:209], off offset:256
	s_mov_b32 s22, 0x10000
	v_lshl_add_u64 v[208:209], v[208:209], 0, s[22:23]
	global_load_dwordx4 v[156:159], v[208:209], off
	global_load_dwordx4 v[160:163], v[208:209], off offset:256
	s_mov_b32 s22, 0x10000
	v_lshl_add_u64 v[208:209], v[208:209], 0, s[22:23]
	global_load_dwordx4 v[164:167], v[208:209], off
	global_load_dwordx4 v[168:171], v[208:209], off offset:256
	s_mov_b32 s22, 0x50000
	v_lshl_add_u64 v[208:209], v[208:209], 0, s[22:23]
	global_load_dwordx4 v[172:175], v[208:209], off
	global_load_dwordx4 v[176:179], v[208:209], off offset:256
	s_mov_b32 s22, 0x10000
	v_lshl_add_u64 v[208:209], v[208:209], 0, s[22:23]
	global_load_dwordx4 v[180:183], v[208:209], off
	global_load_dwordx4 v[184:187], v[208:209], off offset:256
	s_mov_b32 s22, 0x10000
	v_lshl_add_u64 v[208:209], v[208:209], 0, s[22:23]
	global_load_dwordx4 v[188:191], v[208:209], off
	global_load_dwordx4 v[192:195], v[208:209], off offset:256
	s_mov_b32 s22, 0x10000
	v_lshl_add_u64 v[208:209], v[208:209], 0, s[22:23]
	global_load_dwordx4 v[196:199], v[208:209], off
	global_load_dwordx4 v[204:207], v[208:209], off offset:256
	s_waitcnt vmcnt(15)
	v_permlane16_swap_b32_e32 v140, v142
	v_permlane16_swap_b32_e32 v141, v143
	v_lshlrev_b32_e32 v216, 16, v140
	v_and_b32_e32 v217, 0xffff0000, v140
	v_mul_f32_e32 v124, v124, v216
	v_mul_f32_e32 v125, v125, v217
	v_lshlrev_b32_e32 v216, 16, v141
	v_and_b32_e32 v217, 0xffff0000, v141
	v_mul_f32_e32 v126, v126, v216
	v_mul_f32_e32 v127, v127, v217
	v_lshlrev_b32_e32 v216, 16, v142
	v_and_b32_e32 v217, 0xffff0000, v142
	v_mul_f32_e32 v120, v120, v216
	v_mul_f32_e32 v121, v121, v217
	v_lshlrev_b32_e32 v216, 16, v143
	v_and_b32_e32 v217, 0xffff0000, v143
	v_mul_f32_e32 v122, v122, v216
	v_mul_f32_e32 v123, v123, v217
	v_cvt_pk_bf16_f32 v140, v124, v125
	v_cvt_pk_bf16_f32 v141, v126, v127
	v_cvt_pk_bf16_f32 v142, v120, v121
	v_cvt_pk_bf16_f32 v143, v122, v123
	s_nop 1
	v_permlane16_swap_b32_e32 v140, v142
	v_permlane16_swap_b32_e32 v141, v143
	global_store_dwordx4 v[210:211], v[140:143], off
	s_waitcnt vmcnt(15)
	v_permlane16_swap_b32_e32 v144, v146
	v_permlane16_swap_b32_e32 v145, v147
	v_lshlrev_b32_e32 v216, 16, v144
	v_and_b32_e32 v217, 0xffff0000, v144
	v_mul_f32_e32 v92, v92, v216
	v_mul_f32_e32 v93, v93, v217
	v_lshlrev_b32_e32 v216, 16, v145
	v_and_b32_e32 v217, 0xffff0000, v145
	v_mul_f32_e32 v94, v94, v216
	v_mul_f32_e32 v95, v95, v217
	v_lshlrev_b32_e32 v216, 16, v146
	v_and_b32_e32 v217, 0xffff0000, v146
	v_mul_f32_e32 v88, v88, v216
	v_mul_f32_e32 v89, v89, v217
	v_lshlrev_b32_e32 v216, 16, v147
	v_and_b32_e32 v217, 0xffff0000, v147
	v_mul_f32_e32 v90, v90, v216
	v_mul_f32_e32 v91, v91, v217
	v_cvt_pk_bf16_f32 v144, v92, v93
	v_cvt_pk_bf16_f32 v145, v94, v95
	v_cvt_pk_bf16_f32 v146, v88, v89
	v_cvt_pk_bf16_f32 v147, v90, v91
	s_nop 1
	v_permlane16_swap_b32_e32 v144, v146
	v_permlane16_swap_b32_e32 v145, v147
	global_store_dwordx4 v[210:211], v[144:147], off offset:256
	s_mov_b32 s22, 0x8000
	v_lshl_add_u64 v[210:211], v[210:211], 0, s[22:23]
	s_waitcnt vmcnt(15)
	v_permlane16_swap_b32_e32 v148, v150
	v_permlane16_swap_b32_e32 v149, v151
	v_lshlrev_b32_e32 v216, 16, v148
	v_and_b32_e32 v217, 0xffff0000, v148
	v_mul_f32_e32 v116, v116, v216
	v_mul_f32_e32 v117, v117, v217
	v_lshlrev_b32_e32 v216, 16, v149
	v_and_b32_e32 v217, 0xffff0000, v149
	v_mul_f32_e32 v118, v118, v216
	v_mul_f32_e32 v119, v119, v217
	v_lshlrev_b32_e32 v216, 16, v150
	v_and_b32_e32 v217, 0xffff0000, v150
	v_mul_f32_e32 v112, v112, v216
	v_mul_f32_e32 v113, v113, v217
	v_lshlrev_b32_e32 v216, 16, v151
	v_and_b32_e32 v217, 0xffff0000, v151
	v_mul_f32_e32 v114, v114, v216
	v_mul_f32_e32 v115, v115, v217
	v_cvt_pk_bf16_f32 v148, v116, v117
	v_cvt_pk_bf16_f32 v149, v118, v119
	v_cvt_pk_bf16_f32 v150, v112, v113
	v_cvt_pk_bf16_f32 v151, v114, v115
	s_nop 1
	v_permlane16_swap_b32_e32 v148, v150
	v_permlane16_swap_b32_e32 v149, v151
	global_store_dwordx4 v[210:211], v[148:151], off
	s_waitcnt vmcnt(15)
	v_permlane16_swap_b32_e32 v152, v154
	v_permlane16_swap_b32_e32 v153, v155
	v_lshlrev_b32_e32 v216, 16, v152
	v_and_b32_e32 v217, 0xffff0000, v152
	v_mul_f32_e32 v84, v84, v216
	v_mul_f32_e32 v85, v85, v217
	v_lshlrev_b32_e32 v216, 16, v153
	v_and_b32_e32 v217, 0xffff0000, v153
	v_mul_f32_e32 v86, v86, v216
	v_mul_f32_e32 v87, v87, v217
	v_lshlrev_b32_e32 v216, 16, v154
	v_and_b32_e32 v217, 0xffff0000, v154
	v_mul_f32_e32 v80, v80, v216
	v_mul_f32_e32 v81, v81, v217
	v_lshlrev_b32_e32 v216, 16, v155
	v_and_b32_e32 v217, 0xffff0000, v155
	v_mul_f32_e32 v82, v82, v216
	v_mul_f32_e32 v83, v83, v217
	v_cvt_pk_bf16_f32 v152, v84, v85
	v_cvt_pk_bf16_f32 v153, v86, v87
	v_cvt_pk_bf16_f32 v154, v80, v81
	v_cvt_pk_bf16_f32 v155, v82, v83
	s_nop 1
	v_permlane16_swap_b32_e32 v152, v154
	v_permlane16_swap_b32_e32 v153, v155
	global_store_dwordx4 v[210:211], v[152:155], off offset:256
	s_mov_b32 s22, 0x8000
	v_lshl_add_u64 v[210:211], v[210:211], 0, s[22:23]
	s_waitcnt vmcnt(15)
	v_permlane16_swap_b32_e32 v156, v158
	v_permlane16_swap_b32_e32 v157, v159
	v_lshlrev_b32_e32 v216, 16, v156
	v_and_b32_e32 v217, 0xffff0000, v156
	v_mul_f32_e32 v108, v108, v216
	v_mul_f32_e32 v109, v109, v217
	v_lshlrev_b32_e32 v216, 16, v157
	v_and_b32_e32 v217, 0xffff0000, v157
	v_mul_f32_e32 v110, v110, v216
	v_mul_f32_e32 v111, v111, v217
	v_lshlrev_b32_e32 v216, 16, v158
	v_and_b32_e32 v217, 0xffff0000, v158
	v_mul_f32_e32 v104, v104, v216
	v_mul_f32_e32 v105, v105, v217
	v_lshlrev_b32_e32 v216, 16, v159
	v_and_b32_e32 v217, 0xffff0000, v159
	v_mul_f32_e32 v106, v106, v216
	v_mul_f32_e32 v107, v107, v217
	v_cvt_pk_bf16_f32 v156, v108, v109
	v_cvt_pk_bf16_f32 v157, v110, v111
	v_cvt_pk_bf16_f32 v158, v104, v105
	v_cvt_pk_bf16_f32 v159, v106, v107
	s_nop 1
	v_permlane16_swap_b32_e32 v156, v158
	v_permlane16_swap_b32_e32 v157, v159
	global_store_dwordx4 v[210:211], v[156:159], off
	s_waitcnt vmcnt(15)
	v_permlane16_swap_b32_e32 v160, v162
	v_permlane16_swap_b32_e32 v161, v163
	v_lshlrev_b32_e32 v216, 16, v160
	v_and_b32_e32 v217, 0xffff0000, v160
	v_mul_f32_e32 v76, v76, v216
	v_mul_f32_e32 v77, v77, v217
	v_lshlrev_b32_e32 v216, 16, v161
	v_and_b32_e32 v217, 0xffff0000, v161
	v_mul_f32_e32 v78, v78, v216
	v_mul_f32_e32 v79, v79, v217
	v_lshlrev_b32_e32 v216, 16, v162
	v_and_b32_e32 v217, 0xffff0000, v162
	v_mul_f32_e32 v72, v72, v216
	v_mul_f32_e32 v73, v73, v217
	v_lshlrev_b32_e32 v216, 16, v163
	v_and_b32_e32 v217, 0xffff0000, v163
	v_mul_f32_e32 v74, v74, v216
	v_mul_f32_e32 v75, v75, v217
	v_cvt_pk_bf16_f32 v160, v76, v77
	v_cvt_pk_bf16_f32 v161, v78, v79
	v_cvt_pk_bf16_f32 v162, v72, v73
	v_cvt_pk_bf16_f32 v163, v74, v75
	s_nop 1
	v_permlane16_swap_b32_e32 v160, v162
	v_permlane16_swap_b32_e32 v161, v163
	global_store_dwordx4 v[210:211], v[160:163], off offset:256
	s_mov_b32 s22, 0x8000
	v_lshl_add_u64 v[210:211], v[210:211], 0, s[22:23]
	s_waitcnt vmcnt(15)
	v_permlane16_swap_b32_e32 v164, v166
	v_permlane16_swap_b32_e32 v165, v167
	v_lshlrev_b32_e32 v216, 16, v164
	v_and_b32_e32 v217, 0xffff0000, v164
	v_mul_f32_e32 v100, v100, v216
	v_mul_f32_e32 v101, v101, v217
	v_lshlrev_b32_e32 v216, 16, v165
	v_and_b32_e32 v217, 0xffff0000, v165
	v_mul_f32_e32 v102, v102, v216
	v_mul_f32_e32 v103, v103, v217
	v_lshlrev_b32_e32 v216, 16, v166
	v_and_b32_e32 v217, 0xffff0000, v166
	v_mul_f32_e32 v96, v96, v216
	v_mul_f32_e32 v97, v97, v217
	v_lshlrev_b32_e32 v216, 16, v167
	v_and_b32_e32 v217, 0xffff0000, v167
	v_mul_f32_e32 v98, v98, v216
	v_mul_f32_e32 v99, v99, v217
	v_cvt_pk_bf16_f32 v164, v100, v101
	v_cvt_pk_bf16_f32 v165, v102, v103
	v_cvt_pk_bf16_f32 v166, v96, v97
	v_cvt_pk_bf16_f32 v167, v98, v99
	s_nop 1
	v_permlane16_swap_b32_e32 v164, v166
	v_permlane16_swap_b32_e32 v165, v167
	global_store_dwordx4 v[210:211], v[164:167], off
	s_waitcnt vmcnt(15)
	v_permlane16_swap_b32_e32 v168, v170
	v_permlane16_swap_b32_e32 v169, v171
	v_lshlrev_b32_e32 v216, 16, v168
	v_and_b32_e32 v217, 0xffff0000, v168
	v_mul_f32_e32 v68, v68, v216
	v_mul_f32_e32 v69, v69, v217
	v_lshlrev_b32_e32 v216, 16, v169
	v_and_b32_e32 v217, 0xffff0000, v169
	v_mul_f32_e32 v70, v70, v216
	v_mul_f32_e32 v71, v71, v217
	v_lshlrev_b32_e32 v216, 16, v170
	v_and_b32_e32 v217, 0xffff0000, v170
	v_mul_f32_e32 v64, v64, v216
	v_mul_f32_e32 v65, v65, v217
	v_lshlrev_b32_e32 v216, 16, v171
	v_and_b32_e32 v217, 0xffff0000, v171
	v_mul_f32_e32 v66, v66, v216
	v_mul_f32_e32 v67, v67, v217
	v_cvt_pk_bf16_f32 v168, v68, v69
	v_cvt_pk_bf16_f32 v169, v70, v71
	v_cvt_pk_bf16_f32 v170, v64, v65
	v_cvt_pk_bf16_f32 v171, v66, v67
	s_nop 1
	v_permlane16_swap_b32_e32 v168, v170
	v_permlane16_swap_b32_e32 v169, v171
	global_store_dwordx4 v[210:211], v[168:171], off offset:256
	s_mov_b32 s22, 0x28000
	v_lshl_add_u64 v[210:211], v[210:211], 0, s[22:23]
	s_waitcnt vmcnt(15)
	v_permlane16_swap_b32_e32 v172, v174
	v_permlane16_swap_b32_e32 v173, v175
	v_lshlrev_b32_e32 v216, 16, v172
	v_and_b32_e32 v217, 0xffff0000, v172
	v_mul_f32_e32 v60, v60, v216
	v_mul_f32_e32 v61, v61, v217
	v_lshlrev_b32_e32 v216, 16, v173
	v_and_b32_e32 v217, 0xffff0000, v173
	v_mul_f32_e32 v62, v62, v216
	v_mul_f32_e32 v63, v63, v217
	v_lshlrev_b32_e32 v216, 16, v174
	v_and_b32_e32 v217, 0xffff0000, v174
	v_mul_f32_e32 v56, v56, v216
	v_mul_f32_e32 v57, v57, v217
	v_lshlrev_b32_e32 v216, 16, v175
	v_and_b32_e32 v217, 0xffff0000, v175
	v_mul_f32_e32 v58, v58, v216
	v_mul_f32_e32 v59, v59, v217
	v_cvt_pk_bf16_f32 v172, v60, v61
	v_cvt_pk_bf16_f32 v173, v62, v63
	v_cvt_pk_bf16_f32 v174, v56, v57
	v_cvt_pk_bf16_f32 v175, v58, v59
	s_nop 1
	v_permlane16_swap_b32_e32 v172, v174
	v_permlane16_swap_b32_e32 v173, v175
	global_store_dwordx4 v[210:211], v[172:175], off
	s_waitcnt vmcnt(15)
	v_permlane16_swap_b32_e32 v176, v178
	v_permlane16_swap_b32_e32 v177, v179
	v_lshlrev_b32_e32 v216, 16, v176
	v_and_b32_e32 v217, 0xffff0000, v176
	v_mul_f32_e32 v28, v28, v216
	v_mul_f32_e32 v29, v29, v217
	v_lshlrev_b32_e32 v216, 16, v177
	v_and_b32_e32 v217, 0xffff0000, v177
	v_mul_f32_e32 v30, v30, v216
	v_mul_f32_e32 v31, v31, v217
	v_lshlrev_b32_e32 v216, 16, v178
	v_and_b32_e32 v217, 0xffff0000, v178
	v_mul_f32_e32 v24, v24, v216
	v_mul_f32_e32 v25, v25, v217
	v_lshlrev_b32_e32 v216, 16, v179
	v_and_b32_e32 v217, 0xffff0000, v179
	v_mul_f32_e32 v26, v26, v216
	v_mul_f32_e32 v27, v27, v217
	v_cvt_pk_bf16_f32 v176, v28, v29
	v_cvt_pk_bf16_f32 v177, v30, v31
	v_cvt_pk_bf16_f32 v178, v24, v25
	v_cvt_pk_bf16_f32 v179, v26, v27
	s_nop 1
	v_permlane16_swap_b32_e32 v176, v178
	v_permlane16_swap_b32_e32 v177, v179
	global_store_dwordx4 v[210:211], v[176:179], off offset:256
	s_mov_b32 s22, 0x8000
	v_lshl_add_u64 v[210:211], v[210:211], 0, s[22:23]
	s_waitcnt vmcnt(15)
	v_permlane16_swap_b32_e32 v180, v182
	v_permlane16_swap_b32_e32 v181, v183
	v_lshlrev_b32_e32 v216, 16, v180
	v_and_b32_e32 v217, 0xffff0000, v180
	v_mul_f32_e32 v52, v52, v216
	v_mul_f32_e32 v53, v53, v217
	v_lshlrev_b32_e32 v216, 16, v181
	v_and_b32_e32 v217, 0xffff0000, v181
	v_mul_f32_e32 v54, v54, v216
	v_mul_f32_e32 v55, v55, v217
	v_lshlrev_b32_e32 v216, 16, v182
	v_and_b32_e32 v217, 0xffff0000, v182
	v_mul_f32_e32 v48, v48, v216
	v_mul_f32_e32 v49, v49, v217
	v_lshlrev_b32_e32 v216, 16, v183
	v_and_b32_e32 v217, 0xffff0000, v183
	v_mul_f32_e32 v50, v50, v216
	v_mul_f32_e32 v51, v51, v217
	v_cvt_pk_bf16_f32 v180, v52, v53
	v_cvt_pk_bf16_f32 v181, v54, v55
	v_cvt_pk_bf16_f32 v182, v48, v49
	v_cvt_pk_bf16_f32 v183, v50, v51
	s_nop 1
	v_permlane16_swap_b32_e32 v180, v182
	v_permlane16_swap_b32_e32 v181, v183
	global_store_dwordx4 v[210:211], v[180:183], off
	s_waitcnt vmcnt(15)
	v_permlane16_swap_b32_e32 v184, v186
	v_permlane16_swap_b32_e32 v185, v187
	v_lshlrev_b32_e32 v216, 16, v184
	v_and_b32_e32 v217, 0xffff0000, v184
	v_mul_f32_e32 v20, v20, v216
	v_mul_f32_e32 v21, v21, v217
	v_lshlrev_b32_e32 v216, 16, v185
	v_and_b32_e32 v217, 0xffff0000, v185
	v_mul_f32_e32 v22, v22, v216
	v_mul_f32_e32 v23, v23, v217
	v_lshlrev_b32_e32 v216, 16, v186
	v_and_b32_e32 v217, 0xffff0000, v186
	v_mul_f32_e32 v16, v16, v216
	v_mul_f32_e32 v17, v17, v217
	v_lshlrev_b32_e32 v216, 16, v187
	v_and_b32_e32 v217, 0xffff0000, v187
	v_mul_f32_e32 v18, v18, v216
	v_mul_f32_e32 v19, v19, v217
	v_cvt_pk_bf16_f32 v184, v20, v21
	v_cvt_pk_bf16_f32 v185, v22, v23
	v_cvt_pk_bf16_f32 v186, v16, v17
	v_cvt_pk_bf16_f32 v187, v18, v19
	s_nop 1
	v_permlane16_swap_b32_e32 v184, v186
	v_permlane16_swap_b32_e32 v185, v187
	global_store_dwordx4 v[210:211], v[184:187], off offset:256
	s_mov_b32 s22, 0x8000
	v_lshl_add_u64 v[210:211], v[210:211], 0, s[22:23]
	s_waitcnt vmcnt(15)
	v_permlane16_swap_b32_e32 v188, v190
	v_permlane16_swap_b32_e32 v189, v191
	v_lshlrev_b32_e32 v216, 16, v188
	v_and_b32_e32 v217, 0xffff0000, v188
	v_mul_f32_e32 v44, v44, v216
	v_mul_f32_e32 v45, v45, v217
	v_lshlrev_b32_e32 v216, 16, v189
	v_and_b32_e32 v217, 0xffff0000, v189
	v_mul_f32_e32 v46, v46, v216
	v_mul_f32_e32 v47, v47, v217
	v_lshlrev_b32_e32 v216, 16, v190
	v_and_b32_e32 v217, 0xffff0000, v190
	v_mul_f32_e32 v40, v40, v216
	v_mul_f32_e32 v41, v41, v217
	v_lshlrev_b32_e32 v216, 16, v191
	v_and_b32_e32 v217, 0xffff0000, v191
	v_mul_f32_e32 v42, v42, v216
	v_mul_f32_e32 v43, v43, v217
	v_cvt_pk_bf16_f32 v188, v44, v45
	v_cvt_pk_bf16_f32 v189, v46, v47
	v_cvt_pk_bf16_f32 v190, v40, v41
	v_cvt_pk_bf16_f32 v191, v42, v43
	s_nop 1
	v_permlane16_swap_b32_e32 v188, v190
	v_permlane16_swap_b32_e32 v189, v191
	global_store_dwordx4 v[210:211], v[188:191], off
	s_waitcnt vmcnt(15)
	v_permlane16_swap_b32_e32 v192, v194
	v_permlane16_swap_b32_e32 v193, v195
	v_lshlrev_b32_e32 v216, 16, v192
	v_and_b32_e32 v217, 0xffff0000, v192
	v_mul_f32_e32 v12, v12, v216
	v_mul_f32_e32 v13, v13, v217
	v_lshlrev_b32_e32 v216, 16, v193
	v_and_b32_e32 v217, 0xffff0000, v193
	v_mul_f32_e32 v14, v14, v216
	v_mul_f32_e32 v15, v15, v217
	v_lshlrev_b32_e32 v216, 16, v194
	v_and_b32_e32 v217, 0xffff0000, v194
	v_mul_f32_e32 v8, v8, v216
	v_mul_f32_e32 v9, v9, v217
	v_lshlrev_b32_e32 v216, 16, v195
	v_and_b32_e32 v217, 0xffff0000, v195
	v_mul_f32_e32 v10, v10, v216
	v_mul_f32_e32 v11, v11, v217
	v_cvt_pk_bf16_f32 v192, v12, v13
	v_cvt_pk_bf16_f32 v193, v14, v15
	v_cvt_pk_bf16_f32 v194, v8, v9
	v_cvt_pk_bf16_f32 v195, v10, v11
	s_nop 1
	v_permlane16_swap_b32_e32 v192, v194
	v_permlane16_swap_b32_e32 v193, v195
	global_store_dwordx4 v[210:211], v[192:195], off offset:256
	s_mov_b32 s22, 0x8000
	v_lshl_add_u64 v[210:211], v[210:211], 0, s[22:23]
	s_waitcnt vmcnt(15)
	v_permlane16_swap_b32_e32 v196, v198
	v_permlane16_swap_b32_e32 v197, v199
	v_lshlrev_b32_e32 v216, 16, v196
	v_and_b32_e32 v217, 0xffff0000, v196
	v_mul_f32_e32 v36, v36, v216
	v_mul_f32_e32 v37, v37, v217
	v_lshlrev_b32_e32 v216, 16, v197
	v_and_b32_e32 v217, 0xffff0000, v197
	v_mul_f32_e32 v38, v38, v216
	v_mul_f32_e32 v39, v39, v217
	v_lshlrev_b32_e32 v216, 16, v198
	v_and_b32_e32 v217, 0xffff0000, v198
	v_mul_f32_e32 v32, v32, v216
	v_mul_f32_e32 v33, v33, v217
	v_lshlrev_b32_e32 v216, 16, v199
	v_and_b32_e32 v217, 0xffff0000, v199
	v_mul_f32_e32 v34, v34, v216
	v_mul_f32_e32 v35, v35, v217
	v_cvt_pk_bf16_f32 v196, v36, v37
	v_cvt_pk_bf16_f32 v197, v38, v39
	v_cvt_pk_bf16_f32 v198, v32, v33
	v_cvt_pk_bf16_f32 v199, v34, v35
	s_nop 1
	v_permlane16_swap_b32_e32 v196, v198
	v_permlane16_swap_b32_e32 v197, v199
	global_store_dwordx4 v[210:211], v[196:199], off
	s_waitcnt vmcnt(15)
	v_permlane16_swap_b32_e32 v204, v206
	v_permlane16_swap_b32_e32 v205, v207
	v_lshlrev_b32_e32 v216, 16, v204
	v_and_b32_e32 v217, 0xffff0000, v204
	v_mul_f32_e32 v4, v4, v216
	v_mul_f32_e32 v5, v5, v217
	v_lshlrev_b32_e32 v216, 16, v205
	v_and_b32_e32 v217, 0xffff0000, v205
	v_mul_f32_e32 v6, v6, v216
	v_mul_f32_e32 v7, v7, v217
	v_lshlrev_b32_e32 v216, 16, v206
	v_and_b32_e32 v217, 0xffff0000, v206
	v_mul_f32_e32 v0, v0, v216
	v_mul_f32_e32 v1, v1, v217
	v_lshlrev_b32_e32 v216, 16, v207
	v_and_b32_e32 v217, 0xffff0000, v207
	v_mul_f32_e32 v2, v2, v216
	v_mul_f32_e32 v3, v3, v217
	v_cvt_pk_bf16_f32 v204, v4, v5
	v_cvt_pk_bf16_f32 v205, v6, v7
	v_cvt_pk_bf16_f32 v206, v0, v1
	v_cvt_pk_bf16_f32 v207, v2, v3
	s_nop 1
	v_permlane16_swap_b32_e32 v204, v206
	v_permlane16_swap_b32_e32 v205, v207
	global_store_dwordx4 v[210:211], v[204:207], off offset:256
	s_cbranch_execnz .LBB0_727
.LBB0_726:
	v_and_b32_e32 v213, 1, v225
	v_lshlrev_b32_e32 v212, 1, v136
	v_mad_u32_u24 v212, v213, 24, v212
	v_lshlrev_b32_e32 v214, 12, v134
	v_add_u32_e32 v214, v214, v212
	v_mov_b32_e32 v215, 0
	v_lshl_add_u64 v[208:209], v[214:215], 0, s[4:5]
	s_mov_b32 s23, 0
	s_mov_b32 s22, 0x80000
	v_lshl_add_u64 v[210:211], v[208:209], 0, s[22:23]
	s_mov_b32 s22, 0x10000
	global_load_dwordx4 v[140:143], v[208:209], off
	global_load_dwordx4 v[144:147], v[208:209], off offset:2048
	global_load_dwordx4 v[148:151], v[208:209], off offset:256
	global_load_dwordx4 v[152:155], v[208:209], off offset:2304
	v_lshl_add_u64 v[208:209], v[208:209], 0, s[22:23]
	global_load_dwordx4 v[156:159], v[208:209], off
	global_load_dwordx4 v[160:163], v[208:209], off offset:2048
	global_load_dwordx4 v[164:167], v[208:209], off offset:256
	global_load_dwordx4 v[168:171], v[208:209], off offset:2304
	v_lshl_add_u64 v[208:209], v[208:209], 0, s[22:23]
	global_load_dwordx4 v[172:175], v[208:209], off
	global_load_dwordx4 v[176:179], v[208:209], off offset:2048
	global_load_dwordx4 v[180:183], v[208:209], off offset:256
	global_load_dwordx4 v[184:187], v[208:209], off offset:2304
	v_lshl_add_u64 v[208:209], v[208:209], 0, s[22:23]
	global_load_dwordx4 v[188:191], v[208:209], off
	global_load_dwordx4 v[192:195], v[208:209], off offset:2048
	global_load_dwordx4 v[196:199], v[208:209], off offset:256
	global_load_dwordx4 v[204:207], v[208:209], off offset:2304
	s_waitcnt vmcnt(14)
	v_permlane16_swap_b32_e32 v140, v142
	v_permlane16_swap_b32_e32 v141, v143
	v_permlane16_swap_b32_e32 v144, v146
	v_permlane16_swap_b32_e32 v145, v147
	v_lshlrev_b32_e32 v216, 16, v144
	v_and_b32_e32 v217, 0xffff0000, v144
	v_lshlrev_b32_e32 v218, 16, v140
	v_and_b32_e32 v219, 0xffff0000, v140
	v_rcp_f32_e32 v216, v216
	v_rcp_f32_e32 v217, v217
	s_nop 0
	v_mul_f32_e32 v216, v218, v216
	v_mul_f32_e32 v217, v219, v217
	v_mul_f32_e32 v124, v124, v216
	v_mul_f32_e32 v125, v125, v217
	v_lshlrev_b32_e32 v216, 16, v145
	v_and_b32_e32 v217, 0xffff0000, v145
	v_lshlrev_b32_e32 v218, 16, v141
	v_and_b32_e32 v219, 0xffff0000, v141
	v_rcp_f32_e32 v216, v216
	v_rcp_f32_e32 v217, v217
	s_nop 0
	v_mul_f32_e32 v216, v218, v216
	v_mul_f32_e32 v217, v219, v217
	v_mul_f32_e32 v126, v126, v216
	v_mul_f32_e32 v127, v127, v217
	v_lshlrev_b32_e32 v216, 16, v146
	v_and_b32_e32 v217, 0xffff0000, v146
	v_lshlrev_b32_e32 v218, 16, v142
	v_and_b32_e32 v219, 0xffff0000, v142
	v_rcp_f32_e32 v216, v216
	v_rcp_f32_e32 v217, v217
	s_nop 0
	v_mul_f32_e32 v216, v218, v216
	v_mul_f32_e32 v217, v219, v217
	v_mul_f32_e32 v120, v120, v216
	v_mul_f32_e32 v121, v121, v217
	v_lshlrev_b32_e32 v216, 16, v147
	v_and_b32_e32 v217, 0xffff0000, v147
	v_lshlrev_b32_e32 v218, 16, v143
	v_and_b32_e32 v219, 0xffff0000, v143
	v_rcp_f32_e32 v216, v216
	v_rcp_f32_e32 v217, v217
	s_nop 0
	v_mul_f32_e32 v216, v218, v216
	v_mul_f32_e32 v217, v219, v217
	v_mul_f32_e32 v122, v122, v216
	v_mul_f32_e32 v123, v123, v217
	global_load_dwordx4 v[140:143], v[210:211], off
	global_load_dwordx4 v[144:147], v[210:211], off offset:2048
	s_waitcnt vmcnt(14)
	v_permlane16_swap_b32_e32 v148, v150
	v_permlane16_swap_b32_e32 v149, v151
	v_permlane16_swap_b32_e32 v152, v154
	v_permlane16_swap_b32_e32 v153, v155
	v_lshlrev_b32_e32 v216, 16, v152
	v_and_b32_e32 v217, 0xffff0000, v152
	v_lshlrev_b32_e32 v218, 16, v148
	v_and_b32_e32 v219, 0xffff0000, v148
	v_rcp_f32_e32 v216, v216
	v_rcp_f32_e32 v217, v217
	s_nop 0
	v_mul_f32_e32 v216, v218, v216
	v_mul_f32_e32 v217, v219, v217
	v_mul_f32_e32 v92, v92, v216
	v_mul_f32_e32 v93, v93, v217
	v_lshlrev_b32_e32 v216, 16, v153
	v_and_b32_e32 v217, 0xffff0000, v153
	v_lshlrev_b32_e32 v218, 16, v149
	v_and_b32_e32 v219, 0xffff0000, v149
	v_rcp_f32_e32 v216, v216
	v_rcp_f32_e32 v217, v217
	s_nop 0
	v_mul_f32_e32 v216, v218, v216
	v_mul_f32_e32 v217, v219, v217
	v_mul_f32_e32 v94, v94, v216
	v_mul_f32_e32 v95, v95, v217
	v_lshlrev_b32_e32 v216, 16, v154
	v_and_b32_e32 v217, 0xffff0000, v154
	v_lshlrev_b32_e32 v218, 16, v150
	v_and_b32_e32 v219, 0xffff0000, v150
	v_rcp_f32_e32 v216, v216
	v_rcp_f32_e32 v217, v217
	s_nop 0
	v_mul_f32_e32 v216, v218, v216
	v_mul_f32_e32 v217, v219, v217
	v_mul_f32_e32 v88, v88, v216
	v_mul_f32_e32 v89, v89, v217
	v_lshlrev_b32_e32 v216, 16, v155
	v_and_b32_e32 v217, 0xffff0000, v155
	v_lshlrev_b32_e32 v218, 16, v151
	v_and_b32_e32 v219, 0xffff0000, v151
	v_rcp_f32_e32 v216, v216
	v_rcp_f32_e32 v217, v217
	s_nop 0
	v_mul_f32_e32 v216, v218, v216
	v_mul_f32_e32 v217, v219, v217
	v_mul_f32_e32 v90, v90, v216
	v_mul_f32_e32 v91, v91, v217
	global_load_dwordx4 v[148:151], v[210:211], off offset:256
	global_load_dwordx4 v[152:155], v[210:211], off offset:2304
	v_lshl_add_u64 v[210:211], v[210:211], 0, s[22:23]
	s_waitcnt vmcnt(14)
	v_permlane16_swap_b32_e32 v156, v158
	v_permlane16_swap_b32_e32 v157, v159
	v_permlane16_swap_b32_e32 v160, v162
	v_permlane16_swap_b32_e32 v161, v163
	v_lshlrev_b32_e32 v216, 16, v160
	v_and_b32_e32 v217, 0xffff0000, v160
	v_lshlrev_b32_e32 v218, 16, v156
	v_and_b32_e32 v219, 0xffff0000, v156
	v_rcp_f32_e32 v216, v216
	v_rcp_f32_e32 v217, v217
	s_nop 0
	v_mul_f32_e32 v216, v218, v216
	v_mul_f32_e32 v217, v219, v217
	v_mul_f32_e32 v116, v116, v216
	v_mul_f32_e32 v117, v117, v217
	v_lshlrev_b32_e32 v216, 16, v161
	v_and_b32_e32 v217, 0xffff0000, v161
	v_lshlrev_b32_e32 v218, 16, v157
	v_and_b32_e32 v219, 0xffff0000, v157
	v_rcp_f32_e32 v216, v216
	v_rcp_f32_e32 v217, v217
	s_nop 0
	v_mul_f32_e32 v216, v218, v216
	v_mul_f32_e32 v217, v219, v217
	v_mul_f32_e32 v118, v118, v216
	v_mul_f32_e32 v119, v119, v217
	v_lshlrev_b32_e32 v216, 16, v162
	v_and_b32_e32 v217, 0xffff0000, v162
	v_lshlrev_b32_e32 v218, 16, v158
	v_and_b32_e32 v219, 0xffff0000, v158
	v_rcp_f32_e32 v216, v216
	v_rcp_f32_e32 v217, v217
	s_nop 0
	v_mul_f32_e32 v216, v218, v216
	v_mul_f32_e32 v217, v219, v217
	v_mul_f32_e32 v112, v112, v216
	v_mul_f32_e32 v113, v113, v217
	v_lshlrev_b32_e32 v216, 16, v163
	v_and_b32_e32 v217, 0xffff0000, v163
	v_lshlrev_b32_e32 v218, 16, v159
	v_and_b32_e32 v219, 0xffff0000, v159
	v_rcp_f32_e32 v216, v216
	v_rcp_f32_e32 v217, v217
	s_nop 0
	v_mul_f32_e32 v216, v218, v216
	v_mul_f32_e32 v217, v219, v217
	v_mul_f32_e32 v114, v114, v216
	v_mul_f32_e32 v115, v115, v217
	global_load_dwordx4 v[156:159], v[210:211], off
	global_load_dwordx4 v[160:163], v[210:211], off offset:2048
	s_waitcnt vmcnt(14)
	v_permlane16_swap_b32_e32 v164, v166
	v_permlane16_swap_b32_e32 v165, v167
	v_permlane16_swap_b32_e32 v168, v170
	v_permlane16_swap_b32_e32 v169, v171
	v_lshlrev_b32_e32 v216, 16, v168
	v_and_b32_e32 v217, 0xffff0000, v168
	v_lshlrev_b32_e32 v218, 16, v164
	v_and_b32_e32 v219, 0xffff0000, v164
	v_rcp_f32_e32 v216, v216
	v_rcp_f32_e32 v217, v217
	s_nop 0
	v_mul_f32_e32 v216, v218, v216
	v_mul_f32_e32 v217, v219, v217
	v_mul_f32_e32 v84, v84, v216
	v_mul_f32_e32 v85, v85, v217
	v_lshlrev_b32_e32 v216, 16, v169
	v_and_b32_e32 v217, 0xffff0000, v169
	v_lshlrev_b32_e32 v218, 16, v165
	v_and_b32_e32 v219, 0xffff0000, v165
	v_rcp_f32_e32 v216, v216
	v_rcp_f32_e32 v217, v217
	s_nop 0
	v_mul_f32_e32 v216, v218, v216
	v_mul_f32_e32 v217, v219, v217
	v_mul_f32_e32 v86, v86, v216
	v_mul_f32_e32 v87, v87, v217
	v_lshlrev_b32_e32 v216, 16, v170
	v_and_b32_e32 v217, 0xffff0000, v170
	v_lshlrev_b32_e32 v218, 16, v166
	v_and_b32_e32 v219, 0xffff0000, v166
	v_rcp_f32_e32 v216, v216
	v_rcp_f32_e32 v217, v217
	s_nop 0
	v_mul_f32_e32 v216, v218, v216
	v_mul_f32_e32 v217, v219, v217
	v_mul_f32_e32 v80, v80, v216
	v_mul_f32_e32 v81, v81, v217
	v_lshlrev_b32_e32 v216, 16, v171
	v_and_b32_e32 v217, 0xffff0000, v171
	v_lshlrev_b32_e32 v218, 16, v167
	v_and_b32_e32 v219, 0xffff0000, v167
	v_rcp_f32_e32 v216, v216
	v_rcp_f32_e32 v217, v217
	s_nop 0
	v_mul_f32_e32 v216, v218, v216
	v_mul_f32_e32 v217, v219, v217
	v_mul_f32_e32 v82, v82, v216
	v_mul_f32_e32 v83, v83, v217
	global_load_dwordx4 v[164:167], v[210:211], off offset:256
	global_load_dwordx4 v[168:171], v[210:211], off offset:2304
	v_lshl_add_u64 v[210:211], v[210:211], 0, s[22:23]
	s_waitcnt vmcnt(14)
	v_permlane16_swap_b32_e32 v172, v174
	v_permlane16_swap_b32_e32 v173, v175
	v_permlane16_swap_b32_e32 v176, v178
	v_permlane16_swap_b32_e32 v177, v179
	v_lshlrev_b32_e32 v216, 16, v176
	v_and_b32_e32 v217, 0xffff0000, v176
	v_lshlrev_b32_e32 v218, 16, v172
	v_and_b32_e32 v219, 0xffff0000, v172
	v_rcp_f32_e32 v216, v216
	v_rcp_f32_e32 v217, v217
	s_nop 0
	v_mul_f32_e32 v216, v218, v216
	v_mul_f32_e32 v217, v219, v217
	v_mul_f32_e32 v108, v108, v216
	v_mul_f32_e32 v109, v109, v217
	v_lshlrev_b32_e32 v216, 16, v177
	v_and_b32_e32 v217, 0xffff0000, v177
	v_lshlrev_b32_e32 v218, 16, v173
	v_and_b32_e32 v219, 0xffff0000, v173
	v_rcp_f32_e32 v216, v216
	v_rcp_f32_e32 v217, v217
	s_nop 0
	v_mul_f32_e32 v216, v218, v216
	v_mul_f32_e32 v217, v219, v217
	v_mul_f32_e32 v110, v110, v216
	v_mul_f32_e32 v111, v111, v217
	v_lshlrev_b32_e32 v216, 16, v178
	v_and_b32_e32 v217, 0xffff0000, v178
	v_lshlrev_b32_e32 v218, 16, v174
	v_and_b32_e32 v219, 0xffff0000, v174
	v_rcp_f32_e32 v216, v216
	v_rcp_f32_e32 v217, v217
	s_nop 0
	v_mul_f32_e32 v216, v218, v216
	v_mul_f32_e32 v217, v219, v217
	v_mul_f32_e32 v104, v104, v216
	v_mul_f32_e32 v105, v105, v217
	v_lshlrev_b32_e32 v216, 16, v179
	v_and_b32_e32 v217, 0xffff0000, v179
	v_lshlrev_b32_e32 v218, 16, v175
	v_and_b32_e32 v219, 0xffff0000, v175
	v_rcp_f32_e32 v216, v216
	v_rcp_f32_e32 v217, v217
	s_nop 0
	v_mul_f32_e32 v216, v218, v216
	v_mul_f32_e32 v217, v219, v217
	v_mul_f32_e32 v106, v106, v216
	v_mul_f32_e32 v107, v107, v217
	global_load_dwordx4 v[172:175], v[210:211], off
	global_load_dwordx4 v[176:179], v[210:211], off offset:2048
	s_waitcnt vmcnt(14)
	v_permlane16_swap_b32_e32 v180, v182
	v_permlane16_swap_b32_e32 v181, v183
	v_permlane16_swap_b32_e32 v184, v186
	v_permlane16_swap_b32_e32 v185, v187
	v_lshlrev_b32_e32 v216, 16, v184
	v_and_b32_e32 v217, 0xffff0000, v184
	v_lshlrev_b32_e32 v218, 16, v180
	v_and_b32_e32 v219, 0xffff0000, v180
	v_rcp_f32_e32 v216, v216
	v_rcp_f32_e32 v217, v217
	s_nop 0
	v_mul_f32_e32 v216, v218, v216
	v_mul_f32_e32 v217, v219, v217
	v_mul_f32_e32 v76, v76, v216
	v_mul_f32_e32 v77, v77, v217
	v_lshlrev_b32_e32 v216, 16, v185
	v_and_b32_e32 v217, 0xffff0000, v185
	v_lshlrev_b32_e32 v218, 16, v181
	v_and_b32_e32 v219, 0xffff0000, v181
	v_rcp_f32_e32 v216, v216
	v_rcp_f32_e32 v217, v217
	s_nop 0
	v_mul_f32_e32 v216, v218, v216
	v_mul_f32_e32 v217, v219, v217
	v_mul_f32_e32 v78, v78, v216
	v_mul_f32_e32 v79, v79, v217
	v_lshlrev_b32_e32 v216, 16, v186
	v_and_b32_e32 v217, 0xffff0000, v186
	v_lshlrev_b32_e32 v218, 16, v182
	v_and_b32_e32 v219, 0xffff0000, v182
	v_rcp_f32_e32 v216, v216
	v_rcp_f32_e32 v217, v217
	s_nop 0
	v_mul_f32_e32 v216, v218, v216
	v_mul_f32_e32 v217, v219, v217
	v_mul_f32_e32 v72, v72, v216
	v_mul_f32_e32 v73, v73, v217
	v_lshlrev_b32_e32 v216, 16, v187
	v_and_b32_e32 v217, 0xffff0000, v187
	v_lshlrev_b32_e32 v218, 16, v183
	v_and_b32_e32 v219, 0xffff0000, v183
	v_rcp_f32_e32 v216, v216
	v_rcp_f32_e32 v217, v217
	s_nop 0
	v_mul_f32_e32 v216, v218, v216
	v_mul_f32_e32 v217, v219, v217
	v_mul_f32_e32 v74, v74, v216
	v_mul_f32_e32 v75, v75, v217
	global_load_dwordx4 v[180:183], v[210:211], off offset:256
	global_load_dwordx4 v[184:187], v[210:211], off offset:2304
	v_lshl_add_u64 v[210:211], v[210:211], 0, s[22:23]
	s_waitcnt vmcnt(14)
	v_permlane16_swap_b32_e32 v188, v190
	v_permlane16_swap_b32_e32 v189, v191
	v_permlane16_swap_b32_e32 v192, v194
	v_permlane16_swap_b32_e32 v193, v195
	v_lshlrev_b32_e32 v216, 16, v192
	v_and_b32_e32 v217, 0xffff0000, v192
	v_lshlrev_b32_e32 v218, 16, v188
	v_and_b32_e32 v219, 0xffff0000, v188
	v_rcp_f32_e32 v216, v216
	v_rcp_f32_e32 v217, v217
	s_nop 0
	v_mul_f32_e32 v216, v218, v216
	v_mul_f32_e32 v217, v219, v217
	v_mul_f32_e32 v100, v100, v216
	v_mul_f32_e32 v101, v101, v217
	v_lshlrev_b32_e32 v216, 16, v193
	v_and_b32_e32 v217, 0xffff0000, v193
	v_lshlrev_b32_e32 v218, 16, v189
	v_and_b32_e32 v219, 0xffff0000, v189
	v_rcp_f32_e32 v216, v216
	v_rcp_f32_e32 v217, v217
	s_nop 0
	v_mul_f32_e32 v216, v218, v216
	v_mul_f32_e32 v217, v219, v217
	v_mul_f32_e32 v102, v102, v216
	v_mul_f32_e32 v103, v103, v217
	v_lshlrev_b32_e32 v216, 16, v194
	v_and_b32_e32 v217, 0xffff0000, v194
	v_lshlrev_b32_e32 v218, 16, v190
	v_and_b32_e32 v219, 0xffff0000, v190
	v_rcp_f32_e32 v216, v216
	v_rcp_f32_e32 v217, v217
	s_nop 0
	v_mul_f32_e32 v216, v218, v216
	v_mul_f32_e32 v217, v219, v217
	v_mul_f32_e32 v96, v96, v216
	v_mul_f32_e32 v97, v97, v217
	v_lshlrev_b32_e32 v216, 16, v195
	v_and_b32_e32 v217, 0xffff0000, v195
	v_lshlrev_b32_e32 v218, 16, v191
	v_and_b32_e32 v219, 0xffff0000, v191
	v_rcp_f32_e32 v216, v216
	v_rcp_f32_e32 v217, v217
	s_nop 0
	v_mul_f32_e32 v216, v218, v216
	v_mul_f32_e32 v217, v219, v217
	v_mul_f32_e32 v98, v98, v216
	v_mul_f32_e32 v99, v99, v217
	global_load_dwordx4 v[188:191], v[210:211], off
	global_load_dwordx4 v[192:195], v[210:211], off offset:2048
	s_waitcnt vmcnt(14)
	v_permlane16_swap_b32_e32 v196, v198
	v_permlane16_swap_b32_e32 v197, v199
	v_permlane16_swap_b32_e32 v204, v206
	v_permlane16_swap_b32_e32 v205, v207
	v_lshlrev_b32_e32 v216, 16, v204
	v_and_b32_e32 v217, 0xffff0000, v204
	v_lshlrev_b32_e32 v218, 16, v196
	v_and_b32_e32 v219, 0xffff0000, v196
	v_rcp_f32_e32 v216, v216
	v_rcp_f32_e32 v217, v217
	s_nop 0
	v_mul_f32_e32 v216, v218, v216
	v_mul_f32_e32 v217, v219, v217
	v_mul_f32_e32 v68, v68, v216
	v_mul_f32_e32 v69, v69, v217
	v_lshlrev_b32_e32 v216, 16, v205
	v_and_b32_e32 v217, 0xffff0000, v205
	v_lshlrev_b32_e32 v218, 16, v197
	v_and_b32_e32 v219, 0xffff0000, v197
	v_rcp_f32_e32 v216, v216
	v_rcp_f32_e32 v217, v217
	s_nop 0
	v_mul_f32_e32 v216, v218, v216
	v_mul_f32_e32 v217, v219, v217
	v_mul_f32_e32 v70, v70, v216
	v_mul_f32_e32 v71, v71, v217
	v_lshlrev_b32_e32 v216, 16, v206
	v_and_b32_e32 v217, 0xffff0000, v206
	v_lshlrev_b32_e32 v218, 16, v198
	v_and_b32_e32 v219, 0xffff0000, v198
	v_rcp_f32_e32 v216, v216
	v_rcp_f32_e32 v217, v217
	s_nop 0
	v_mul_f32_e32 v216, v218, v216
	v_mul_f32_e32 v217, v219, v217
	v_mul_f32_e32 v64, v64, v216
	v_mul_f32_e32 v65, v65, v217
	v_lshlrev_b32_e32 v216, 16, v207
	v_and_b32_e32 v217, 0xffff0000, v207
	v_lshlrev_b32_e32 v218, 16, v199
	v_and_b32_e32 v219, 0xffff0000, v199
	v_rcp_f32_e32 v216, v216
	v_rcp_f32_e32 v217, v217
	s_nop 0
	v_mul_f32_e32 v216, v218, v216
	v_mul_f32_e32 v217, v219, v217
	v_mul_f32_e32 v66, v66, v216
	v_mul_f32_e32 v67, v67, v217
	global_load_dwordx4 v[196:199], v[210:211], off offset:256
	global_load_dwordx4 v[204:207], v[210:211], off offset:2304
	s_waitcnt vmcnt(14)
	v_permlane16_swap_b32_e32 v140, v142
	v_permlane16_swap_b32_e32 v141, v143
	v_permlane16_swap_b32_e32 v144, v146
	v_permlane16_swap_b32_e32 v145, v147
	v_lshlrev_b32_e32 v216, 16, v144
	v_and_b32_e32 v217, 0xffff0000, v144
	v_lshlrev_b32_e32 v218, 16, v140
	v_and_b32_e32 v219, 0xffff0000, v140
	v_rcp_f32_e32 v216, v216
	v_rcp_f32_e32 v217, v217
	s_nop 0
	v_mul_f32_e32 v216, v218, v216
	v_mul_f32_e32 v217, v219, v217
	v_mul_f32_e32 v60, v60, v216
	v_mul_f32_e32 v61, v61, v217
	v_lshlrev_b32_e32 v216, 16, v145
	v_and_b32_e32 v217, 0xffff0000, v145
	v_lshlrev_b32_e32 v218, 16, v141
	v_and_b32_e32 v219, 0xffff0000, v141
	v_rcp_f32_e32 v216, v216
	v_rcp_f32_e32 v217, v217
	s_nop 0
	v_mul_f32_e32 v216, v218, v216
	v_mul_f32_e32 v217, v219, v217
	v_mul_f32_e32 v62, v62, v216
	v_mul_f32_e32 v63, v63, v217
	v_lshlrev_b32_e32 v216, 16, v146
	v_and_b32_e32 v217, 0xffff0000, v146
	v_lshlrev_b32_e32 v218, 16, v142
	v_and_b32_e32 v219, 0xffff0000, v142
	v_rcp_f32_e32 v216, v216
	v_rcp_f32_e32 v217, v217
	s_nop 0
	v_mul_f32_e32 v216, v218, v216
	v_mul_f32_e32 v217, v219, v217
	v_mul_f32_e32 v56, v56, v216
	v_mul_f32_e32 v57, v57, v217
	v_lshlrev_b32_e32 v216, 16, v147
	v_and_b32_e32 v217, 0xffff0000, v147
	v_lshlrev_b32_e32 v218, 16, v143
	v_and_b32_e32 v219, 0xffff0000, v143
	v_rcp_f32_e32 v216, v216
	v_rcp_f32_e32 v217, v217
	s_nop 0
	v_mul_f32_e32 v216, v218, v216
	v_mul_f32_e32 v217, v219, v217
	v_mul_f32_e32 v58, v58, v216
	v_mul_f32_e32 v59, v59, v217
	s_waitcnt vmcnt(12)
	v_permlane16_swap_b32_e32 v148, v150
	v_permlane16_swap_b32_e32 v149, v151
	v_permlane16_swap_b32_e32 v152, v154
	v_permlane16_swap_b32_e32 v153, v155
	v_lshlrev_b32_e32 v216, 16, v152
	v_and_b32_e32 v217, 0xffff0000, v152
	v_lshlrev_b32_e32 v218, 16, v148
	v_and_b32_e32 v219, 0xffff0000, v148
	v_rcp_f32_e32 v216, v216
	v_rcp_f32_e32 v217, v217
	s_nop 0
	v_mul_f32_e32 v216, v218, v216
	v_mul_f32_e32 v217, v219, v217
	v_mul_f32_e32 v28, v28, v216
	v_mul_f32_e32 v29, v29, v217
	v_lshlrev_b32_e32 v216, 16, v153
	v_and_b32_e32 v217, 0xffff0000, v153
	v_lshlrev_b32_e32 v218, 16, v149
	v_and_b32_e32 v219, 0xffff0000, v149
	v_rcp_f32_e32 v216, v216
	v_rcp_f32_e32 v217, v217
	s_nop 0
	v_mul_f32_e32 v216, v218, v216
	v_mul_f32_e32 v217, v219, v217
	v_mul_f32_e32 v30, v30, v216
	v_mul_f32_e32 v31, v31, v217
	v_lshlrev_b32_e32 v216, 16, v154
	v_and_b32_e32 v217, 0xffff0000, v154
	v_lshlrev_b32_e32 v218, 16, v150
	v_and_b32_e32 v219, 0xffff0000, v150
	v_rcp_f32_e32 v216, v216
	v_rcp_f32_e32 v217, v217
	s_nop 0
	v_mul_f32_e32 v216, v218, v216
	v_mul_f32_e32 v217, v219, v217
	v_mul_f32_e32 v24, v24, v216
	v_mul_f32_e32 v25, v25, v217
	v_lshlrev_b32_e32 v216, 16, v155
	v_and_b32_e32 v217, 0xffff0000, v155
	v_lshlrev_b32_e32 v218, 16, v151
	v_and_b32_e32 v219, 0xffff0000, v151
	v_rcp_f32_e32 v216, v216
	v_rcp_f32_e32 v217, v217
	s_nop 0
	v_mul_f32_e32 v216, v218, v216
	v_mul_f32_e32 v217, v219, v217
	v_mul_f32_e32 v26, v26, v216
	v_mul_f32_e32 v27, v27, v217
	s_waitcnt vmcnt(10)
	v_permlane16_swap_b32_e32 v156, v158
	v_permlane16_swap_b32_e32 v157, v159
	v_permlane16_swap_b32_e32 v160, v162
	v_permlane16_swap_b32_e32 v161, v163
	v_lshlrev_b32_e32 v216, 16, v160
	v_and_b32_e32 v217, 0xffff0000, v160
	v_lshlrev_b32_e32 v218, 16, v156
	v_and_b32_e32 v219, 0xffff0000, v156
	v_rcp_f32_e32 v216, v216
	v_rcp_f32_e32 v217, v217
	s_nop 0
	v_mul_f32_e32 v216, v218, v216
	v_mul_f32_e32 v217, v219, v217
	v_mul_f32_e32 v52, v52, v216
	v_mul_f32_e32 v53, v53, v217
	v_lshlrev_b32_e32 v216, 16, v161
	v_and_b32_e32 v217, 0xffff0000, v161
	v_lshlrev_b32_e32 v218, 16, v157
	v_and_b32_e32 v219, 0xffff0000, v157
	v_rcp_f32_e32 v216, v216
	v_rcp_f32_e32 v217, v217
	s_nop 0
	v_mul_f32_e32 v216, v218, v216
	v_mul_f32_e32 v217, v219, v217
	v_mul_f32_e32 v54, v54, v216
	v_mul_f32_e32 v55, v55, v217
	v_lshlrev_b32_e32 v216, 16, v162
	v_and_b32_e32 v217, 0xffff0000, v162
	v_lshlrev_b32_e32 v218, 16, v158
	v_and_b32_e32 v219, 0xffff0000, v158
	v_rcp_f32_e32 v216, v216
	v_rcp_f32_e32 v217, v217
	s_nop 0
	v_mul_f32_e32 v216, v218, v216
	v_mul_f32_e32 v217, v219, v217
	v_mul_f32_e32 v48, v48, v216
	v_mul_f32_e32 v49, v49, v217
	v_lshlrev_b32_e32 v216, 16, v163
	v_and_b32_e32 v217, 0xffff0000, v163
	v_lshlrev_b32_e32 v218, 16, v159
	v_and_b32_e32 v219, 0xffff0000, v159
	v_rcp_f32_e32 v216, v216
	v_rcp_f32_e32 v217, v217
	s_nop 0
	v_mul_f32_e32 v216, v218, v216
	v_mul_f32_e32 v217, v219, v217
	v_mul_f32_e32 v50, v50, v216
	v_mul_f32_e32 v51, v51, v217
	s_waitcnt vmcnt(8)
	v_permlane16_swap_b32_e32 v164, v166
	v_permlane16_swap_b32_e32 v165, v167
	v_permlane16_swap_b32_e32 v168, v170
	v_permlane16_swap_b32_e32 v169, v171
	v_lshlrev_b32_e32 v216, 16, v168
	v_and_b32_e32 v217, 0xffff0000, v168
	v_lshlrev_b32_e32 v218, 16, v164
	v_and_b32_e32 v219, 0xffff0000, v164
	v_rcp_f32_e32 v216, v216
	v_rcp_f32_e32 v217, v217
	s_nop 0
	v_mul_f32_e32 v216, v218, v216
	v_mul_f32_e32 v217, v219, v217
	v_mul_f32_e32 v20, v20, v216
	v_mul_f32_e32 v21, v21, v217
	v_lshlrev_b32_e32 v216, 16, v169
	v_and_b32_e32 v217, 0xffff0000, v169
	v_lshlrev_b32_e32 v218, 16, v165
	v_and_b32_e32 v219, 0xffff0000, v165
	v_rcp_f32_e32 v216, v216
	v_rcp_f32_e32 v217, v217
	s_nop 0
	v_mul_f32_e32 v216, v218, v216
	v_mul_f32_e32 v217, v219, v217
	v_mul_f32_e32 v22, v22, v216
	v_mul_f32_e32 v23, v23, v217
	v_lshlrev_b32_e32 v216, 16, v170
	v_and_b32_e32 v217, 0xffff0000, v170
	v_lshlrev_b32_e32 v218, 16, v166
	v_and_b32_e32 v219, 0xffff0000, v166
	v_rcp_f32_e32 v216, v216
	v_rcp_f32_e32 v217, v217
	s_nop 0
	v_mul_f32_e32 v216, v218, v216
	v_mul_f32_e32 v217, v219, v217
	v_mul_f32_e32 v16, v16, v216
	v_mul_f32_e32 v17, v17, v217
	v_lshlrev_b32_e32 v216, 16, v171
	v_and_b32_e32 v217, 0xffff0000, v171
	v_lshlrev_b32_e32 v218, 16, v167
	v_and_b32_e32 v219, 0xffff0000, v167
	v_rcp_f32_e32 v216, v216
	v_rcp_f32_e32 v217, v217
	s_nop 0
	v_mul_f32_e32 v216, v218, v216
	v_mul_f32_e32 v217, v219, v217
	v_mul_f32_e32 v18, v18, v216
	v_mul_f32_e32 v19, v19, v217
	s_waitcnt vmcnt(6)
	v_permlane16_swap_b32_e32 v172, v174
	v_permlane16_swap_b32_e32 v173, v175
	v_permlane16_swap_b32_e32 v176, v178
	v_permlane16_swap_b32_e32 v177, v179
	v_lshlrev_b32_e32 v216, 16, v176
	v_and_b32_e32 v217, 0xffff0000, v176
	v_lshlrev_b32_e32 v218, 16, v172
	v_and_b32_e32 v219, 0xffff0000, v172
	v_rcp_f32_e32 v216, v216
	v_rcp_f32_e32 v217, v217
	s_nop 0
	v_mul_f32_e32 v216, v218, v216
	v_mul_f32_e32 v217, v219, v217
	v_mul_f32_e32 v44, v44, v216
	v_mul_f32_e32 v45, v45, v217
	v_lshlrev_b32_e32 v216, 16, v177
	v_and_b32_e32 v217, 0xffff0000, v177
	v_lshlrev_b32_e32 v218, 16, v173
	v_and_b32_e32 v219, 0xffff0000, v173
	v_rcp_f32_e32 v216, v216
	v_rcp_f32_e32 v217, v217
	s_nop 0
	v_mul_f32_e32 v216, v218, v216
	v_mul_f32_e32 v217, v219, v217
	v_mul_f32_e32 v46, v46, v216
	v_mul_f32_e32 v47, v47, v217
	v_lshlrev_b32_e32 v216, 16, v178
	v_and_b32_e32 v217, 0xffff0000, v178
	v_lshlrev_b32_e32 v218, 16, v174
	v_and_b32_e32 v219, 0xffff0000, v174
	v_rcp_f32_e32 v216, v216
	v_rcp_f32_e32 v217, v217
	s_nop 0
	v_mul_f32_e32 v216, v218, v216
	v_mul_f32_e32 v217, v219, v217
	v_mul_f32_e32 v40, v40, v216
	v_mul_f32_e32 v41, v41, v217
	v_lshlrev_b32_e32 v216, 16, v179
	v_and_b32_e32 v217, 0xffff0000, v179
	v_lshlrev_b32_e32 v218, 16, v175
	v_and_b32_e32 v219, 0xffff0000, v175
	v_rcp_f32_e32 v216, v216
	v_rcp_f32_e32 v217, v217
	s_nop 0
	v_mul_f32_e32 v216, v218, v216
	v_mul_f32_e32 v217, v219, v217
	v_mul_f32_e32 v42, v42, v216
	v_mul_f32_e32 v43, v43, v217
	s_waitcnt vmcnt(4)
	v_permlane16_swap_b32_e32 v180, v182
	v_permlane16_swap_b32_e32 v181, v183
	v_permlane16_swap_b32_e32 v184, v186
	v_permlane16_swap_b32_e32 v185, v187
	v_lshlrev_b32_e32 v216, 16, v184
	v_and_b32_e32 v217, 0xffff0000, v184
	v_lshlrev_b32_e32 v218, 16, v180
	v_and_b32_e32 v219, 0xffff0000, v180
	v_rcp_f32_e32 v216, v216
	v_rcp_f32_e32 v217, v217
	s_nop 0
	v_mul_f32_e32 v216, v218, v216
	v_mul_f32_e32 v217, v219, v217
	v_mul_f32_e32 v12, v12, v216
	v_mul_f32_e32 v13, v13, v217
	v_lshlrev_b32_e32 v216, 16, v185
	v_and_b32_e32 v217, 0xffff0000, v185
	v_lshlrev_b32_e32 v218, 16, v181
	v_and_b32_e32 v219, 0xffff0000, v181
	v_rcp_f32_e32 v216, v216
	v_rcp_f32_e32 v217, v217
	s_nop 0
	v_mul_f32_e32 v216, v218, v216
	v_mul_f32_e32 v217, v219, v217
	v_mul_f32_e32 v14, v14, v216
	v_mul_f32_e32 v15, v15, v217
	v_lshlrev_b32_e32 v216, 16, v186
	v_and_b32_e32 v217, 0xffff0000, v186
	v_lshlrev_b32_e32 v218, 16, v182
	v_and_b32_e32 v219, 0xffff0000, v182
	v_rcp_f32_e32 v216, v216
	v_rcp_f32_e32 v217, v217
	s_nop 0
	v_mul_f32_e32 v216, v218, v216
	v_mul_f32_e32 v217, v219, v217
	v_mul_f32_e32 v8, v8, v216
	v_mul_f32_e32 v9, v9, v217
	v_lshlrev_b32_e32 v216, 16, v187
	v_and_b32_e32 v217, 0xffff0000, v187
	v_lshlrev_b32_e32 v218, 16, v183
	v_and_b32_e32 v219, 0xffff0000, v183
	v_rcp_f32_e32 v216, v216
	v_rcp_f32_e32 v217, v217
	s_nop 0
	v_mul_f32_e32 v216, v218, v216
	v_mul_f32_e32 v217, v219, v217
	v_mul_f32_e32 v10, v10, v216
	v_mul_f32_e32 v11, v11, v217
	s_waitcnt vmcnt(2)
	v_permlane16_swap_b32_e32 v188, v190
	v_permlane16_swap_b32_e32 v189, v191
	v_permlane16_swap_b32_e32 v192, v194
	v_permlane16_swap_b32_e32 v193, v195
	v_lshlrev_b32_e32 v216, 16, v192
	v_and_b32_e32 v217, 0xffff0000, v192
	v_lshlrev_b32_e32 v218, 16, v188
	v_and_b32_e32 v219, 0xffff0000, v188
	v_rcp_f32_e32 v216, v216
	v_rcp_f32_e32 v217, v217
	s_nop 0
	v_mul_f32_e32 v216, v218, v216
	v_mul_f32_e32 v217, v219, v217
	v_mul_f32_e32 v36, v36, v216
	v_mul_f32_e32 v37, v37, v217
	v_lshlrev_b32_e32 v216, 16, v193
	v_and_b32_e32 v217, 0xffff0000, v193
	v_lshlrev_b32_e32 v218, 16, v189
	v_and_b32_e32 v219, 0xffff0000, v189
	v_rcp_f32_e32 v216, v216
	v_rcp_f32_e32 v217, v217
	s_nop 0
	v_mul_f32_e32 v216, v218, v216
	v_mul_f32_e32 v217, v219, v217
	v_mul_f32_e32 v38, v38, v216
	v_mul_f32_e32 v39, v39, v217
	v_lshlrev_b32_e32 v216, 16, v194
	v_and_b32_e32 v217, 0xffff0000, v194
	v_lshlrev_b32_e32 v218, 16, v190
	v_and_b32_e32 v219, 0xffff0000, v190
	v_rcp_f32_e32 v216, v216
	v_rcp_f32_e32 v217, v217
	s_nop 0
	v_mul_f32_e32 v216, v218, v216
	v_mul_f32_e32 v217, v219, v217
	v_mul_f32_e32 v32, v32, v216
	v_mul_f32_e32 v33, v33, v217
	v_lshlrev_b32_e32 v216, 16, v195
	v_and_b32_e32 v217, 0xffff0000, v195
	v_lshlrev_b32_e32 v218, 16, v191
	v_and_b32_e32 v219, 0xffff0000, v191
	v_rcp_f32_e32 v216, v216
	v_rcp_f32_e32 v217, v217
	s_nop 0
	v_mul_f32_e32 v216, v218, v216
	v_mul_f32_e32 v217, v219, v217
	v_mul_f32_e32 v34, v34, v216
	v_mul_f32_e32 v35, v35, v217
	s_waitcnt vmcnt(0)
	v_permlane16_swap_b32_e32 v196, v198
	v_permlane16_swap_b32_e32 v197, v199
	v_permlane16_swap_b32_e32 v204, v206
	v_permlane16_swap_b32_e32 v205, v207
	v_lshlrev_b32_e32 v216, 16, v204
	v_and_b32_e32 v217, 0xffff0000, v204
	v_lshlrev_b32_e32 v218, 16, v196
	v_and_b32_e32 v219, 0xffff0000, v196
	v_rcp_f32_e32 v216, v216
	v_rcp_f32_e32 v217, v217
	s_nop 0
	v_mul_f32_e32 v216, v218, v216
	v_mul_f32_e32 v217, v219, v217
	v_mul_f32_e32 v4, v4, v216
	v_mul_f32_e32 v5, v5, v217
	v_lshlrev_b32_e32 v216, 16, v205
	v_and_b32_e32 v217, 0xffff0000, v205
	v_lshlrev_b32_e32 v218, 16, v197
	v_and_b32_e32 v219, 0xffff0000, v197
	v_rcp_f32_e32 v216, v216
	v_rcp_f32_e32 v217, v217
	s_nop 0
	v_mul_f32_e32 v216, v218, v216
	v_mul_f32_e32 v217, v219, v217
	v_mul_f32_e32 v6, v6, v216
	v_mul_f32_e32 v7, v7, v217
	v_lshlrev_b32_e32 v216, 16, v206
	v_and_b32_e32 v217, 0xffff0000, v206
	v_lshlrev_b32_e32 v218, 16, v198
	v_and_b32_e32 v219, 0xffff0000, v198
	v_rcp_f32_e32 v216, v216
	v_rcp_f32_e32 v217, v217
	s_nop 0
	v_mul_f32_e32 v216, v218, v216
	v_mul_f32_e32 v217, v219, v217
	v_mul_f32_e32 v0, v0, v216
	v_mul_f32_e32 v1, v1, v217
	v_lshlrev_b32_e32 v216, 16, v207
	v_and_b32_e32 v217, 0xffff0000, v207
	v_lshlrev_b32_e32 v218, 16, v199
	v_and_b32_e32 v219, 0xffff0000, v199
	v_rcp_f32_e32 v216, v216
	v_rcp_f32_e32 v217, v217
	s_nop 0
	v_mul_f32_e32 v216, v218, v216
	v_mul_f32_e32 v217, v219, v217
	v_mul_f32_e32 v2, v2, v216
	v_mul_f32_e32 v3, v3, v217

.LBB0_890:
	s_lshl_b32 s2, s8, 7
	s_or_b32 s2, s2, s53
	v_lshl_add_u32 v226, v207, 2, s2
	v_lshlrev_b32_e32 v226, 2, v226
	v_add_u32_e32 v210, 0x5800, v226
	v_add_u32_e32 v211, 0xb000, v226
	v_add_u32_e32 v212, 0x2c00, v226
	v_add_u32_e32 v213, 0x8400, v226
	v_add_u32_e32 v214, 0xdc00, v226
	global_load_dwordx4 v[160:163], v226, s[70:71]
	global_load_dwordx4 v[164:167], v210, s[70:71]
	global_load_dwordx4 v[168:171], v211, s[70:71]
	global_load_dwordx4 v[182:185], v212, s[70:71]
	global_load_dwordx4 v[186:189], v213, s[70:71]
	global_load_dwordx4 v[190:193], v214, s[70:71]
	global_load_dwordx4 v[172:175], v226, s[58:59]
	global_load_dwordx4 v[194:197], v212, s[58:59]
	s_lshl_b32 s0, s9, 10
	v_readlane_b32 s3, v254, 24
	v_readlane_b32 s1, v254, 36
	v_readlane_b32 s6, v254, 22
	v_readlane_b32 s7, v254, 23
	s_add_i32 s0, s3, s0
	v_lshl_add_u32 v227, v206, 2, s0
	ds_read2_b32 v[104:105], v227 offset1:16
	ds_read2_b32 v[106:107], v227 offset0:32 offset1:48
	ds_read2_b32 v[108:109], v227 offset0:128 offset1:144
	ds_read2_b32 v[110:111], v227 offset0:160 offset1:176
	s_lshl_b32 s3, s9, 13
	s_and_b32 s3, s3, 0x2000
	s_add_i32 s1, s1, s3
	s_add_i32 s1, s1, s96
	v_lshl_add_u32 v135, v207, 4, s1
	v_add_u32_e32 v228, 0xffffff00, v135
	v_cmp_eq_u32_e64 s[4:5], 0, v206
	v_cmp_eq_u32_e64 s[16:17], 15, v206
	s_waitcnt lgkmcnt(0)
	v_mul_f32_e32 v100, v100, v104
	v_mul_f32_e32 v101, v101, v104
	v_mul_f32_e32 v102, v102, v104
	v_mul_f32_e32 v103, v103, v104
	v_mul_f32_e32 v60, v60, v104
	v_mul_f32_e32 v61, v61, v104
	v_mul_f32_e32 v62, v62, v104
	v_mul_f32_e32 v63, v63, v104
	v_mul_f32_e32 v96, v96, v104
	v_mul_f32_e32 v97, v97, v104
	v_mul_f32_e32 v98, v98, v104
	v_mul_f32_e32 v99, v99, v104
	v_mul_f32_e32 v56, v56, v104
	v_mul_f32_e32 v57, v57, v104
	v_mul_f32_e32 v58, v58, v104
	v_mul_f32_e32 v59, v59, v104
	v_mul_f32_e32 v156, v156, v105
	v_mul_f32_e32 v157, v157, v105
	v_mul_f32_e32 v158, v158, v105
	v_mul_f32_e32 v159, v159, v105
	v_mul_f32_e32 v52, v52, v105
	v_mul_f32_e32 v53, v53, v105
	v_mul_f32_e32 v54, v54, v105
	v_mul_f32_e32 v55, v55, v105
	v_mul_f32_e32 v152, v152, v105
	v_mul_f32_e32 v153, v153, v105
	v_mul_f32_e32 v154, v154, v105
	v_mul_f32_e32 v155, v155, v105
	v_mul_f32_e32 v48, v48, v105
	v_mul_f32_e32 v49, v49, v105
	v_mul_f32_e32 v50, v50, v105
	v_mul_f32_e32 v51, v51, v105
	v_mul_f32_e32 v140, v140, v106
	v_mul_f32_e32 v141, v141, v106
	v_mul_f32_e32 v142, v142, v106
	v_mul_f32_e32 v143, v143, v106
	v_mul_f32_e32 v44, v44, v106
	v_mul_f32_e32 v45, v45, v106
	v_mul_f32_e32 v46, v46, v106
	v_mul_f32_e32 v47, v47, v106
	v_mul_f32_e32 v136, v136, v106
	v_mul_f32_e32 v137, v137, v106
	v_mul_f32_e32 v138, v138, v106
	v_mul_f32_e32 v139, v139, v106
	v_mul_f32_e32 v40, v40, v106
	v_mul_f32_e32 v41, v41, v106
	v_mul_f32_e32 v42, v42, v106
	v_mul_f32_e32 v43, v43, v106
	v_mul_f32_e32 v88, v88, v107
	v_mul_f32_e32 v89, v89, v107
	v_mul_f32_e32 v90, v90, v107
	v_mul_f32_e32 v91, v91, v107
	v_mul_f32_e32 v84, v84, v107
	v_mul_f32_e32 v85, v85, v107
	v_mul_f32_e32 v86, v86, v107
	v_mul_f32_e32 v87, v87, v107
	v_mul_f32_e32 v80, v80, v107
	v_mul_f32_e32 v81, v81, v107
	v_mul_f32_e32 v82, v82, v107
	v_mul_f32_e32 v83, v83, v107
	v_mul_f32_e32 v32, v32, v107
	v_mul_f32_e32 v33, v33, v107
	v_mul_f32_e32 v34, v34, v107
	v_mul_f32_e32 v35, v35, v107
	v_mul_f32_e32 v92, v92, v108
	v_mul_f32_e32 v93, v93, v108
	v_mul_f32_e32 v94, v94, v108
	v_mul_f32_e32 v95, v95, v108
	v_mul_f32_e32 v28, v28, v108
	v_mul_f32_e32 v29, v29, v108
	v_mul_f32_e32 v30, v30, v108
	v_mul_f32_e32 v31, v31, v108
	v_mul_f32_e32 v36, v36, v108
	v_mul_f32_e32 v37, v37, v108
	v_mul_f32_e32 v38, v38, v108
	v_mul_f32_e32 v39, v39, v108
	v_mul_f32_e32 v24, v24, v108
	v_mul_f32_e32 v25, v25, v108
	v_mul_f32_e32 v26, v26, v108
	v_mul_f32_e32 v27, v27, v108
	v_mul_f32_e32 v116, v116, v109
	v_mul_f32_e32 v117, v117, v109
	v_mul_f32_e32 v118, v118, v109
	v_mul_f32_e32 v119, v119, v109
	v_mul_f32_e32 v20, v20, v109
	v_mul_f32_e32 v21, v21, v109
	v_mul_f32_e32 v22, v22, v109
	v_mul_f32_e32 v23, v23, v109
	v_mul_f32_e32 v112, v112, v109
	v_mul_f32_e32 v113, v113, v109
	v_mul_f32_e32 v114, v114, v109
	v_mul_f32_e32 v115, v115, v109
	v_mul_f32_e32 v16, v16, v109
	v_mul_f32_e32 v17, v17, v109
	v_mul_f32_e32 v18, v18, v109
	v_mul_f32_e32 v19, v19, v109
	v_mul_f32_e32 v76, v76, v110
	v_mul_f32_e32 v77, v77, v110
	v_mul_f32_e32 v78, v78, v110
	v_mul_f32_e32 v79, v79, v110
	v_mul_f32_e32 v12, v12, v110
	v_mul_f32_e32 v13, v13, v110
	v_mul_f32_e32 v14, v14, v110
	v_mul_f32_e32 v15, v15, v110
	v_mul_f32_e32 v72, v72, v110
	v_mul_f32_e32 v73, v73, v110
	v_mul_f32_e32 v74, v74, v110
	v_mul_f32_e32 v75, v75, v110
	v_mul_f32_e32 v8, v8, v110
	v_mul_f32_e32 v9, v9, v110
	v_mul_f32_e32 v10, v10, v110
	v_mul_f32_e32 v11, v11, v110
	v_mul_f32_e32 v68, v68, v111
	v_mul_f32_e32 v69, v69, v111
	v_mul_f32_e32 v70, v70, v111
	v_mul_f32_e32 v71, v71, v111
	v_mul_f32_e32 v4, v4, v111
	v_mul_f32_e32 v5, v5, v111
	v_mul_f32_e32 v6, v6, v111
	v_mul_f32_e32 v7, v7, v111
	v_mul_f32_e32 v64, v64, v111
	v_mul_f32_e32 v65, v65, v111
	v_mul_f32_e32 v66, v66, v111
	v_mul_f32_e32 v67, v67, v111
	v_mul_f32_e32 v0, v0, v111
	v_mul_f32_e32 v1, v1, v111
	v_mul_f32_e32 v2, v2, v111
	v_mul_f32_e32 v3, v3, v111
	s_and_saveexec_b64 s[18:19], s[4:5]
	ds_write_b128 v135, v[100:103]
	ds_write_b128 v135, v[60:63] offset:64
	ds_write_b128 v135, v[96:99] offset:128
	ds_write_b128 v135, v[56:59] offset:192
	ds_write_b128 v135, v[92:95] offset:1024
	ds_write_b128 v135, v[28:31] offset:1088
	ds_write_b128 v135, v[36:39] offset:1152
	ds_write_b128 v135, v[24:27] offset:1216
	s_mov_b64 exec, s[18:19]
	s_and_saveexec_b64 s[18:19], s[16:17]
	ds_write_b128 v135, v[88:91] offset:256
	ds_write_b128 v135, v[84:87] offset:320
	ds_write_b128 v135, v[80:83] offset:384
	ds_write_b128 v135, v[32:35] offset:448
	ds_write_b128 v135, v[68:71] offset:1280
	ds_write_b128 v135, v[4:7] offset:1344
	ds_write_b128 v135, v[64:67] offset:1408
	ds_write_b128 v135, v[0:3] offset:1472
	s_mov_b64 exec, s[18:19]
	v_readlane_b32 s18, v254, 30
	v_readlane_b32 s19, v254, 31
	s_lshl_b32 s3, s86, 2
	s_lshl_b32 s56, s8, 8
	s_or_b32 s56, s56, s53
	v_lshl_add_u32 v226, v207, 2, s56
	s_and_b64 vcc, exec, s[66:67]
	s_cbranch_vccz .Lp6e_ue1
	v_add_u32_e32 v227, s3, v206
	v_mul_u32_u24_e32 v227, 0x1600, v227
	v_add_lshl_u32 v227, v227, v226, 1
	v_cmp_gt_u32_e64 s[44:45], 2, v206
	v_cvt_pk_bf16_f32 v210, v100, v101
	v_cvt_pk_bf16_f32 v211, v102, v103
	v_cvt_pk_bf16_f32 v212, v60, v61
	v_cvt_pk_bf16_f32 v213, v62, v63
	v_cvt_pk_bf16_f32 v214, v96, v97
	v_cvt_pk_bf16_f32 v215, v98, v99
	v_cvt_pk_bf16_f32 v216, v56, v57
	v_cvt_pk_bf16_f32 v217, v58, v59
	s_and_saveexec_b64 s[20:21], s[44:45]
	global_store_dwordx2 v227, v[210:211], s[18:19]
	global_store_dwordx2 v227, v[212:213], s[18:19] offset:32
	global_store_dwordx2 v227, v[214:215], s[18:19] offset:256
	global_store_dwordx2 v227, v[216:217], s[18:19] offset:288
	s_mov_b64 exec, s[20:21]
	s_branch .Lp6e_ue2
.Lp6e_ue1:
	v_add_u32_e32 v227, s3, v206
	v_add_u32_e32 v227, -12, v227
	v_mul_u32_u24_e32 v227, 0x1600, v227
	v_add_lshl_u32 v227, v227, v226, 1
	v_cmp_lt_u32_e64 s[44:45], 13, v206
	v_cvt_pk_bf16_f32 v210, v68, v69
	v_cvt_pk_bf16_f32 v211, v70, v71
	v_cvt_pk_bf16_f32 v212, v4, v5
	v_cvt_pk_bf16_f32 v213, v6, v7
	v_cvt_pk_bf16_f32 v214, v64, v65
	v_cvt_pk_bf16_f32 v215, v66, v67
	v_cvt_pk_bf16_f32 v216, v0, v1
	v_cvt_pk_bf16_f32 v217, v2, v3
	s_and_saveexec_b64 s[20:21], s[44:45]
	global_store_dwordx2 v227, v[210:211], s[18:19]
	global_store_dwordx2 v227, v[212:213], s[18:19] offset:32
	global_store_dwordx2 v227, v[214:215], s[18:19] offset:256
	global_store_dwordx2 v227, v[216:217], s[18:19] offset:288
	s_mov_b64 exec, s[20:21]
.Lp6e_ue2:
	s_waitcnt lgkmcnt(0)
	s_barrier
	v_mov_b32_e32 v134, 0x3f07dc22
	s_mov_b32 s10, 0x3e6d3388
	s_mov_b32 s15, 0
	v_readlane_b32 s3, v254, 32
	s_lshl_b32 s56, s86, 8
	s_nop 0
	s_add_i32 s3, s3, s56
	v_add_u32_e32 v226, s3, v206
	v_mul_u32_u24_e32 v226, 0x1600, v226
	v_and_b32_e32 v227, 1, v207
	v_lshlrev_b32_e32 v132, 3, v207
	v_mad_u32_u24 v227, v227, 24, v132
	s_lshl_b32 s3, s2, 1
	v_add3_u32 v132, v226, v227, s3
	v_mov_b32_e32 v133, 0
	v_lshl_add_u64 v[132:133], v[132:133], 0, s[60:61]
	s_and_b64 vcc, exec, s[6:7]
	s_cbranch_vccz .Lp6e_z0
	ds_read_b128 v[120:123], v228 offset:0
	ds_read_b128 v[124:127], v228 offset:128
	s_branch .Lp6e_d0
.Lp6e_z0:
	v_mov_b32_e32 v120, 0
	v_mov_b32_e32 v121, 0
	v_mov_b32_e32 v122, 0
	v_mov_b32_e32 v123, 0
	v_mov_b32_e32 v124, 0
	v_mov_b32_e32 v125, 0
	v_mov_b32_e32 v126, 0
	v_mov_b32_e32 v127, 0
.Lp6e_d0:
	s_waitcnt lgkmcnt(0)
	s_waitcnt vmcnt(0)
	v_cndmask_b32_e64 v104, v100, v120, s[16:17]
	v_cndmask_b32_e64 v105, v101, v121, s[16:17]
	v_cndmask_b32_e64 v106, v102, v122, s[16:17]
	v_cndmask_b32_e64 v107, v103, v123, s[16:17]
	v_cndmask_b32_e64 v108, v100, v156, s[4:5]
	v_cndmask_b32_e64 v109, v101, v157, s[4:5]
	v_cndmask_b32_e64 v110, v102, v158, s[4:5]
	v_cndmask_b32_e64 v111, v103, v159, s[4:5]
	v_mul_f32_dpp v144, v104, v160 row_ror:1 row_mask:0xf bank_mask:0xf
	v_mul_f32_dpp v145, v105, v161 row_ror:1 row_mask:0xf bank_mask:0xf
	v_mul_f32_dpp v146, v106, v162 row_ror:1 row_mask:0xf bank_mask:0xf
	v_mul_f32_dpp v147, v107, v163 row_ror:1 row_mask:0xf bank_mask:0xf
	v_fmac_f32_e32 v144, v100, v164
	v_fmac_f32_e32 v145, v101, v165
	v_fmac_f32_e32 v146, v102, v166
	v_fmac_f32_e32 v147, v103, v167
	v_fmac_f32_dpp v144, v108, v168 row_ror:15 row_mask:0xf bank_mask:0xf
	v_fmac_f32_dpp v145, v109, v169 row_ror:15 row_mask:0xf bank_mask:0xf
	v_fmac_f32_dpp v146, v110, v170 row_ror:15 row_mask:0xf bank_mask:0xf
	v_fmac_f32_dpp v147, v111, v171 row_ror:15 row_mask:0xf bank_mask:0xf
	v_add_f32_e32 v144, v172, v144
	v_add_f32_e32 v145, v173, v145
	v_add_f32_e32 v146, v174, v146
	v_add_f32_e32 v147, v175, v147
	v_cndmask_b32_e64 v104, v96, v124, s[16:17]
	v_cndmask_b32_e64 v105, v97, v125, s[16:17]
	v_cndmask_b32_e64 v106, v98, v126, s[16:17]
	v_cndmask_b32_e64 v107, v99, v127, s[16:17]
	v_cndmask_b32_e64 v108, v96, v152, s[4:5]
	v_cndmask_b32_e64 v109, v97, v153, s[4:5]
	v_cndmask_b32_e64 v110, v98, v154, s[4:5]
	v_cndmask_b32_e64 v111, v99, v155, s[4:5]
	v_mul_f32_dpp v148, v104, v182 row_ror:1 row_mask:0xf bank_mask:0xf
	v_mul_f32_dpp v149, v105, v183 row_ror:1 row_mask:0xf bank_mask:0xf
	v_mul_f32_dpp v150, v106, v184 row_ror:1 row_mask:0xf bank_mask:0xf
	v_mul_f32_dpp v151, v107, v185 row_ror:1 row_mask:0xf bank_mask:0xf
	v_fmac_f32_e32 v148, v96, v186
	v_fmac_f32_e32 v149, v97, v187
	v_fmac_f32_e32 v150, v98, v188
	v_fmac_f32_e32 v151, v99, v189
	v_fmac_f32_dpp v148, v108, v190 row_ror:15 row_mask:0xf bank_mask:0xf
	v_fmac_f32_dpp v149, v109, v191 row_ror:15 row_mask:0xf bank_mask:0xf
	v_fmac_f32_dpp v150, v110, v192 row_ror:15 row_mask:0xf bank_mask:0xf
	v_fmac_f32_dpp v151, v111, v193 row_ror:15 row_mask:0xf bank_mask:0xf
	v_add_f32_e32 v148, v194, v148
	v_add_f32_e32 v149, v195, v149
	v_add_f32_e32 v150, v196, v150
	v_add_f32_e32 v151, v197, v151
	v_fma_f32 v210, |v148|, s10, 1.0
	v_fma_f32 v211, |v149|, s10, 1.0
	v_fma_f32 v212, |v150|, s10, 1.0
	v_fma_f32 v213, |v151|, s10, 1.0
	v_rcp_f32_e32 v210, v210
	v_rcp_f32_e32 v211, v211
	v_rcp_f32_e32 v212, v212
	v_rcp_f32_e32 v213, v213
	v_mul_f32_e32 v218, v148, v148
	v_mul_f32_e32 v219, v149, v149
	v_mul_f32_e32 v220, v150, v150
	v_mul_f32_e32 v221, v151, v151
	v_fmaak_f32 v214, v210, v134, 0xbf3a00e3
	v_fmaak_f32 v215, v211, v134, 0xbf3a00e3
	v_fmaak_f32 v216, v212, v134, 0xbf3a00e3
	v_fmaak_f32 v217, v213, v134, 0xbf3a00e3
	v_fmaak_f32 v214, v214, v210, 0x3f35f0e3
	v_fmaak_f32 v215, v215, v211, 0x3f35f0e3
	v_fmaak_f32 v216, v216, v212, 0x3f35f0e3
	v_fmaak_f32 v217, v217, v213, 0x3f35f0e3
	v_fmaak_f32 v214, v214, v210, 0xbe11a98e
	v_fmaak_f32 v215, v215, v211, 0xbe11a98e
	v_fmaak_f32 v216, v216, v212, 0xbe11a98e
	v_fmaak_f32 v217, v217, v213, 0xbe11a98e
	v_fmaak_f32 v214, v214, v210, 0x3e027906
	v_fmaak_f32 v215, v215, v211, 0x3e027906
	v_fmaak_f32 v216, v216, v212, 0x3e027906
	v_fmaak_f32 v217, v217, v213, 0x3e027906
	v_mul_f32_e32 v214, v214, v210
	v_mul_f32_e32 v215, v215, v211
	v_mul_f32_e32 v216, v216, v212
	v_mul_f32_e32 v217, v217, v213
	v_mul_f32_e32 v218, 0xbf38aa3b, v218
	v_mul_f32_e32 v219, 0xbf38aa3b, v219
	v_mul_f32_e32 v220, 0xbf38aa3b, v220
	v_mul_f32_e32 v221, 0xbf38aa3b, v221
	v_exp_f32_e32 v218, v218
	v_exp_f32_e32 v219, v219
	v_exp_f32_e32 v220, v220
	v_exp_f32_e32 v221, v221
	v_cmp_gt_f32_e64 s[18:19], 0, v148
	v_cmp_gt_f32_e64 s[20:21], 0, v149
	v_cmp_gt_f32_e64 s[44:45], 0, v150
	v_cmp_gt_f32_e64 s[46:47], 0, v151
	v_mul_f32_e32 v218, v218, v214
	v_mul_f32_e32 v219, v219, v215
	v_mul_f32_e32 v220, v220, v216
	v_mul_f32_e32 v221, v221, v217
	v_mul_f32_e32 v222, v148, v218
	v_mul_f32_e32 v223, v149, v219
	v_mul_f32_e32 v224, v150, v220
	v_mul_f32_e32 v225, v151, v221
	v_fma_f32 v210, -v148, v218, v148
	v_fma_f32 v211, -v149, v219, v149
	v_fma_f32 v212, -v150, v220, v150
	v_fma_f32 v213, -v151, v221, v151
	v_cndmask_b32_e64 v222, v210, v222, s[18:19]
	v_cndmask_b32_e64 v223, v211, v223, s[20:21]
	v_cndmask_b32_e64 v224, v212, v224, s[44:45]
	v_cndmask_b32_e64 v225, v213, v225, s[46:47]
	v_mul_f32_e32 v144, v144, v222
	v_mul_f32_e32 v145, v145, v223
	v_mul_f32_e32 v146, v146, v224
	v_mul_f32_e32 v147, v147, v225
	v_cvt_pk_bf16_f32 v202, v144, v145
	v_cvt_pk_bf16_f32 v203, v146, v147
	ds_read_b128 v[120:123], v135 offset:512
	ds_read_b128 v[124:127], v135 offset:640
	v_cndmask_b32_e64 v104, v156, v100, s[16:17]
	v_cndmask_b32_e64 v105, v157, v101, s[16:17]
	v_cndmask_b32_e64 v106, v158, v102, s[16:17]
	v_cndmask_b32_e64 v107, v159, v103, s[16:17]
	v_cndmask_b32_e64 v108, v156, v140, s[4:5]
	v_cndmask_b32_e64 v109, v157, v141, s[4:5]
	v_cndmask_b32_e64 v110, v158, v142, s[4:5]
	v_cndmask_b32_e64 v111, v159, v143, s[4:5]
	v_mul_f32_dpp v144, v104, v160 row_ror:1 row_mask:0xf bank_mask:0xf
	v_mul_f32_dpp v145, v105, v161 row_ror:1 row_mask:0xf bank_mask:0xf
	v_mul_f32_dpp v146, v106, v162 row_ror:1 row_mask:0xf bank_mask:0xf
	v_mul_f32_dpp v147, v107, v163 row_ror:1 row_mask:0xf bank_mask:0xf
	v_fmac_f32_e32 v144, v156, v164
	v_fmac_f32_e32 v145, v157, v165
	v_fmac_f32_e32 v146, v158, v166
	v_fmac_f32_e32 v147, v159, v167
	v_fmac_f32_dpp v144, v108, v168 row_ror:15 row_mask:0xf bank_mask:0xf
	v_fmac_f32_dpp v145, v109, v169 row_ror:15 row_mask:0xf bank_mask:0xf
	v_fmac_f32_dpp v146, v110, v170 row_ror:15 row_mask:0xf bank_mask:0xf
	v_fmac_f32_dpp v147, v111, v171 row_ror:15 row_mask:0xf bank_mask:0xf
	v_add_f32_e32 v144, v172, v144
	v_add_f32_e32 v145, v173, v145
	v_add_f32_e32 v146, v174, v146
	v_add_f32_e32 v147, v175, v147
	v_cndmask_b32_e64 v104, v152, v96, s[16:17]
	v_cndmask_b32_e64 v105, v153, v97, s[16:17]
	v_cndmask_b32_e64 v106, v154, v98, s[16:17]
	v_cndmask_b32_e64 v107, v155, v99, s[16:17]
	v_cndmask_b32_e64 v108, v152, v136, s[4:5]
	v_cndmask_b32_e64 v109, v153, v137, s[4:5]
	v_cndmask_b32_e64 v110, v154, v138, s[4:5]
	v_cndmask_b32_e64 v111, v155, v139, s[4:5]
	v_mul_f32_dpp v148, v104, v182 row_ror:1 row_mask:0xf bank_mask:0xf
	v_mul_f32_dpp v149, v105, v183 row_ror:1 row_mask:0xf bank_mask:0xf
	v_mul_f32_dpp v150, v106, v184 row_ror:1 row_mask:0xf bank_mask:0xf
	v_mul_f32_dpp v151, v107, v185 row_ror:1 row_mask:0xf bank_mask:0xf
	v_fmac_f32_e32 v148, v152, v186
	v_fmac_f32_e32 v149, v153, v187
	v_fmac_f32_e32 v150, v154, v188
	v_fmac_f32_e32 v151, v155, v189
	v_fmac_f32_dpp v148, v108, v190 row_ror:15 row_mask:0xf bank_mask:0xf
	v_fmac_f32_dpp v149, v109, v191 row_ror:15 row_mask:0xf bank_mask:0xf
	v_fmac_f32_dpp v150, v110, v192 row_ror:15 row_mask:0xf bank_mask:0xf
	v_fmac_f32_dpp v151, v111, v193 row_ror:15 row_mask:0xf bank_mask:0xf
	v_add_f32_e32 v148, v194, v148
	v_add_f32_e32 v149, v195, v149
	v_add_f32_e32 v150, v196, v150
	v_add_f32_e32 v151, v197, v151
	v_fma_f32 v210, |v148|, s10, 1.0
	v_fma_f32 v211, |v149|, s10, 1.0
	v_fma_f32 v212, |v150|, s10, 1.0
	v_fma_f32 v213, |v151|, s10, 1.0
	v_rcp_f32_e32 v210, v210
	v_rcp_f32_e32 v211, v211
	v_rcp_f32_e32 v212, v212
	v_rcp_f32_e32 v213, v213
	v_mul_f32_e32 v218, v148, v148
	v_mul_f32_e32 v219, v149, v149
	v_mul_f32_e32 v220, v150, v150
	v_mul_f32_e32 v221, v151, v151
	v_fmaak_f32 v214, v210, v134, 0xbf3a00e3
	v_fmaak_f32 v215, v211, v134, 0xbf3a00e3
	v_fmaak_f32 v216, v212, v134, 0xbf3a00e3
	v_fmaak_f32 v217, v213, v134, 0xbf3a00e3
	v_fmaak_f32 v214, v214, v210, 0x3f35f0e3
	v_fmaak_f32 v215, v215, v211, 0x3f35f0e3
	v_fmaak_f32 v216, v216, v212, 0x3f35f0e3
	v_fmaak_f32 v217, v217, v213, 0x3f35f0e3
	v_fmaak_f32 v214, v214, v210, 0xbe11a98e
	v_fmaak_f32 v215, v215, v211, 0xbe11a98e
	v_fmaak_f32 v216, v216, v212, 0xbe11a98e
	v_fmaak_f32 v217, v217, v213, 0xbe11a98e
	v_fmaak_f32 v214, v214, v210, 0x3e027906
	v_fmaak_f32 v215, v215, v211, 0x3e027906
	v_fmaak_f32 v216, v216, v212, 0x3e027906
	v_fmaak_f32 v217, v217, v213, 0x3e027906
	v_mul_f32_e32 v214, v214, v210
	v_mul_f32_e32 v215, v215, v211
	v_mul_f32_e32 v216, v216, v212
	v_mul_f32_e32 v217, v217, v213
	v_mul_f32_e32 v218, 0xbf38aa3b, v218
	v_mul_f32_e32 v219, 0xbf38aa3b, v219
	v_mul_f32_e32 v220, 0xbf38aa3b, v220
	v_mul_f32_e32 v221, 0xbf38aa3b, v221
	v_exp_f32_e32 v218, v218
	v_exp_f32_e32 v219, v219
	v_exp_f32_e32 v220, v220
	v_exp_f32_e32 v221, v221
	v_cmp_gt_f32_e64 s[18:19], 0, v148
	v_cmp_gt_f32_e64 s[20:21], 0, v149
	v_cmp_gt_f32_e64 s[44:45], 0, v150
	v_cmp_gt_f32_e64 s[46:47], 0, v151
	v_mul_f32_e32 v218, v218, v214
	v_mul_f32_e32 v219, v219, v215
	v_mul_f32_e32 v220, v220, v216
	v_mul_f32_e32 v221, v221, v217
	v_mul_f32_e32 v222, v148, v218
	v_mul_f32_e32 v223, v149, v219
	v_mul_f32_e32 v224, v150, v220
	v_mul_f32_e32 v225, v151, v221
	v_fma_f32 v210, -v148, v218, v148
	v_fma_f32 v211, -v149, v219, v149
	v_fma_f32 v212, -v150, v220, v150
	v_fma_f32 v213, -v151, v221, v151
	v_cndmask_b32_e64 v222, v210, v222, s[18:19]
	v_cndmask_b32_e64 v223, v211, v223, s[20:21]
	v_cndmask_b32_e64 v224, v212, v224, s[44:45]
	v_cndmask_b32_e64 v225, v213, v225, s[46:47]
	v_mul_f32_e32 v144, v144, v222
	v_mul_f32_e32 v145, v145, v223
	v_mul_f32_e32 v146, v146, v224
	v_mul_f32_e32 v147, v147, v225
	v_cvt_pk_bf16_f32 v128, v144, v145
	v_cvt_pk_bf16_f32 v129, v146, v147
	v_cndmask_b32_e64 v104, v140, v156, s[16:17]
	v_cndmask_b32_e64 v105, v141, v157, s[16:17]
	v_cndmask_b32_e64 v106, v142, v158, s[16:17]
	v_cndmask_b32_e64 v107, v143, v159, s[16:17]
	v_cndmask_b32_e64 v108, v140, v88, s[4:5]
	v_cndmask_b32_e64 v109, v141, v89, s[4:5]
	v_cndmask_b32_e64 v110, v142, v90, s[4:5]
	v_cndmask_b32_e64 v111, v143, v91, s[4:5]
	v_mul_f32_dpp v144, v104, v160 row_ror:1 row_mask:0xf bank_mask:0xf
	v_mul_f32_dpp v145, v105, v161 row_ror:1 row_mask:0xf bank_mask:0xf
	v_mul_f32_dpp v146, v106, v162 row_ror:1 row_mask:0xf bank_mask:0xf
	v_mul_f32_dpp v147, v107, v163 row_ror:1 row_mask:0xf bank_mask:0xf
	v_fmac_f32_e32 v144, v140, v164
	v_fmac_f32_e32 v145, v141, v165
	v_fmac_f32_e32 v146, v142, v166
	v_fmac_f32_e32 v147, v143, v167
	v_fmac_f32_dpp v144, v108, v168 row_ror:15 row_mask:0xf bank_mask:0xf
	v_fmac_f32_dpp v145, v109, v169 row_ror:15 row_mask:0xf bank_mask:0xf
	v_fmac_f32_dpp v146, v110, v170 row_ror:15 row_mask:0xf bank_mask:0xf
	v_fmac_f32_dpp v147, v111, v171 row_ror:15 row_mask:0xf bank_mask:0xf
	v_add_f32_e32 v144, v172, v144
	v_add_f32_e32 v145, v173, v145
	v_add_f32_e32 v146, v174, v146
	v_add_f32_e32 v147, v175, v147
	v_cndmask_b32_e64 v104, v136, v152, s[16:17]
	v_cndmask_b32_e64 v105, v137, v153, s[16:17]
	v_cndmask_b32_e64 v106, v138, v154, s[16:17]
	v_cndmask_b32_e64 v107, v139, v155, s[16:17]
	v_cndmask_b32_e64 v108, v136, v80, s[4:5]
	v_cndmask_b32_e64 v109, v137, v81, s[4:5]
	v_cndmask_b32_e64 v110, v138, v82, s[4:5]
	v_cndmask_b32_e64 v111, v139, v83, s[4:5]
	v_mul_f32_dpp v148, v104, v182 row_ror:1 row_mask:0xf bank_mask:0xf
	v_mul_f32_dpp v149, v105, v183 row_ror:1 row_mask:0xf bank_mask:0xf
	v_mul_f32_dpp v150, v106, v184 row_ror:1 row_mask:0xf bank_mask:0xf
	v_mul_f32_dpp v151, v107, v185 row_ror:1 row_mask:0xf bank_mask:0xf
	v_fmac_f32_e32 v148, v136, v186
	v_fmac_f32_e32 v149, v137, v187
	v_fmac_f32_e32 v150, v138, v188
	v_fmac_f32_e32 v151, v139, v189
	v_fmac_f32_dpp v148, v108, v190 row_ror:15 row_mask:0xf bank_mask:0xf
	v_fmac_f32_dpp v149, v109, v191 row_ror:15 row_mask:0xf bank_mask:0xf
	v_fmac_f32_dpp v150, v110, v192 row_ror:15 row_mask:0xf bank_mask:0xf
	v_fmac_f32_dpp v151, v111, v193 row_ror:15 row_mask:0xf bank_mask:0xf
	v_add_f32_e32 v148, v194, v148
	v_add_f32_e32 v149, v195, v149
	v_add_f32_e32 v150, v196, v150
	v_add_f32_e32 v151, v197, v151
	v_fma_f32 v210, |v148|, s10, 1.0
	v_fma_f32 v211, |v149|, s10, 1.0
	v_fma_f32 v212, |v150|, s10, 1.0
	v_fma_f32 v213, |v151|, s10, 1.0
	v_rcp_f32_e32 v210, v210
	v_rcp_f32_e32 v211, v211
	v_rcp_f32_e32 v212, v212
	v_rcp_f32_e32 v213, v213
	v_mul_f32_e32 v218, v148, v148
	v_mul_f32_e32 v219, v149, v149
	v_mul_f32_e32 v220, v150, v150
	v_mul_f32_e32 v221, v151, v151
	v_fmaak_f32 v214, v210, v134, 0xbf3a00e3
	v_fmaak_f32 v215, v211, v134, 0xbf3a00e3
	v_fmaak_f32 v216, v212, v134, 0xbf3a00e3
	v_fmaak_f32 v217, v213, v134, 0xbf3a00e3
	v_fmaak_f32 v214, v214, v210, 0x3f35f0e3
	v_fmaak_f32 v215, v215, v211, 0x3f35f0e3
	v_fmaak_f32 v216, v216, v212, 0x3f35f0e3
	v_fmaak_f32 v217, v217, v213, 0x3f35f0e3
	v_fmaak_f32 v214, v214, v210, 0xbe11a98e
	v_fmaak_f32 v215, v215, v211, 0xbe11a98e
	v_fmaak_f32 v216, v216, v212, 0xbe11a98e
	v_fmaak_f32 v217, v217, v213, 0xbe11a98e
	v_fmaak_f32 v214, v214, v210, 0x3e027906
	v_fmaak_f32 v215, v215, v211, 0x3e027906
	v_fmaak_f32 v216, v216, v212, 0x3e027906
	v_fmaak_f32 v217, v217, v213, 0x3e027906
	v_mul_f32_e32 v214, v214, v210
	v_mul_f32_e32 v215, v215, v211
	v_mul_f32_e32 v216, v216, v212
	v_mul_f32_e32 v217, v217, v213
	v_mul_f32_e32 v218, 0xbf38aa3b, v218
	v_mul_f32_e32 v219, 0xbf38aa3b, v219
	v_mul_f32_e32 v220, 0xbf38aa3b, v220
	v_mul_f32_e32 v221, 0xbf38aa3b, v221
	v_exp_f32_e32 v218, v218
	v_exp_f32_e32 v219, v219
	v_exp_f32_e32 v220, v220
	v_exp_f32_e32 v221, v221
	v_cmp_gt_f32_e64 s[18:19], 0, v148
	v_cmp_gt_f32_e64 s[20:21], 0, v149
	v_cmp_gt_f32_e64 s[44:45], 0, v150
	v_cmp_gt_f32_e64 s[46:47], 0, v151
	v_mul_f32_e32 v218, v218, v214
	v_mul_f32_e32 v219, v219, v215
	v_mul_f32_e32 v220, v220, v216
	v_mul_f32_e32 v221, v221, v217
	v_mul_f32_e32 v222, v148, v218
	v_mul_f32_e32 v223, v149, v219
	v_mul_f32_e32 v224, v150, v220
	v_mul_f32_e32 v225, v151, v221
	v_fma_f32 v210, -v148, v218, v148
	v_fma_f32 v211, -v149, v219, v149
	v_fma_f32 v212, -v150, v220, v150
	v_fma_f32 v213, -v151, v221, v151
	v_cndmask_b32_e64 v222, v210, v222, s[18:19]
	v_cndmask_b32_e64 v223, v211, v223, s[20:21]
	v_cndmask_b32_e64 v224, v212, v224, s[44:45]
	v_cndmask_b32_e64 v225, v213, v225, s[46:47]
	v_mul_f32_e32 v144, v144, v222
	v_mul_f32_e32 v145, v145, v223
	v_mul_f32_e32 v146, v146, v224
	v_mul_f32_e32 v147, v147, v225
	v_cvt_pk_bf16_f32 v100, v144, v145
	v_cvt_pk_bf16_f32 v101, v146, v147
	s_waitcnt lgkmcnt(0)
	v_cndmask_b32_e64 v104, v88, v140, s[16:17]
	v_cndmask_b32_e64 v105, v89, v141, s[16:17]
	v_cndmask_b32_e64 v106, v90, v142, s[16:17]
	v_cndmask_b32_e64 v107, v91, v143, s[16:17]
	v_cndmask_b32_e64 v108, v88, v120, s[4:5]
	v_cndmask_b32_e64 v109, v89, v121, s[4:5]
	v_cndmask_b32_e64 v110, v90, v122, s[4:5]
	v_cndmask_b32_e64 v111, v91, v123, s[4:5]
	v_mul_f32_dpp v144, v104, v160 row_ror:1 row_mask:0xf bank_mask:0xf
	v_mul_f32_dpp v145, v105, v161 row_ror:1 row_mask:0xf bank_mask:0xf
	v_mul_f32_dpp v146, v106, v162 row_ror:1 row_mask:0xf bank_mask:0xf
	v_mul_f32_dpp v147, v107, v163 row_ror:1 row_mask:0xf bank_mask:0xf
	v_fmac_f32_e32 v144, v88, v164
	v_fmac_f32_e32 v145, v89, v165
	v_fmac_f32_e32 v146, v90, v166
	v_fmac_f32_e32 v147, v91, v167
	v_fmac_f32_dpp v144, v108, v168 row_ror:15 row_mask:0xf bank_mask:0xf
	v_fmac_f32_dpp v145, v109, v169 row_ror:15 row_mask:0xf bank_mask:0xf
	v_fmac_f32_dpp v146, v110, v170 row_ror:15 row_mask:0xf bank_mask:0xf
	v_fmac_f32_dpp v147, v111, v171 row_ror:15 row_mask:0xf bank_mask:0xf
	v_add_f32_e32 v144, v172, v144
	v_add_f32_e32 v145, v173, v145
	v_add_f32_e32 v146, v174, v146
	v_add_f32_e32 v147, v175, v147
	v_cndmask_b32_e64 v104, v80, v136, s[16:17]
	v_cndmask_b32_e64 v105, v81, v137, s[16:17]
	v_cndmask_b32_e64 v106, v82, v138, s[16:17]
	v_cndmask_b32_e64 v107, v83, v139, s[16:17]
	v_cndmask_b32_e64 v108, v80, v124, s[4:5]
	v_cndmask_b32_e64 v109, v81, v125, s[4:5]
	v_cndmask_b32_e64 v110, v82, v126, s[4:5]
	v_cndmask_b32_e64 v111, v83, v127, s[4:5]
	v_mul_f32_dpp v148, v104, v182 row_ror:1 row_mask:0xf bank_mask:0xf
	v_mul_f32_dpp v149, v105, v183 row_ror:1 row_mask:0xf bank_mask:0xf
	v_mul_f32_dpp v150, v106, v184 row_ror:1 row_mask:0xf bank_mask:0xf
	v_mul_f32_dpp v151, v107, v185 row_ror:1 row_mask:0xf bank_mask:0xf
	v_fmac_f32_e32 v148, v80, v186
	v_fmac_f32_e32 v149, v81, v187
	v_fmac_f32_e32 v150, v82, v188
	v_fmac_f32_e32 v151, v83, v189
	v_fmac_f32_dpp v148, v108, v190 row_ror:15 row_mask:0xf bank_mask:0xf
	v_fmac_f32_dpp v149, v109, v191 row_ror:15 row_mask:0xf bank_mask:0xf
	v_fmac_f32_dpp v150, v110, v192 row_ror:15 row_mask:0xf bank_mask:0xf
	v_fmac_f32_dpp v151, v111, v193 row_ror:15 row_mask:0xf bank_mask:0xf
	v_add_f32_e32 v148, v194, v148
	v_add_f32_e32 v149, v195, v149
	v_add_f32_e32 v150, v196, v150
	v_add_f32_e32 v151, v197, v151
	v_fma_f32 v210, |v148|, s10, 1.0
	v_fma_f32 v211, |v149|, s10, 1.0
	v_fma_f32 v212, |v150|, s10, 1.0
	v_fma_f32 v213, |v151|, s10, 1.0
	v_rcp_f32_e32 v210, v210
	v_rcp_f32_e32 v211, v211
	v_rcp_f32_e32 v212, v212
	v_rcp_f32_e32 v213, v213
	v_mul_f32_e32 v218, v148, v148
	v_mul_f32_e32 v219, v149, v149
	v_mul_f32_e32 v220, v150, v150
	v_mul_f32_e32 v221, v151, v151
	v_fmaak_f32 v214, v210, v134, 0xbf3a00e3
	v_fmaak_f32 v215, v211, v134, 0xbf3a00e3
	v_fmaak_f32 v216, v212, v134, 0xbf3a00e3
	v_fmaak_f32 v217, v213, v134, 0xbf3a00e3
	v_fmaak_f32 v214, v214, v210, 0x3f35f0e3
	v_fmaak_f32 v215, v215, v211, 0x3f35f0e3
	v_fmaak_f32 v216, v216, v212, 0x3f35f0e3
	v_fmaak_f32 v217, v217, v213, 0x3f35f0e3
	v_fmaak_f32 v214, v214, v210, 0xbe11a98e
	v_fmaak_f32 v215, v215, v211, 0xbe11a98e
	v_fmaak_f32 v216, v216, v212, 0xbe11a98e
	v_fmaak_f32 v217, v217, v213, 0xbe11a98e
	v_fmaak_f32 v214, v214, v210, 0x3e027906
	v_fmaak_f32 v215, v215, v211, 0x3e027906
	v_fmaak_f32 v216, v216, v212, 0x3e027906
	v_fmaak_f32 v217, v217, v213, 0x3e027906
	v_mul_f32_e32 v214, v214, v210
	v_mul_f32_e32 v215, v215, v211
	v_mul_f32_e32 v216, v216, v212
	v_mul_f32_e32 v217, v217, v213
	v_mul_f32_e32 v218, 0xbf38aa3b, v218
	v_mul_f32_e32 v219, 0xbf38aa3b, v219
	v_mul_f32_e32 v220, 0xbf38aa3b, v220
	v_mul_f32_e32 v221, 0xbf38aa3b, v221
	v_exp_f32_e32 v218, v218
	v_exp_f32_e32 v219, v219
	v_exp_f32_e32 v220, v220
	v_exp_f32_e32 v221, v221
	v_cmp_gt_f32_e64 s[18:19], 0, v148
	v_cmp_gt_f32_e64 s[20:21], 0, v149
	v_cmp_gt_f32_e64 s[44:45], 0, v150
	v_cmp_gt_f32_e64 s[46:47], 0, v151
	v_mul_f32_e32 v218, v218, v214
	v_mul_f32_e32 v219, v219, v215
	v_mul_f32_e32 v220, v220, v216
	v_mul_f32_e32 v221, v221, v217
	v_mul_f32_e32 v222, v148, v218
	v_mul_f32_e32 v223, v149, v219
	v_mul_f32_e32 v224, v150, v220
	v_mul_f32_e32 v225, v151, v221
	v_fma_f32 v210, -v148, v218, v148
	v_fma_f32 v211, -v149, v219, v149
	v_fma_f32 v212, -v150, v220, v150
	v_fma_f32 v213, -v151, v221, v151
	v_cndmask_b32_e64 v222, v210, v222, s[18:19]
	v_cndmask_b32_e64 v223, v211, v223, s[20:21]
	v_cndmask_b32_e64 v224, v212, v224, s[44:45]
	v_cndmask_b32_e64 v225, v213, v225, s[46:47]
	v_mul_f32_e32 v144, v144, v222
	v_mul_f32_e32 v145, v145, v223
	v_mul_f32_e32 v146, v146, v224
	v_mul_f32_e32 v147, v147, v225
	v_cvt_pk_bf16_f32 v96, v144, v145
	v_cvt_pk_bf16_f32 v97, v146, v147
	ds_read_b128 v[120:123], v228 offset:1024
	ds_read_b128 v[124:127], v228 offset:1152
	s_waitcnt lgkmcnt(0)
	v_cndmask_b32_e64 v104, v92, v120, s[16:17]
	v_cndmask_b32_e64 v105, v93, v121, s[16:17]
	v_cndmask_b32_e64 v106, v94, v122, s[16:17]
	v_cndmask_b32_e64 v107, v95, v123, s[16:17]
	v_cndmask_b32_e64 v108, v92, v116, s[4:5]
	v_cndmask_b32_e64 v109, v93, v117, s[4:5]
	v_cndmask_b32_e64 v110, v94, v118, s[4:5]
	v_cndmask_b32_e64 v111, v95, v119, s[4:5]
	v_mul_f32_dpp v144, v104, v160 row_ror:1 row_mask:0xf bank_mask:0xf
	v_mul_f32_dpp v145, v105, v161 row_ror:1 row_mask:0xf bank_mask:0xf
	v_mul_f32_dpp v146, v106, v162 row_ror:1 row_mask:0xf bank_mask:0xf
	v_mul_f32_dpp v147, v107, v163 row_ror:1 row_mask:0xf bank_mask:0xf
	v_fmac_f32_e32 v144, v92, v164
	v_fmac_f32_e32 v145, v93, v165
	v_fmac_f32_e32 v146, v94, v166
	v_fmac_f32_e32 v147, v95, v167
	v_fmac_f32_dpp v144, v108, v168 row_ror:15 row_mask:0xf bank_mask:0xf
	v_fmac_f32_dpp v145, v109, v169 row_ror:15 row_mask:0xf bank_mask:0xf
	v_fmac_f32_dpp v146, v110, v170 row_ror:15 row_mask:0xf bank_mask:0xf
	v_fmac_f32_dpp v147, v111, v171 row_ror:15 row_mask:0xf bank_mask:0xf
	v_add_f32_e32 v144, v172, v144
	v_add_f32_e32 v145, v173, v145
	v_add_f32_e32 v146, v174, v146
	v_add_f32_e32 v147, v175, v147
	v_cndmask_b32_e64 v104, v36, v124, s[16:17]
	v_cndmask_b32_e64 v105, v37, v125, s[16:17]
	v_cndmask_b32_e64 v106, v38, v126, s[16:17]
	v_cndmask_b32_e64 v107, v39, v127, s[16:17]
	v_cndmask_b32_e64 v108, v36, v112, s[4:5]
	v_cndmask_b32_e64 v109, v37, v113, s[4:5]
	v_cndmask_b32_e64 v110, v38, v114, s[4:5]
	v_cndmask_b32_e64 v111, v39, v115, s[4:5]
	v_mul_f32_dpp v148, v104, v182 row_ror:1 row_mask:0xf bank_mask:0xf
	v_mul_f32_dpp v149, v105, v183 row_ror:1 row_mask:0xf bank_mask:0xf
	v_mul_f32_dpp v150, v106, v184 row_ror:1 row_mask:0xf bank_mask:0xf
	v_mul_f32_dpp v151, v107, v185 row_ror:1 row_mask:0xf bank_mask:0xf
	v_fmac_f32_e32 v148, v36, v186
	v_fmac_f32_e32 v149, v37, v187
	v_fmac_f32_e32 v150, v38, v188
	v_fmac_f32_e32 v151, v39, v189
	v_fmac_f32_dpp v148, v108, v190 row_ror:15 row_mask:0xf bank_mask:0xf
	v_fmac_f32_dpp v149, v109, v191 row_ror:15 row_mask:0xf bank_mask:0xf
	v_fmac_f32_dpp v150, v110, v192 row_ror:15 row_mask:0xf bank_mask:0xf
	v_fmac_f32_dpp v151, v111, v193 row_ror:15 row_mask:0xf bank_mask:0xf
	v_add_f32_e32 v148, v194, v148
	v_add_f32_e32 v149, v195, v149
	v_add_f32_e32 v150, v196, v150
	v_add_f32_e32 v151, v197, v151
	v_fma_f32 v210, |v148|, s10, 1.0
	v_fma_f32 v211, |v149|, s10, 1.0
	v_fma_f32 v212, |v150|, s10, 1.0
	v_fma_f32 v213, |v151|, s10, 1.0
	v_rcp_f32_e32 v210, v210
	v_rcp_f32_e32 v211, v211
	v_rcp_f32_e32 v212, v212
	v_rcp_f32_e32 v213, v213
	v_mul_f32_e32 v218, v148, v148
	v_mul_f32_e32 v219, v149, v149
	v_mul_f32_e32 v220, v150, v150
	v_mul_f32_e32 v221, v151, v151
	v_fmaak_f32 v214, v210, v134, 0xbf3a00e3
	v_fmaak_f32 v215, v211, v134, 0xbf3a00e3
	v_fmaak_f32 v216, v212, v134, 0xbf3a00e3
	v_fmaak_f32 v217, v213, v134, 0xbf3a00e3
	v_fmaak_f32 v214, v214, v210, 0x3f35f0e3
	v_fmaak_f32 v215, v215, v211, 0x3f35f0e3
	v_fmaak_f32 v216, v216, v212, 0x3f35f0e3
	v_fmaak_f32 v217, v217, v213, 0x3f35f0e3
	v_fmaak_f32 v214, v214, v210, 0xbe11a98e
	v_fmaak_f32 v215, v215, v211, 0xbe11a98e
	v_fmaak_f32 v216, v216, v212, 0xbe11a98e
	v_fmaak_f32 v217, v217, v213, 0xbe11a98e
	v_fmaak_f32 v214, v214, v210, 0x3e027906
	v_fmaak_f32 v215, v215, v211, 0x3e027906
	v_fmaak_f32 v216, v216, v212, 0x3e027906
	v_fmaak_f32 v217, v217, v213, 0x3e027906
	v_mul_f32_e32 v214, v214, v210
	v_mul_f32_e32 v215, v215, v211
	v_mul_f32_e32 v216, v216, v212
	v_mul_f32_e32 v217, v217, v213
	v_mul_f32_e32 v218, 0xbf38aa3b, v218
	v_mul_f32_e32 v219, 0xbf38aa3b, v219
	v_mul_f32_e32 v220, 0xbf38aa3b, v220
	v_mul_f32_e32 v221, 0xbf38aa3b, v221
	v_exp_f32_e32 v218, v218
	v_exp_f32_e32 v219, v219
	v_exp_f32_e32 v220, v220
	v_exp_f32_e32 v221, v221
	v_cmp_gt_f32_e64 s[18:19], 0, v148
	v_cmp_gt_f32_e64 s[20:21], 0, v149
	v_cmp_gt_f32_e64 s[44:45], 0, v150
	v_cmp_gt_f32_e64 s[46:47], 0, v151
	v_mul_f32_e32 v218, v218, v214
	v_mul_f32_e32 v219, v219, v215
	v_mul_f32_e32 v220, v220, v216
	v_mul_f32_e32 v221, v221, v217
	v_mul_f32_e32 v222, v148, v218
	v_mul_f32_e32 v223, v149, v219
	v_mul_f32_e32 v224, v150, v220
	v_mul_f32_e32 v225, v151, v221
	v_fma_f32 v210, -v148, v218, v148
	v_fma_f32 v211, -v149, v219, v149
	v_fma_f32 v212, -v150, v220, v150
	v_fma_f32 v213, -v151, v221, v151
	v_cndmask_b32_e64 v222, v210, v222, s[18:19]
	v_cndmask_b32_e64 v223, v211, v223, s[20:21]
	v_cndmask_b32_e64 v224, v212, v224, s[44:45]
	v_cndmask_b32_e64 v225, v213, v225, s[46:47]
	v_mul_f32_e32 v144, v144, v222
	v_mul_f32_e32 v145, v145, v223
	v_mul_f32_e32 v146, v146, v224
	v_mul_f32_e32 v147, v147, v225
	v_cvt_pk_bf16_f32 v156, v144, v145
	v_cvt_pk_bf16_f32 v157, v146, v147
	s_and_b64 vcc, exec, s[66:67]
	s_cbranch_vccz .Lp6e_z3
	ds_read_b128 v[120:123], v135 offset:1536
	ds_read_b128 v[124:127], v135 offset:1664
	s_branch .Lp6e_d3

.Lp6e_d3:
	v_cndmask_b32_e64 v104, v116, v92, s[16:17]
	v_cndmask_b32_e64 v105, v117, v93, s[16:17]
	v_cndmask_b32_e64 v106, v118, v94, s[16:17]
	v_cndmask_b32_e64 v107, v119, v95, s[16:17]
	v_cndmask_b32_e64 v108, v116, v76, s[4:5]
	v_cndmask_b32_e64 v109, v117, v77, s[4:5]
	v_cndmask_b32_e64 v110, v118, v78, s[4:5]
	v_cndmask_b32_e64 v111, v119, v79, s[4:5]
	v_mul_f32_dpp v144, v104, v160 row_ror:1 row_mask:0xf bank_mask:0xf
	v_mul_f32_dpp v145, v105, v161 row_ror:1 row_mask:0xf bank_mask:0xf
	v_mul_f32_dpp v146, v106, v162 row_ror:1 row_mask:0xf bank_mask:0xf
	v_mul_f32_dpp v147, v107, v163 row_ror:1 row_mask:0xf bank_mask:0xf
	v_fmac_f32_e32 v144, v116, v164
	v_fmac_f32_e32 v145, v117, v165
	v_fmac_f32_e32 v146, v118, v166
	v_fmac_f32_e32 v147, v119, v167
	v_fmac_f32_dpp v144, v108, v168 row_ror:15 row_mask:0xf bank_mask:0xf
	v_fmac_f32_dpp v145, v109, v169 row_ror:15 row_mask:0xf bank_mask:0xf
	v_fmac_f32_dpp v146, v110, v170 row_ror:15 row_mask:0xf bank_mask:0xf
	v_fmac_f32_dpp v147, v111, v171 row_ror:15 row_mask:0xf bank_mask:0xf
	v_add_f32_e32 v144, v172, v144
	v_add_f32_e32 v145, v173, v145
	v_add_f32_e32 v146, v174, v146
	v_add_f32_e32 v147, v175, v147
	v_cndmask_b32_e64 v104, v112, v36, s[16:17]
	v_cndmask_b32_e64 v105, v113, v37, s[16:17]
	v_cndmask_b32_e64 v106, v114, v38, s[16:17]
	v_cndmask_b32_e64 v107, v115, v39, s[16:17]
	v_cndmask_b32_e64 v108, v112, v72, s[4:5]
	v_cndmask_b32_e64 v109, v113, v73, s[4:5]
	v_cndmask_b32_e64 v110, v114, v74, s[4:5]
	v_cndmask_b32_e64 v111, v115, v75, s[4:5]
	v_mul_f32_dpp v148, v104, v182 row_ror:1 row_mask:0xf bank_mask:0xf
	v_mul_f32_dpp v149, v105, v183 row_ror:1 row_mask:0xf bank_mask:0xf
	v_mul_f32_dpp v150, v106, v184 row_ror:1 row_mask:0xf bank_mask:0xf
	v_mul_f32_dpp v151, v107, v185 row_ror:1 row_mask:0xf bank_mask:0xf
	v_fmac_f32_e32 v148, v112, v186
	v_fmac_f32_e32 v149, v113, v187
	v_fmac_f32_e32 v150, v114, v188
	v_fmac_f32_e32 v151, v115, v189
	v_fmac_f32_dpp v148, v108, v190 row_ror:15 row_mask:0xf bank_mask:0xf
	v_fmac_f32_dpp v149, v109, v191 row_ror:15 row_mask:0xf bank_mask:0xf
	v_fmac_f32_dpp v150, v110, v192 row_ror:15 row_mask:0xf bank_mask:0xf
	v_fmac_f32_dpp v151, v111, v193 row_ror:15 row_mask:0xf bank_mask:0xf
	v_add_f32_e32 v148, v194, v148
	v_add_f32_e32 v149, v195, v149
	v_add_f32_e32 v150, v196, v150
	v_add_f32_e32 v151, v197, v151
	v_fma_f32 v210, |v148|, s10, 1.0
	v_fma_f32 v211, |v149|, s10, 1.0
	v_fma_f32 v212, |v150|, s10, 1.0
	v_fma_f32 v213, |v151|, s10, 1.0
	v_rcp_f32_e32 v210, v210
	v_rcp_f32_e32 v211, v211
	v_rcp_f32_e32 v212, v212
	v_rcp_f32_e32 v213, v213
	v_mul_f32_e32 v218, v148, v148
	v_mul_f32_e32 v219, v149, v149
	v_mul_f32_e32 v220, v150, v150
	v_mul_f32_e32 v221, v151, v151
	v_fmaak_f32 v214, v210, v134, 0xbf3a00e3
	v_fmaak_f32 v215, v211, v134, 0xbf3a00e3
	v_fmaak_f32 v216, v212, v134, 0xbf3a00e3
	v_fmaak_f32 v217, v213, v134, 0xbf3a00e3
	v_fmaak_f32 v214, v214, v210, 0x3f35f0e3
	v_fmaak_f32 v215, v215, v211, 0x3f35f0e3
	v_fmaak_f32 v216, v216, v212, 0x3f35f0e3
	v_fmaak_f32 v217, v217, v213, 0x3f35f0e3
	v_fmaak_f32 v214, v214, v210, 0xbe11a98e
	v_fmaak_f32 v215, v215, v211, 0xbe11a98e
	v_fmaak_f32 v216, v216, v212, 0xbe11a98e
	v_fmaak_f32 v217, v217, v213, 0xbe11a98e
	v_fmaak_f32 v214, v214, v210, 0x3e027906
	v_fmaak_f32 v215, v215, v211, 0x3e027906
	v_fmaak_f32 v216, v216, v212, 0x3e027906
	v_fmaak_f32 v217, v217, v213, 0x3e027906
	v_mul_f32_e32 v214, v214, v210
	v_mul_f32_e32 v215, v215, v211
	v_mul_f32_e32 v216, v216, v212
	v_mul_f32_e32 v217, v217, v213
	v_mul_f32_e32 v218, 0xbf38aa3b, v218
	v_mul_f32_e32 v219, 0xbf38aa3b, v219
	v_mul_f32_e32 v220, 0xbf38aa3b, v220
	v_mul_f32_e32 v221, 0xbf38aa3b, v221
	v_exp_f32_e32 v218, v218
	v_exp_f32_e32 v219, v219
	v_exp_f32_e32 v220, v220
	v_exp_f32_e32 v221, v221
	v_cmp_gt_f32_e64 s[18:19], 0, v148
	v_cmp_gt_f32_e64 s[20:21], 0, v149
	v_cmp_gt_f32_e64 s[44:45], 0, v150
	v_cmp_gt_f32_e64 s[46:47], 0, v151
	v_mul_f32_e32 v218, v218, v214
	v_mul_f32_e32 v219, v219, v215
	v_mul_f32_e32 v220, v220, v216
	v_mul_f32_e32 v221, v221, v217
	v_mul_f32_e32 v222, v148, v218
	v_mul_f32_e32 v223, v149, v219
	v_mul_f32_e32 v224, v150, v220
	v_mul_f32_e32 v225, v151, v221
	v_fma_f32 v210, -v148, v218, v148
	v_fma_f32 v211, -v149, v219, v149
	v_fma_f32 v212, -v150, v220, v150
	v_fma_f32 v213, -v151, v221, v151
	v_cndmask_b32_e64 v222, v210, v222, s[18:19]
	v_cndmask_b32_e64 v223, v211, v223, s[20:21]
	v_cndmask_b32_e64 v224, v212, v224, s[44:45]
	v_cndmask_b32_e64 v225, v213, v225, s[46:47]
	v_mul_f32_e32 v144, v144, v222
	v_mul_f32_e32 v145, v145, v223
	v_mul_f32_e32 v146, v146, v224
	v_mul_f32_e32 v147, v147, v225
	v_cvt_pk_bf16_f32 v152, v144, v145
	v_cvt_pk_bf16_f32 v153, v146, v147
	v_cndmask_b32_e64 v104, v76, v116, s[16:17]
	v_cndmask_b32_e64 v105, v77, v117, s[16:17]
	v_cndmask_b32_e64 v106, v78, v118, s[16:17]
	v_cndmask_b32_e64 v107, v79, v119, s[16:17]
	v_cndmask_b32_e64 v108, v76, v68, s[4:5]
	v_cndmask_b32_e64 v109, v77, v69, s[4:5]
	v_cndmask_b32_e64 v110, v78, v70, s[4:5]
	v_cndmask_b32_e64 v111, v79, v71, s[4:5]
	v_mul_f32_dpp v144, v104, v160 row_ror:1 row_mask:0xf bank_mask:0xf
	v_mul_f32_dpp v145, v105, v161 row_ror:1 row_mask:0xf bank_mask:0xf
	v_mul_f32_dpp v146, v106, v162 row_ror:1 row_mask:0xf bank_mask:0xf
	v_mul_f32_dpp v147, v107, v163 row_ror:1 row_mask:0xf bank_mask:0xf
	v_fmac_f32_e32 v144, v76, v164
	v_fmac_f32_e32 v145, v77, v165
	v_fmac_f32_e32 v146, v78, v166
	v_fmac_f32_e32 v147, v79, v167
	v_fmac_f32_dpp v144, v108, v168 row_ror:15 row_mask:0xf bank_mask:0xf
	v_fmac_f32_dpp v145, v109, v169 row_ror:15 row_mask:0xf bank_mask:0xf
	v_fmac_f32_dpp v146, v110, v170 row_ror:15 row_mask:0xf bank_mask:0xf
	v_fmac_f32_dpp v147, v111, v171 row_ror:15 row_mask:0xf bank_mask:0xf
	v_add_f32_e32 v144, v172, v144
	v_add_f32_e32 v145, v173, v145
	v_add_f32_e32 v146, v174, v146
	v_add_f32_e32 v147, v175, v147
	v_cndmask_b32_e64 v104, v72, v112, s[16:17]
	v_cndmask_b32_e64 v105, v73, v113, s[16:17]
	v_cndmask_b32_e64 v106, v74, v114, s[16:17]
	v_cndmask_b32_e64 v107, v75, v115, s[16:17]
	v_cndmask_b32_e64 v108, v72, v64, s[4:5]
	v_cndmask_b32_e64 v109, v73, v65, s[4:5]
	v_cndmask_b32_e64 v110, v74, v66, s[4:5]
	v_cndmask_b32_e64 v111, v75, v67, s[4:5]
	v_mul_f32_dpp v148, v104, v182 row_ror:1 row_mask:0xf bank_mask:0xf
	v_mul_f32_dpp v149, v105, v183 row_ror:1 row_mask:0xf bank_mask:0xf
	v_mul_f32_dpp v150, v106, v184 row_ror:1 row_mask:0xf bank_mask:0xf
	v_mul_f32_dpp v151, v107, v185 row_ror:1 row_mask:0xf bank_mask:0xf
	v_fmac_f32_e32 v148, v72, v186
	v_fmac_f32_e32 v149, v73, v187
	v_fmac_f32_e32 v150, v74, v188
	v_fmac_f32_e32 v151, v75, v189
	v_fmac_f32_dpp v148, v108, v190 row_ror:15 row_mask:0xf bank_mask:0xf
	v_fmac_f32_dpp v149, v109, v191 row_ror:15 row_mask:0xf bank_mask:0xf
	v_fmac_f32_dpp v150, v110, v192 row_ror:15 row_mask:0xf bank_mask:0xf
	v_fmac_f32_dpp v151, v111, v193 row_ror:15 row_mask:0xf bank_mask:0xf
	v_add_f32_e32 v148, v194, v148
	v_add_f32_e32 v149, v195, v149
	v_add_f32_e32 v150, v196, v150
	v_add_f32_e32 v151, v197, v151
	v_fma_f32 v210, |v148|, s10, 1.0
	v_fma_f32 v211, |v149|, s10, 1.0
	v_fma_f32 v212, |v150|, s10, 1.0
	v_fma_f32 v213, |v151|, s10, 1.0
	v_rcp_f32_e32 v210, v210
	v_rcp_f32_e32 v211, v211
	v_rcp_f32_e32 v212, v212
	v_rcp_f32_e32 v213, v213
	v_mul_f32_e32 v218, v148, v148
	v_mul_f32_e32 v219, v149, v149
	v_mul_f32_e32 v220, v150, v150
	v_mul_f32_e32 v221, v151, v151
	v_fmaak_f32 v214, v210, v134, 0xbf3a00e3
	v_fmaak_f32 v215, v211, v134, 0xbf3a00e3
	v_fmaak_f32 v216, v212, v134, 0xbf3a00e3
	v_fmaak_f32 v217, v213, v134, 0xbf3a00e3
	v_fmaak_f32 v214, v214, v210, 0x3f35f0e3
	v_fmaak_f32 v215, v215, v211, 0x3f35f0e3
	v_fmaak_f32 v216, v216, v212, 0x3f35f0e3
	v_fmaak_f32 v217, v217, v213, 0x3f35f0e3
	v_fmaak_f32 v214, v214, v210, 0xbe11a98e
	v_fmaak_f32 v215, v215, v211, 0xbe11a98e
	v_fmaak_f32 v216, v216, v212, 0xbe11a98e
	v_fmaak_f32 v217, v217, v213, 0xbe11a98e
	v_fmaak_f32 v214, v214, v210, 0x3e027906
	v_fmaak_f32 v215, v215, v211, 0x3e027906
	v_fmaak_f32 v216, v216, v212, 0x3e027906
	v_fmaak_f32 v217, v217, v213, 0x3e027906
	v_mul_f32_e32 v214, v214, v210
	v_mul_f32_e32 v215, v215, v211
	v_mul_f32_e32 v216, v216, v212
	v_mul_f32_e32 v217, v217, v213
	v_mul_f32_e32 v218, 0xbf38aa3b, v218
	v_mul_f32_e32 v219, 0xbf38aa3b, v219
	v_mul_f32_e32 v220, 0xbf38aa3b, v220
	v_mul_f32_e32 v221, 0xbf38aa3b, v221
	v_exp_f32_e32 v218, v218
	v_exp_f32_e32 v219, v219
	v_exp_f32_e32 v220, v220
	v_exp_f32_e32 v221, v221
	v_cmp_gt_f32_e64 s[18:19], 0, v148
	v_cmp_gt_f32_e64 s[20:21], 0, v149
	v_cmp_gt_f32_e64 s[44:45], 0, v150
	v_cmp_gt_f32_e64 s[46:47], 0, v151
	v_mul_f32_e32 v218, v218, v214
	v_mul_f32_e32 v219, v219, v215
	v_mul_f32_e32 v220, v220, v216
	v_mul_f32_e32 v221, v221, v217
	v_mul_f32_e32 v222, v148, v218
	v_mul_f32_e32 v223, v149, v219
	v_mul_f32_e32 v224, v150, v220
	v_mul_f32_e32 v225, v151, v221
	v_fma_f32 v210, -v148, v218, v148
	v_fma_f32 v211, -v149, v219, v149
	v_fma_f32 v212, -v150, v220, v150
	v_fma_f32 v213, -v151, v221, v151
	v_cndmask_b32_e64 v222, v210, v222, s[18:19]
	v_cndmask_b32_e64 v223, v211, v223, s[20:21]
	v_cndmask_b32_e64 v224, v212, v224, s[44:45]
	v_cndmask_b32_e64 v225, v213, v225, s[46:47]
	v_mul_f32_e32 v144, v144, v222
	v_mul_f32_e32 v145, v145, v223
	v_mul_f32_e32 v146, v146, v224
	v_mul_f32_e32 v147, v147, v225
	v_cvt_pk_bf16_f32 v140, v144, v145
	v_cvt_pk_bf16_f32 v141, v146, v147
	s_waitcnt lgkmcnt(0)
	v_cndmask_b32_e64 v104, v68, v76, s[16:17]
	v_cndmask_b32_e64 v105, v69, v77, s[16:17]
	v_cndmask_b32_e64 v106, v70, v78, s[16:17]
	v_cndmask_b32_e64 v107, v71, v79, s[16:17]
	v_cndmask_b32_e64 v108, v68, v120, s[4:5]
	v_cndmask_b32_e64 v109, v69, v121, s[4:5]
	v_cndmask_b32_e64 v110, v70, v122, s[4:5]
	v_cndmask_b32_e64 v111, v71, v123, s[4:5]
	v_mul_f32_dpp v144, v104, v160 row_ror:1 row_mask:0xf bank_mask:0xf
	v_mul_f32_dpp v145, v105, v161 row_ror:1 row_mask:0xf bank_mask:0xf
	v_mul_f32_dpp v146, v106, v162 row_ror:1 row_mask:0xf bank_mask:0xf
	v_mul_f32_dpp v147, v107, v163 row_ror:1 row_mask:0xf bank_mask:0xf
	v_fmac_f32_e32 v144, v68, v164
	v_fmac_f32_e32 v145, v69, v165
	v_fmac_f32_e32 v146, v70, v166
	v_fmac_f32_e32 v147, v71, v167
	v_fmac_f32_dpp v144, v108, v168 row_ror:15 row_mask:0xf bank_mask:0xf
	v_fmac_f32_dpp v145, v109, v169 row_ror:15 row_mask:0xf bank_mask:0xf
	v_fmac_f32_dpp v146, v110, v170 row_ror:15 row_mask:0xf bank_mask:0xf
	v_fmac_f32_dpp v147, v111, v171 row_ror:15 row_mask:0xf bank_mask:0xf
	v_add_f32_e32 v144, v172, v144
	v_add_f32_e32 v145, v173, v145
	v_add_f32_e32 v146, v174, v146
	v_add_f32_e32 v147, v175, v147
	v_cndmask_b32_e64 v104, v64, v72, s[16:17]
	v_cndmask_b32_e64 v105, v65, v73, s[16:17]
	v_cndmask_b32_e64 v106, v66, v74, s[16:17]
	v_cndmask_b32_e64 v107, v67, v75, s[16:17]
	v_cndmask_b32_e64 v108, v64, v124, s[4:5]
	v_cndmask_b32_e64 v109, v65, v125, s[4:5]
	v_cndmask_b32_e64 v110, v66, v126, s[4:5]
	v_cndmask_b32_e64 v111, v67, v127, s[4:5]
	v_mul_f32_dpp v148, v104, v182 row_ror:1 row_mask:0xf bank_mask:0xf
	v_mul_f32_dpp v149, v105, v183 row_ror:1 row_mask:0xf bank_mask:0xf
	v_mul_f32_dpp v150, v106, v184 row_ror:1 row_mask:0xf bank_mask:0xf
	v_mul_f32_dpp v151, v107, v185 row_ror:1 row_mask:0xf bank_mask:0xf
	v_fmac_f32_e32 v148, v64, v186
	v_fmac_f32_e32 v149, v65, v187
	v_fmac_f32_e32 v150, v66, v188
	v_fmac_f32_e32 v151, v67, v189
	v_fmac_f32_dpp v148, v108, v190 row_ror:15 row_mask:0xf bank_mask:0xf
	v_fmac_f32_dpp v149, v109, v191 row_ror:15 row_mask:0xf bank_mask:0xf
	v_fmac_f32_dpp v150, v110, v192 row_ror:15 row_mask:0xf bank_mask:0xf
	v_fmac_f32_dpp v151, v111, v193 row_ror:15 row_mask:0xf bank_mask:0xf
	v_add_f32_e32 v148, v194, v148
	v_add_f32_e32 v149, v195, v149
	v_add_f32_e32 v150, v196, v150
	v_add_f32_e32 v151, v197, v151
	v_fma_f32 v210, |v148|, s10, 1.0
	v_fma_f32 v211, |v149|, s10, 1.0
	v_fma_f32 v212, |v150|, s10, 1.0
	v_fma_f32 v213, |v151|, s10, 1.0
	v_rcp_f32_e32 v210, v210
	v_rcp_f32_e32 v211, v211
	v_rcp_f32_e32 v212, v212
	v_rcp_f32_e32 v213, v213
	v_mul_f32_e32 v218, v148, v148
	v_mul_f32_e32 v219, v149, v149
	v_mul_f32_e32 v220, v150, v150
	v_mul_f32_e32 v221, v151, v151
	v_fmaak_f32 v214, v210, v134, 0xbf3a00e3
	v_fmaak_f32 v215, v211, v134, 0xbf3a00e3
	v_fmaak_f32 v216, v212, v134, 0xbf3a00e3
	v_fmaak_f32 v217, v213, v134, 0xbf3a00e3
	v_fmaak_f32 v214, v214, v210, 0x3f35f0e3
	v_fmaak_f32 v215, v215, v211, 0x3f35f0e3
	v_fmaak_f32 v216, v216, v212, 0x3f35f0e3
	v_fmaak_f32 v217, v217, v213, 0x3f35f0e3
	v_fmaak_f32 v214, v214, v210, 0xbe11a98e
	v_fmaak_f32 v215, v215, v211, 0xbe11a98e
	v_fmaak_f32 v216, v216, v212, 0xbe11a98e
	v_fmaak_f32 v217, v217, v213, 0xbe11a98e
	v_fmaak_f32 v214, v214, v210, 0x3e027906
	v_fmaak_f32 v215, v215, v211, 0x3e027906
	v_fmaak_f32 v216, v216, v212, 0x3e027906
	v_fmaak_f32 v217, v217, v213, 0x3e027906
	v_mul_f32_e32 v214, v214, v210
	v_mul_f32_e32 v215, v215, v211
	v_mul_f32_e32 v216, v216, v212
	v_mul_f32_e32 v217, v217, v213
	v_mul_f32_e32 v218, 0xbf38aa3b, v218
	v_mul_f32_e32 v219, 0xbf38aa3b, v219
	v_mul_f32_e32 v220, 0xbf38aa3b, v220
	v_mul_f32_e32 v221, 0xbf38aa3b, v221
	v_exp_f32_e32 v218, v218
	v_exp_f32_e32 v219, v219
	v_exp_f32_e32 v220, v220
	v_exp_f32_e32 v221, v221
	v_cmp_gt_f32_e64 s[18:19], 0, v148
	v_cmp_gt_f32_e64 s[20:21], 0, v149
	v_cmp_gt_f32_e64 s[44:45], 0, v150
	v_cmp_gt_f32_e64 s[46:47], 0, v151
	v_mul_f32_e32 v218, v218, v214
	v_mul_f32_e32 v219, v219, v215
	v_mul_f32_e32 v220, v220, v216
	v_mul_f32_e32 v221, v221, v217
	v_mul_f32_e32 v222, v148, v218
	v_mul_f32_e32 v223, v149, v219
	v_mul_f32_e32 v224, v150, v220
	v_mul_f32_e32 v225, v151, v221
	v_fma_f32 v210, -v148, v218, v148
	v_fma_f32 v211, -v149, v219, v149
	v_fma_f32 v212, -v150, v220, v150
	v_fma_f32 v213, -v151, v221, v151
	v_cndmask_b32_e64 v222, v210, v222, s[18:19]
	v_cndmask_b32_e64 v223, v211, v223, s[20:21]
	v_cndmask_b32_e64 v224, v212, v224, s[44:45]
	v_cndmask_b32_e64 v225, v213, v225, s[46:47]
	v_mul_f32_e32 v144, v144, v222
	v_mul_f32_e32 v145, v145, v223
	v_mul_f32_e32 v146, v146, v224
	v_mul_f32_e32 v147, v147, v225
	v_cvt_pk_bf16_f32 v136, v144, v145
	v_cvt_pk_bf16_f32 v137, v146, v147
	s_lshl_b32 s2, s8, 7
	s_or_b32 s2, s2, s53
	v_lshl_add_u32 v226, v207, 2, s2
	v_lshlrev_b32_e32 v226, 2, v226
	v_add_u32_e32 v210, 0x5800, v226
	v_add_u32_e32 v211, 0xb000, v226
	v_add_u32_e32 v212, 0x2c00, v226
	v_add_u32_e32 v213, 0x8400, v226
	v_add_u32_e32 v214, 0xdc00, v226
	global_load_dwordx4 v[160:163], v226, s[70:71] offset:64
	global_load_dwordx4 v[164:167], v210, s[70:71] offset:64
	global_load_dwordx4 v[168:171], v211, s[70:71] offset:64
	global_load_dwordx4 v[182:185], v212, s[70:71] offset:64
	global_load_dwordx4 v[186:189], v213, s[70:71] offset:64
	global_load_dwordx4 v[190:193], v214, s[70:71] offset:64
	global_load_dwordx4 v[172:175], v226, s[58:59] offset:64
	global_load_dwordx4 v[194:197], v212, s[58:59] offset:64
	s_and_b64 vcc, exec, s[6:7]
	s_cbranch_vccz .Lp6e_z4
	ds_read_b128 v[120:123], v228 offset:64
	ds_read_b128 v[124:127], v228 offset:192
	s_branch .Lp6e_d4

.Lp6e_d4:
	s_waitcnt lgkmcnt(0)
	s_waitcnt vmcnt(0)
	v_cndmask_b32_e64 v104, v60, v120, s[16:17]
	v_cndmask_b32_e64 v105, v61, v121, s[16:17]
	v_cndmask_b32_e64 v106, v62, v122, s[16:17]
	v_cndmask_b32_e64 v107, v63, v123, s[16:17]
	v_cndmask_b32_e64 v108, v60, v52, s[4:5]
	v_cndmask_b32_e64 v109, v61, v53, s[4:5]
	v_cndmask_b32_e64 v110, v62, v54, s[4:5]
	v_cndmask_b32_e64 v111, v63, v55, s[4:5]
	v_mul_f32_dpp v144, v104, v160 row_ror:1 row_mask:0xf bank_mask:0xf
	v_mul_f32_dpp v145, v105, v161 row_ror:1 row_mask:0xf bank_mask:0xf
	v_mul_f32_dpp v146, v106, v162 row_ror:1 row_mask:0xf bank_mask:0xf
	v_mul_f32_dpp v147, v107, v163 row_ror:1 row_mask:0xf bank_mask:0xf
	v_fmac_f32_e32 v144, v60, v164
	v_fmac_f32_e32 v145, v61, v165
	v_fmac_f32_e32 v146, v62, v166
	v_fmac_f32_e32 v147, v63, v167
	v_fmac_f32_dpp v144, v108, v168 row_ror:15 row_mask:0xf bank_mask:0xf
	v_fmac_f32_dpp v145, v109, v169 row_ror:15 row_mask:0xf bank_mask:0xf
	v_fmac_f32_dpp v146, v110, v170 row_ror:15 row_mask:0xf bank_mask:0xf
	v_fmac_f32_dpp v147, v111, v171 row_ror:15 row_mask:0xf bank_mask:0xf
	v_add_f32_e32 v144, v172, v144
	v_add_f32_e32 v145, v173, v145
	v_add_f32_e32 v146, v174, v146
	v_add_f32_e32 v147, v175, v147
	v_cndmask_b32_e64 v104, v56, v124, s[16:17]
	v_cndmask_b32_e64 v105, v57, v125, s[16:17]
	v_cndmask_b32_e64 v106, v58, v126, s[16:17]
	v_cndmask_b32_e64 v107, v59, v127, s[16:17]
	v_cndmask_b32_e64 v108, v56, v48, s[4:5]
	v_cndmask_b32_e64 v109, v57, v49, s[4:5]
	v_cndmask_b32_e64 v110, v58, v50, s[4:5]
	v_cndmask_b32_e64 v111, v59, v51, s[4:5]
	v_mul_f32_dpp v148, v104, v182 row_ror:1 row_mask:0xf bank_mask:0xf
	v_mul_f32_dpp v149, v105, v183 row_ror:1 row_mask:0xf bank_mask:0xf
	v_mul_f32_dpp v150, v106, v184 row_ror:1 row_mask:0xf bank_mask:0xf
	v_mul_f32_dpp v151, v107, v185 row_ror:1 row_mask:0xf bank_mask:0xf
	v_fmac_f32_e32 v148, v56, v186
	v_fmac_f32_e32 v149, v57, v187
	v_fmac_f32_e32 v150, v58, v188
	v_fmac_f32_e32 v151, v59, v189
	v_fmac_f32_dpp v148, v108, v190 row_ror:15 row_mask:0xf bank_mask:0xf
	v_fmac_f32_dpp v149, v109, v191 row_ror:15 row_mask:0xf bank_mask:0xf
	v_fmac_f32_dpp v150, v110, v192 row_ror:15 row_mask:0xf bank_mask:0xf
	v_fmac_f32_dpp v151, v111, v193 row_ror:15 row_mask:0xf bank_mask:0xf
	v_add_f32_e32 v148, v194, v148
	v_add_f32_e32 v149, v195, v149
	v_add_f32_e32 v150, v196, v150
	v_add_f32_e32 v151, v197, v151
	v_fma_f32 v210, |v148|, s10, 1.0
	v_fma_f32 v211, |v149|, s10, 1.0
	v_fma_f32 v212, |v150|, s10, 1.0
	v_fma_f32 v213, |v151|, s10, 1.0
	v_rcp_f32_e32 v210, v210
	v_rcp_f32_e32 v211, v211
	v_rcp_f32_e32 v212, v212
	v_rcp_f32_e32 v213, v213
	v_mul_f32_e32 v218, v148, v148
	v_mul_f32_e32 v219, v149, v149
	v_mul_f32_e32 v220, v150, v150
	v_mul_f32_e32 v221, v151, v151
	v_fmaak_f32 v214, v210, v134, 0xbf3a00e3
	v_fmaak_f32 v215, v211, v134, 0xbf3a00e3
	v_fmaak_f32 v216, v212, v134, 0xbf3a00e3
	v_fmaak_f32 v217, v213, v134, 0xbf3a00e3
	v_fmaak_f32 v214, v214, v210, 0x3f35f0e3
	v_fmaak_f32 v215, v215, v211, 0x3f35f0e3
	v_fmaak_f32 v216, v216, v212, 0x3f35f0e3
	v_fmaak_f32 v217, v217, v213, 0x3f35f0e3
	v_fmaak_f32 v214, v214, v210, 0xbe11a98e
	v_fmaak_f32 v215, v215, v211, 0xbe11a98e
	v_fmaak_f32 v216, v216, v212, 0xbe11a98e
	v_fmaak_f32 v217, v217, v213, 0xbe11a98e
	v_fmaak_f32 v214, v214, v210, 0x3e027906
	v_fmaak_f32 v215, v215, v211, 0x3e027906
	v_fmaak_f32 v216, v216, v212, 0x3e027906
	v_fmaak_f32 v217, v217, v213, 0x3e027906
	v_mul_f32_e32 v214, v214, v210
	v_mul_f32_e32 v215, v215, v211
	v_mul_f32_e32 v216, v216, v212
	v_mul_f32_e32 v217, v217, v213
	v_mul_f32_e32 v218, 0xbf38aa3b, v218
	v_mul_f32_e32 v219, 0xbf38aa3b, v219
	v_mul_f32_e32 v220, 0xbf38aa3b, v220
	v_mul_f32_e32 v221, 0xbf38aa3b, v221
	v_exp_f32_e32 v218, v218
	v_exp_f32_e32 v219, v219
	v_exp_f32_e32 v220, v220
	v_exp_f32_e32 v221, v221
	v_cmp_gt_f32_e64 s[18:19], 0, v148
	v_cmp_gt_f32_e64 s[20:21], 0, v149
	v_cmp_gt_f32_e64 s[44:45], 0, v150
	v_cmp_gt_f32_e64 s[46:47], 0, v151
	v_mul_f32_e32 v218, v218, v214
	v_mul_f32_e32 v219, v219, v215
	v_mul_f32_e32 v220, v220, v216
	v_mul_f32_e32 v221, v221, v217
	v_mul_f32_e32 v222, v148, v218
	v_mul_f32_e32 v223, v149, v219
	v_mul_f32_e32 v224, v150, v220
	v_mul_f32_e32 v225, v151, v221
	v_fma_f32 v210, -v148, v218, v148
	v_fma_f32 v211, -v149, v219, v149
	v_fma_f32 v212, -v150, v220, v150
	v_fma_f32 v213, -v151, v221, v151
	v_cndmask_b32_e64 v222, v210, v222, s[18:19]
	v_cndmask_b32_e64 v223, v211, v223, s[20:21]
	v_cndmask_b32_e64 v224, v212, v224, s[44:45]
	v_cndmask_b32_e64 v225, v213, v225, s[46:47]
	v_mul_f32_e32 v144, v144, v222
	v_mul_f32_e32 v145, v145, v223
	v_mul_f32_e32 v146, v146, v224
	v_mul_f32_e32 v147, v147, v225
	v_cvt_pk_bf16_f32 v204, v144, v145
	v_cvt_pk_bf16_f32 v205, v146, v147
	s_mov_b32 s14, 0x0
	v_lshl_add_u64 v[198:199], v[132:133], 0, s[14:15]
	v_permlane16_swap_b32_e32 v202, v204
	v_permlane16_swap_b32_e32 v203, v205
	s_and_b64 s[18:19], s[4:5], s[66:67]
	s_andn2_b64 s[18:19], exec, s[18:19]
	s_and_saveexec_b64 s[20:21], s[18:19]
	global_store_dwordx4 v[198:199], v[202:205], off
	s_mov_b64 exec, s[20:21]
	ds_read_b128 v[120:123], v135 offset:576
	ds_read_b128 v[124:127], v135 offset:704
	v_cndmask_b32_e64 v104, v52, v60, s[16:17]
	v_cndmask_b32_e64 v105, v53, v61, s[16:17]
	v_cndmask_b32_e64 v106, v54, v62, s[16:17]
	v_cndmask_b32_e64 v107, v55, v63, s[16:17]
	v_cndmask_b32_e64 v108, v52, v44, s[4:5]
	v_cndmask_b32_e64 v109, v53, v45, s[4:5]
	v_cndmask_b32_e64 v110, v54, v46, s[4:5]
	v_cndmask_b32_e64 v111, v55, v47, s[4:5]
	v_mul_f32_dpp v144, v104, v160 row_ror:1 row_mask:0xf bank_mask:0xf
	v_mul_f32_dpp v145, v105, v161 row_ror:1 row_mask:0xf bank_mask:0xf
	v_mul_f32_dpp v146, v106, v162 row_ror:1 row_mask:0xf bank_mask:0xf
	v_mul_f32_dpp v147, v107, v163 row_ror:1 row_mask:0xf bank_mask:0xf
	v_fmac_f32_e32 v144, v52, v164
	v_fmac_f32_e32 v145, v53, v165
	v_fmac_f32_e32 v146, v54, v166
	v_fmac_f32_e32 v147, v55, v167
	v_fmac_f32_dpp v144, v108, v168 row_ror:15 row_mask:0xf bank_mask:0xf
	v_fmac_f32_dpp v145, v109, v169 row_ror:15 row_mask:0xf bank_mask:0xf
	v_fmac_f32_dpp v146, v110, v170 row_ror:15 row_mask:0xf bank_mask:0xf
	v_fmac_f32_dpp v147, v111, v171 row_ror:15 row_mask:0xf bank_mask:0xf
	v_add_f32_e32 v144, v172, v144
	v_add_f32_e32 v145, v173, v145
	v_add_f32_e32 v146, v174, v146
	v_add_f32_e32 v147, v175, v147
	v_cndmask_b32_e64 v104, v48, v56, s[16:17]
	v_cndmask_b32_e64 v105, v49, v57, s[16:17]
	v_cndmask_b32_e64 v106, v50, v58, s[16:17]
	v_cndmask_b32_e64 v107, v51, v59, s[16:17]
	v_cndmask_b32_e64 v108, v48, v40, s[4:5]
	v_cndmask_b32_e64 v109, v49, v41, s[4:5]
	v_cndmask_b32_e64 v110, v50, v42, s[4:5]
	v_cndmask_b32_e64 v111, v51, v43, s[4:5]
	v_mul_f32_dpp v148, v104, v182 row_ror:1 row_mask:0xf bank_mask:0xf
	v_mul_f32_dpp v149, v105, v183 row_ror:1 row_mask:0xf bank_mask:0xf
	v_mul_f32_dpp v150, v106, v184 row_ror:1 row_mask:0xf bank_mask:0xf
	v_mul_f32_dpp v151, v107, v185 row_ror:1 row_mask:0xf bank_mask:0xf
	v_fmac_f32_e32 v148, v48, v186
	v_fmac_f32_e32 v149, v49, v187
	v_fmac_f32_e32 v150, v50, v188
	v_fmac_f32_e32 v151, v51, v189
	v_fmac_f32_dpp v148, v108, v190 row_ror:15 row_mask:0xf bank_mask:0xf
	v_fmac_f32_dpp v149, v109, v191 row_ror:15 row_mask:0xf bank_mask:0xf
	v_fmac_f32_dpp v150, v110, v192 row_ror:15 row_mask:0xf bank_mask:0xf
	v_fmac_f32_dpp v151, v111, v193 row_ror:15 row_mask:0xf bank_mask:0xf
	v_add_f32_e32 v148, v194, v148
	v_add_f32_e32 v149, v195, v149
	v_add_f32_e32 v150, v196, v150
	v_add_f32_e32 v151, v197, v151
	v_fma_f32 v210, |v148|, s10, 1.0
	v_fma_f32 v211, |v149|, s10, 1.0
	v_fma_f32 v212, |v150|, s10, 1.0
	v_fma_f32 v213, |v151|, s10, 1.0
	v_rcp_f32_e32 v210, v210
	v_rcp_f32_e32 v211, v211
	v_rcp_f32_e32 v212, v212
	v_rcp_f32_e32 v213, v213
	v_mul_f32_e32 v218, v148, v148
	v_mul_f32_e32 v219, v149, v149
	v_mul_f32_e32 v220, v150, v150
	v_mul_f32_e32 v221, v151, v151
	v_fmaak_f32 v214, v210, v134, 0xbf3a00e3
	v_fmaak_f32 v215, v211, v134, 0xbf3a00e3
	v_fmaak_f32 v216, v212, v134, 0xbf3a00e3
	v_fmaak_f32 v217, v213, v134, 0xbf3a00e3
	v_fmaak_f32 v214, v214, v210, 0x3f35f0e3
	v_fmaak_f32 v215, v215, v211, 0x3f35f0e3
	v_fmaak_f32 v216, v216, v212, 0x3f35f0e3
	v_fmaak_f32 v217, v217, v213, 0x3f35f0e3
	v_fmaak_f32 v214, v214, v210, 0xbe11a98e
	v_fmaak_f32 v215, v215, v211, 0xbe11a98e
	v_fmaak_f32 v216, v216, v212, 0xbe11a98e
	v_fmaak_f32 v217, v217, v213, 0xbe11a98e
	v_fmaak_f32 v214, v214, v210, 0x3e027906
	v_fmaak_f32 v215, v215, v211, 0x3e027906
	v_fmaak_f32 v216, v216, v212, 0x3e027906
	v_fmaak_f32 v217, v217, v213, 0x3e027906
	v_mul_f32_e32 v214, v214, v210
	v_mul_f32_e32 v215, v215, v211
	v_mul_f32_e32 v216, v216, v212
	v_mul_f32_e32 v217, v217, v213
	v_mul_f32_e32 v218, 0xbf38aa3b, v218
	v_mul_f32_e32 v219, 0xbf38aa3b, v219
	v_mul_f32_e32 v220, 0xbf38aa3b, v220
	v_mul_f32_e32 v221, 0xbf38aa3b, v221
	v_exp_f32_e32 v218, v218
	v_exp_f32_e32 v219, v219
	v_exp_f32_e32 v220, v220
	v_exp_f32_e32 v221, v221
	v_cmp_gt_f32_e64 s[18:19], 0, v148
	v_cmp_gt_f32_e64 s[20:21], 0, v149
	v_cmp_gt_f32_e64 s[44:45], 0, v150
	v_cmp_gt_f32_e64 s[46:47], 0, v151
	v_mul_f32_e32 v218, v218, v214
	v_mul_f32_e32 v219, v219, v215
	v_mul_f32_e32 v220, v220, v216
	v_mul_f32_e32 v221, v221, v217
	v_mul_f32_e32 v222, v148, v218
	v_mul_f32_e32 v223, v149, v219
	v_mul_f32_e32 v224, v150, v220
	v_mul_f32_e32 v225, v151, v221
	v_fma_f32 v210, -v148, v218, v148
	v_fma_f32 v211, -v149, v219, v149
	v_fma_f32 v212, -v150, v220, v150
	v_fma_f32 v213, -v151, v221, v151
	v_cndmask_b32_e64 v222, v210, v222, s[18:19]
	v_cndmask_b32_e64 v223, v211, v223, s[20:21]
	v_cndmask_b32_e64 v224, v212, v224, s[44:45]
	v_cndmask_b32_e64 v225, v213, v225, s[46:47]
	v_mul_f32_e32 v144, v144, v222
	v_mul_f32_e32 v145, v145, v223
	v_mul_f32_e32 v146, v146, v224
	v_mul_f32_e32 v147, v147, v225
	v_cvt_pk_bf16_f32 v130, v144, v145
	v_cvt_pk_bf16_f32 v131, v146, v147
	s_mov_b32 s14, 0x16000
	v_lshl_add_u64 v[198:199], v[132:133], 0, s[14:15]
	v_permlane16_swap_b32_e32 v128, v130
	v_permlane16_swap_b32_e32 v129, v131
	global_store_dwordx4 v[198:199], v[128:131], off
	v_cndmask_b32_e64 v104, v44, v52, s[16:17]
	v_cndmask_b32_e64 v105, v45, v53, s[16:17]
	v_cndmask_b32_e64 v106, v46, v54, s[16:17]
	v_cndmask_b32_e64 v107, v47, v55, s[16:17]
	v_cndmask_b32_e64 v108, v44, v84, s[4:5]
	v_cndmask_b32_e64 v109, v45, v85, s[4:5]
	v_cndmask_b32_e64 v110, v46, v86, s[4:5]
	v_cndmask_b32_e64 v111, v47, v87, s[4:5]
	v_mul_f32_dpp v144, v104, v160 row_ror:1 row_mask:0xf bank_mask:0xf
	v_mul_f32_dpp v145, v105, v161 row_ror:1 row_mask:0xf bank_mask:0xf
	v_mul_f32_dpp v146, v106, v162 row_ror:1 row_mask:0xf bank_mask:0xf
	v_mul_f32_dpp v147, v107, v163 row_ror:1 row_mask:0xf bank_mask:0xf
	v_fmac_f32_e32 v144, v44, v164
	v_fmac_f32_e32 v145, v45, v165
	v_fmac_f32_e32 v146, v46, v166
	v_fmac_f32_e32 v147, v47, v167
	v_fmac_f32_dpp v144, v108, v168 row_ror:15 row_mask:0xf bank_mask:0xf
	v_fmac_f32_dpp v145, v109, v169 row_ror:15 row_mask:0xf bank_mask:0xf
	v_fmac_f32_dpp v146, v110, v170 row_ror:15 row_mask:0xf bank_mask:0xf
	v_fmac_f32_dpp v147, v111, v171 row_ror:15 row_mask:0xf bank_mask:0xf
	v_add_f32_e32 v144, v172, v144
	v_add_f32_e32 v145, v173, v145
	v_add_f32_e32 v146, v174, v146
	v_add_f32_e32 v147, v175, v147
	v_cndmask_b32_e64 v104, v40, v48, s[16:17]
	v_cndmask_b32_e64 v105, v41, v49, s[16:17]
	v_cndmask_b32_e64 v106, v42, v50, s[16:17]
	v_cndmask_b32_e64 v107, v43, v51, s[16:17]
	v_cndmask_b32_e64 v108, v40, v32, s[4:5]
	v_cndmask_b32_e64 v109, v41, v33, s[4:5]
	v_cndmask_b32_e64 v110, v42, v34, s[4:5]
	v_cndmask_b32_e64 v111, v43, v35, s[4:5]
	v_mul_f32_dpp v148, v104, v182 row_ror:1 row_mask:0xf bank_mask:0xf
	v_mul_f32_dpp v149, v105, v183 row_ror:1 row_mask:0xf bank_mask:0xf
	v_mul_f32_dpp v150, v106, v184 row_ror:1 row_mask:0xf bank_mask:0xf
	v_mul_f32_dpp v151, v107, v185 row_ror:1 row_mask:0xf bank_mask:0xf
	v_fmac_f32_e32 v148, v40, v186
	v_fmac_f32_e32 v149, v41, v187
	v_fmac_f32_e32 v150, v42, v188
	v_fmac_f32_e32 v151, v43, v189
	v_fmac_f32_dpp v148, v108, v190 row_ror:15 row_mask:0xf bank_mask:0xf
	v_fmac_f32_dpp v149, v109, v191 row_ror:15 row_mask:0xf bank_mask:0xf
	v_fmac_f32_dpp v150, v110, v192 row_ror:15 row_mask:0xf bank_mask:0xf
	v_fmac_f32_dpp v151, v111, v193 row_ror:15 row_mask:0xf bank_mask:0xf
	v_add_f32_e32 v148, v194, v148
	v_add_f32_e32 v149, v195, v149
	v_add_f32_e32 v150, v196, v150
	v_add_f32_e32 v151, v197, v151
	v_fma_f32 v210, |v148|, s10, 1.0
	v_fma_f32 v211, |v149|, s10, 1.0
	v_fma_f32 v212, |v150|, s10, 1.0
	v_fma_f32 v213, |v151|, s10, 1.0
	v_rcp_f32_e32 v210, v210
	v_rcp_f32_e32 v211, v211
	v_rcp_f32_e32 v212, v212
	v_rcp_f32_e32 v213, v213
	v_mul_f32_e32 v218, v148, v148
	v_mul_f32_e32 v219, v149, v149
	v_mul_f32_e32 v220, v150, v150
	v_mul_f32_e32 v221, v151, v151
	v_fmaak_f32 v214, v210, v134, 0xbf3a00e3
	v_fmaak_f32 v215, v211, v134, 0xbf3a00e3
	v_fmaak_f32 v216, v212, v134, 0xbf3a00e3
	v_fmaak_f32 v217, v213, v134, 0xbf3a00e3
	v_fmaak_f32 v214, v214, v210, 0x3f35f0e3
	v_fmaak_f32 v215, v215, v211, 0x3f35f0e3
	v_fmaak_f32 v216, v216, v212, 0x3f35f0e3
	v_fmaak_f32 v217, v217, v213, 0x3f35f0e3
	v_fmaak_f32 v214, v214, v210, 0xbe11a98e
	v_fmaak_f32 v215, v215, v211, 0xbe11a98e
	v_fmaak_f32 v216, v216, v212, 0xbe11a98e
	v_fmaak_f32 v217, v217, v213, 0xbe11a98e
	v_fmaak_f32 v214, v214, v210, 0x3e027906
	v_fmaak_f32 v215, v215, v211, 0x3e027906
	v_fmaak_f32 v216, v216, v212, 0x3e027906
	v_fmaak_f32 v217, v217, v213, 0x3e027906
	v_mul_f32_e32 v214, v214, v210
	v_mul_f32_e32 v215, v215, v211
	v_mul_f32_e32 v216, v216, v212
	v_mul_f32_e32 v217, v217, v213
	v_mul_f32_e32 v218, 0xbf38aa3b, v218
	v_mul_f32_e32 v219, 0xbf38aa3b, v219
	v_mul_f32_e32 v220, 0xbf38aa3b, v220
	v_mul_f32_e32 v221, 0xbf38aa3b, v221
	v_exp_f32_e32 v218, v218
	v_exp_f32_e32 v219, v219
	v_exp_f32_e32 v220, v220
	v_exp_f32_e32 v221, v221
	v_cmp_gt_f32_e64 s[18:19], 0, v148
	v_cmp_gt_f32_e64 s[20:21], 0, v149
	v_cmp_gt_f32_e64 s[44:45], 0, v150
	v_cmp_gt_f32_e64 s[46:47], 0, v151
	v_mul_f32_e32 v218, v218, v214
	v_mul_f32_e32 v219, v219, v215
	v_mul_f32_e32 v220, v220, v216
	v_mul_f32_e32 v221, v221, v217
	v_mul_f32_e32 v222, v148, v218
	v_mul_f32_e32 v223, v149, v219
	v_mul_f32_e32 v224, v150, v220
	v_mul_f32_e32 v225, v151, v221
	v_fma_f32 v210, -v148, v218, v148
	v_fma_f32 v211, -v149, v219, v149
	v_fma_f32 v212, -v150, v220, v150
	v_fma_f32 v213, -v151, v221, v151
	v_cndmask_b32_e64 v222, v210, v222, s[18:19]
	v_cndmask_b32_e64 v223, v211, v223, s[20:21]
	v_cndmask_b32_e64 v224, v212, v224, s[44:45]
	v_cndmask_b32_e64 v225, v213, v225, s[46:47]
	v_mul_f32_e32 v144, v144, v222
	v_mul_f32_e32 v145, v145, v223
	v_mul_f32_e32 v146, v146, v224
	v_mul_f32_e32 v147, v147, v225
	v_cvt_pk_bf16_f32 v102, v144, v145
	v_cvt_pk_bf16_f32 v103, v146, v147
	s_mov_b32 s14, 0x2c000
	v_lshl_add_u64 v[198:199], v[132:133], 0, s[14:15]
	v_permlane16_swap_b32_e32 v100, v102
	v_permlane16_swap_b32_e32 v101, v103
	global_store_dwordx4 v[198:199], v[100:103], off
	s_waitcnt lgkmcnt(0)
	v_cndmask_b32_e64 v104, v84, v44, s[16:17]
	v_cndmask_b32_e64 v105, v85, v45, s[16:17]
	v_cndmask_b32_e64 v106, v86, v46, s[16:17]
	v_cndmask_b32_e64 v107, v87, v47, s[16:17]
	v_cndmask_b32_e64 v108, v84, v120, s[4:5]
	v_cndmask_b32_e64 v109, v85, v121, s[4:5]
	v_cndmask_b32_e64 v110, v86, v122, s[4:5]
	v_cndmask_b32_e64 v111, v87, v123, s[4:5]
	v_mul_f32_dpp v144, v104, v160 row_ror:1 row_mask:0xf bank_mask:0xf
	v_mul_f32_dpp v145, v105, v161 row_ror:1 row_mask:0xf bank_mask:0xf
	v_mul_f32_dpp v146, v106, v162 row_ror:1 row_mask:0xf bank_mask:0xf
	v_mul_f32_dpp v147, v107, v163 row_ror:1 row_mask:0xf bank_mask:0xf
	v_fmac_f32_e32 v144, v84, v164
	v_fmac_f32_e32 v145, v85, v165
	v_fmac_f32_e32 v146, v86, v166
	v_fmac_f32_e32 v147, v87, v167
	v_fmac_f32_dpp v144, v108, v168 row_ror:15 row_mask:0xf bank_mask:0xf
	v_fmac_f32_dpp v145, v109, v169 row_ror:15 row_mask:0xf bank_mask:0xf
	v_fmac_f32_dpp v146, v110, v170 row_ror:15 row_mask:0xf bank_mask:0xf
	v_fmac_f32_dpp v147, v111, v171 row_ror:15 row_mask:0xf bank_mask:0xf
	v_add_f32_e32 v144, v172, v144
	v_add_f32_e32 v145, v173, v145
	v_add_f32_e32 v146, v174, v146
	v_add_f32_e32 v147, v175, v147
	v_cndmask_b32_e64 v104, v32, v40, s[16:17]
	v_cndmask_b32_e64 v105, v33, v41, s[16:17]
	v_cndmask_b32_e64 v106, v34, v42, s[16:17]
	v_cndmask_b32_e64 v107, v35, v43, s[16:17]
	v_cndmask_b32_e64 v108, v32, v124, s[4:5]
	v_cndmask_b32_e64 v109, v33, v125, s[4:5]
	v_cndmask_b32_e64 v110, v34, v126, s[4:5]
	v_cndmask_b32_e64 v111, v35, v127, s[4:5]
	v_mul_f32_dpp v148, v104, v182 row_ror:1 row_mask:0xf bank_mask:0xf
	v_mul_f32_dpp v149, v105, v183 row_ror:1 row_mask:0xf bank_mask:0xf
	v_mul_f32_dpp v150, v106, v184 row_ror:1 row_mask:0xf bank_mask:0xf
	v_mul_f32_dpp v151, v107, v185 row_ror:1 row_mask:0xf bank_mask:0xf
	v_fmac_f32_e32 v148, v32, v186
	v_fmac_f32_e32 v149, v33, v187
	v_fmac_f32_e32 v150, v34, v188
	v_fmac_f32_e32 v151, v35, v189
	v_fmac_f32_dpp v148, v108, v190 row_ror:15 row_mask:0xf bank_mask:0xf
	v_fmac_f32_dpp v149, v109, v191 row_ror:15 row_mask:0xf bank_mask:0xf
	v_fmac_f32_dpp v150, v110, v192 row_ror:15 row_mask:0xf bank_mask:0xf
	v_fmac_f32_dpp v151, v111, v193 row_ror:15 row_mask:0xf bank_mask:0xf
	v_add_f32_e32 v148, v194, v148
	v_add_f32_e32 v149, v195, v149
	v_add_f32_e32 v150, v196, v150
	v_add_f32_e32 v151, v197, v151
	v_fma_f32 v210, |v148|, s10, 1.0
	v_fma_f32 v211, |v149|, s10, 1.0
	v_fma_f32 v212, |v150|, s10, 1.0
	v_fma_f32 v213, |v151|, s10, 1.0
	v_rcp_f32_e32 v210, v210
	v_rcp_f32_e32 v211, v211
	v_rcp_f32_e32 v212, v212
	v_rcp_f32_e32 v213, v213
	v_mul_f32_e32 v218, v148, v148
	v_mul_f32_e32 v219, v149, v149
	v_mul_f32_e32 v220, v150, v150
	v_mul_f32_e32 v221, v151, v151
	v_fmaak_f32 v214, v210, v134, 0xbf3a00e3
	v_fmaak_f32 v215, v211, v134, 0xbf3a00e3
	v_fmaak_f32 v216, v212, v134, 0xbf3a00e3
	v_fmaak_f32 v217, v213, v134, 0xbf3a00e3
	v_fmaak_f32 v214, v214, v210, 0x3f35f0e3
	v_fmaak_f32 v215, v215, v211, 0x3f35f0e3
	v_fmaak_f32 v216, v216, v212, 0x3f35f0e3
	v_fmaak_f32 v217, v217, v213, 0x3f35f0e3
	v_fmaak_f32 v214, v214, v210, 0xbe11a98e
	v_fmaak_f32 v215, v215, v211, 0xbe11a98e
	v_fmaak_f32 v216, v216, v212, 0xbe11a98e
	v_fmaak_f32 v217, v217, v213, 0xbe11a98e
	v_fmaak_f32 v214, v214, v210, 0x3e027906
	v_fmaak_f32 v215, v215, v211, 0x3e027906
	v_fmaak_f32 v216, v216, v212, 0x3e027906
	v_fmaak_f32 v217, v217, v213, 0x3e027906
	v_mul_f32_e32 v214, v214, v210
	v_mul_f32_e32 v215, v215, v211
	v_mul_f32_e32 v216, v216, v212
	v_mul_f32_e32 v217, v217, v213
	v_mul_f32_e32 v218, 0xbf38aa3b, v218
	v_mul_f32_e32 v219, 0xbf38aa3b, v219
	v_mul_f32_e32 v220, 0xbf38aa3b, v220
	v_mul_f32_e32 v221, 0xbf38aa3b, v221
	v_exp_f32_e32 v218, v218
	v_exp_f32_e32 v219, v219
	v_exp_f32_e32 v220, v220
	v_exp_f32_e32 v221, v221
	v_cmp_gt_f32_e64 s[18:19], 0, v148
	v_cmp_gt_f32_e64 s[20:21], 0, v149
	v_cmp_gt_f32_e64 s[44:45], 0, v150
	v_cmp_gt_f32_e64 s[46:47], 0, v151
	v_mul_f32_e32 v218, v218, v214
	v_mul_f32_e32 v219, v219, v215
	v_mul_f32_e32 v220, v220, v216
	v_mul_f32_e32 v221, v221, v217
	v_mul_f32_e32 v222, v148, v218
	v_mul_f32_e32 v223, v149, v219
	v_mul_f32_e32 v224, v150, v220
	v_mul_f32_e32 v225, v151, v221
	v_fma_f32 v210, -v148, v218, v148
	v_fma_f32 v211, -v149, v219, v149
	v_fma_f32 v212, -v150, v220, v150
	v_fma_f32 v213, -v151, v221, v151
	v_cndmask_b32_e64 v222, v210, v222, s[18:19]
	v_cndmask_b32_e64 v223, v211, v223, s[20:21]
	v_cndmask_b32_e64 v224, v212, v224, s[44:45]
	v_cndmask_b32_e64 v225, v213, v225, s[46:47]
	v_mul_f32_e32 v144, v144, v222
	v_mul_f32_e32 v145, v145, v223
	v_mul_f32_e32 v146, v146, v224
	v_mul_f32_e32 v147, v147, v225
	v_cvt_pk_bf16_f32 v98, v144, v145
	v_cvt_pk_bf16_f32 v99, v146, v147
	s_mov_b32 s14, 0x42000
	v_lshl_add_u64 v[198:199], v[132:133], 0, s[14:15]
	v_permlane16_swap_b32_e32 v96, v98
	v_permlane16_swap_b32_e32 v97, v99
	global_store_dwordx4 v[198:199], v[96:99], off
	ds_read_b128 v[120:123], v228 offset:1088
	ds_read_b128 v[124:127], v228 offset:1216
	s_waitcnt lgkmcnt(0)
	v_cndmask_b32_e64 v104, v28, v120, s[16:17]
	v_cndmask_b32_e64 v105, v29, v121, s[16:17]
	v_cndmask_b32_e64 v106, v30, v122, s[16:17]
	v_cndmask_b32_e64 v107, v31, v123, s[16:17]
	v_cndmask_b32_e64 v108, v28, v20, s[4:5]
	v_cndmask_b32_e64 v109, v29, v21, s[4:5]
	v_cndmask_b32_e64 v110, v30, v22, s[4:5]
	v_cndmask_b32_e64 v111, v31, v23, s[4:5]
	v_mul_f32_dpp v144, v104, v160 row_ror:1 row_mask:0xf bank_mask:0xf
	v_mul_f32_dpp v145, v105, v161 row_ror:1 row_mask:0xf bank_mask:0xf
	v_mul_f32_dpp v146, v106, v162 row_ror:1 row_mask:0xf bank_mask:0xf
	v_mul_f32_dpp v147, v107, v163 row_ror:1 row_mask:0xf bank_mask:0xf
	v_fmac_f32_e32 v144, v28, v164
	v_fmac_f32_e32 v145, v29, v165
	v_fmac_f32_e32 v146, v30, v166
	v_fmac_f32_e32 v147, v31, v167
	v_fmac_f32_dpp v144, v108, v168 row_ror:15 row_mask:0xf bank_mask:0xf
	v_fmac_f32_dpp v145, v109, v169 row_ror:15 row_mask:0xf bank_mask:0xf
	v_fmac_f32_dpp v146, v110, v170 row_ror:15 row_mask:0xf bank_mask:0xf
	v_fmac_f32_dpp v147, v111, v171 row_ror:15 row_mask:0xf bank_mask:0xf
	v_add_f32_e32 v144, v172, v144
	v_add_f32_e32 v145, v173, v145
	v_add_f32_e32 v146, v174, v146
	v_add_f32_e32 v147, v175, v147
	v_cndmask_b32_e64 v104, v24, v124, s[16:17]
	v_cndmask_b32_e64 v105, v25, v125, s[16:17]
	v_cndmask_b32_e64 v106, v26, v126, s[16:17]
	v_cndmask_b32_e64 v107, v27, v127, s[16:17]
	v_cndmask_b32_e64 v108, v24, v16, s[4:5]
	v_cndmask_b32_e64 v109, v25, v17, s[4:5]
	v_cndmask_b32_e64 v110, v26, v18, s[4:5]
	v_cndmask_b32_e64 v111, v27, v19, s[4:5]
	v_mul_f32_dpp v148, v104, v182 row_ror:1 row_mask:0xf bank_mask:0xf
	v_mul_f32_dpp v149, v105, v183 row_ror:1 row_mask:0xf bank_mask:0xf
	v_mul_f32_dpp v150, v106, v184 row_ror:1 row_mask:0xf bank_mask:0xf
	v_mul_f32_dpp v151, v107, v185 row_ror:1 row_mask:0xf bank_mask:0xf
	v_fmac_f32_e32 v148, v24, v186
	v_fmac_f32_e32 v149, v25, v187
	v_fmac_f32_e32 v150, v26, v188
	v_fmac_f32_e32 v151, v27, v189
	v_fmac_f32_dpp v148, v108, v190 row_ror:15 row_mask:0xf bank_mask:0xf
	v_fmac_f32_dpp v149, v109, v191 row_ror:15 row_mask:0xf bank_mask:0xf
	v_fmac_f32_dpp v150, v110, v192 row_ror:15 row_mask:0xf bank_mask:0xf
	v_fmac_f32_dpp v151, v111, v193 row_ror:15 row_mask:0xf bank_mask:0xf
	v_add_f32_e32 v148, v194, v148
	v_add_f32_e32 v149, v195, v149
	v_add_f32_e32 v150, v196, v150
	v_add_f32_e32 v151, v197, v151
	v_fma_f32 v210, |v148|, s10, 1.0
	v_fma_f32 v211, |v149|, s10, 1.0
	v_fma_f32 v212, |v150|, s10, 1.0
	v_fma_f32 v213, |v151|, s10, 1.0
	v_rcp_f32_e32 v210, v210
	v_rcp_f32_e32 v211, v211
	v_rcp_f32_e32 v212, v212
	v_rcp_f32_e32 v213, v213
	v_mul_f32_e32 v218, v148, v148
	v_mul_f32_e32 v219, v149, v149
	v_mul_f32_e32 v220, v150, v150
	v_mul_f32_e32 v221, v151, v151
	v_fmaak_f32 v214, v210, v134, 0xbf3a00e3
	v_fmaak_f32 v215, v211, v134, 0xbf3a00e3
	v_fmaak_f32 v216, v212, v134, 0xbf3a00e3
	v_fmaak_f32 v217, v213, v134, 0xbf3a00e3
	v_fmaak_f32 v214, v214, v210, 0x3f35f0e3
	v_fmaak_f32 v215, v215, v211, 0x3f35f0e3
	v_fmaak_f32 v216, v216, v212, 0x3f35f0e3
	v_fmaak_f32 v217, v217, v213, 0x3f35f0e3
	v_fmaak_f32 v214, v214, v210, 0xbe11a98e
	v_fmaak_f32 v215, v215, v211, 0xbe11a98e
	v_fmaak_f32 v216, v216, v212, 0xbe11a98e
	v_fmaak_f32 v217, v217, v213, 0xbe11a98e
	v_fmaak_f32 v214, v214, v210, 0x3e027906
	v_fmaak_f32 v215, v215, v211, 0x3e027906
	v_fmaak_f32 v216, v216, v212, 0x3e027906
	v_fmaak_f32 v217, v217, v213, 0x3e027906
	v_mul_f32_e32 v214, v214, v210
	v_mul_f32_e32 v215, v215, v211
	v_mul_f32_e32 v216, v216, v212
	v_mul_f32_e32 v217, v217, v213
	v_mul_f32_e32 v218, 0xbf38aa3b, v218
	v_mul_f32_e32 v219, 0xbf38aa3b, v219
	v_mul_f32_e32 v220, 0xbf38aa3b, v220
	v_mul_f32_e32 v221, 0xbf38aa3b, v221
	v_exp_f32_e32 v218, v218
	v_exp_f32_e32 v219, v219
	v_exp_f32_e32 v220, v220
	v_exp_f32_e32 v221, v221
	v_cmp_gt_f32_e64 s[18:19], 0, v148
	v_cmp_gt_f32_e64 s[20:21], 0, v149
	v_cmp_gt_f32_e64 s[44:45], 0, v150
	v_cmp_gt_f32_e64 s[46:47], 0, v151
	v_mul_f32_e32 v218, v218, v214
	v_mul_f32_e32 v219, v219, v215
	v_mul_f32_e32 v220, v220, v216
	v_mul_f32_e32 v221, v221, v217
	v_mul_f32_e32 v222, v148, v218
	v_mul_f32_e32 v223, v149, v219
	v_mul_f32_e32 v224, v150, v220
	v_mul_f32_e32 v225, v151, v221
	v_fma_f32 v210, -v148, v218, v148
	v_fma_f32 v211, -v149, v219, v149
	v_fma_f32 v212, -v150, v220, v150
	v_fma_f32 v213, -v151, v221, v151
	v_cndmask_b32_e64 v222, v210, v222, s[18:19]
	v_cndmask_b32_e64 v223, v211, v223, s[20:21]
	v_cndmask_b32_e64 v224, v212, v224, s[44:45]
	v_cndmask_b32_e64 v225, v213, v225, s[46:47]
	v_mul_f32_e32 v144, v144, v222
	v_mul_f32_e32 v145, v145, v223
	v_mul_f32_e32 v146, v146, v224
	v_mul_f32_e32 v147, v147, v225
	v_cvt_pk_bf16_f32 v158, v144, v145
	v_cvt_pk_bf16_f32 v159, v146, v147
	s_mov_b32 s14, 0xb0000
	v_lshl_add_u64 v[198:199], v[132:133], 0, s[14:15]
	v_permlane16_swap_b32_e32 v156, v158
	v_permlane16_swap_b32_e32 v157, v159
	global_store_dwordx4 v[198:199], v[156:159], off
	s_and_b64 vcc, exec, s[66:67]
	s_cbranch_vccz .Lp6e_z7
	ds_read_b128 v[120:123], v135 offset:1600
	ds_read_b128 v[124:127], v135 offset:1728
	s_branch .Lp6e_d7

.Lp6e_d7:
	v_cndmask_b32_e64 v104, v20, v28, s[16:17]
	v_cndmask_b32_e64 v105, v21, v29, s[16:17]
	v_cndmask_b32_e64 v106, v22, v30, s[16:17]
	v_cndmask_b32_e64 v107, v23, v31, s[16:17]
	v_cndmask_b32_e64 v108, v20, v12, s[4:5]
	v_cndmask_b32_e64 v109, v21, v13, s[4:5]
	v_cndmask_b32_e64 v110, v22, v14, s[4:5]
	v_cndmask_b32_e64 v111, v23, v15, s[4:5]
	v_mul_f32_dpp v144, v104, v160 row_ror:1 row_mask:0xf bank_mask:0xf
	v_mul_f32_dpp v145, v105, v161 row_ror:1 row_mask:0xf bank_mask:0xf
	v_mul_f32_dpp v146, v106, v162 row_ror:1 row_mask:0xf bank_mask:0xf
	v_mul_f32_dpp v147, v107, v163 row_ror:1 row_mask:0xf bank_mask:0xf
	v_fmac_f32_e32 v144, v20, v164
	v_fmac_f32_e32 v145, v21, v165
	v_fmac_f32_e32 v146, v22, v166
	v_fmac_f32_e32 v147, v23, v167
	v_fmac_f32_dpp v144, v108, v168 row_ror:15 row_mask:0xf bank_mask:0xf
	v_fmac_f32_dpp v145, v109, v169 row_ror:15 row_mask:0xf bank_mask:0xf
	v_fmac_f32_dpp v146, v110, v170 row_ror:15 row_mask:0xf bank_mask:0xf
	v_fmac_f32_dpp v147, v111, v171 row_ror:15 row_mask:0xf bank_mask:0xf
	v_add_f32_e32 v144, v172, v144
	v_add_f32_e32 v145, v173, v145
	v_add_f32_e32 v146, v174, v146
	v_add_f32_e32 v147, v175, v147
	v_cndmask_b32_e64 v104, v16, v24, s[16:17]
	v_cndmask_b32_e64 v105, v17, v25, s[16:17]
	v_cndmask_b32_e64 v106, v18, v26, s[16:17]
	v_cndmask_b32_e64 v107, v19, v27, s[16:17]
	v_cndmask_b32_e64 v108, v16, v8, s[4:5]
	v_cndmask_b32_e64 v109, v17, v9, s[4:5]
	v_cndmask_b32_e64 v110, v18, v10, s[4:5]
	v_cndmask_b32_e64 v111, v19, v11, s[4:5]
	v_mul_f32_dpp v148, v104, v182 row_ror:1 row_mask:0xf bank_mask:0xf
	v_mul_f32_dpp v149, v105, v183 row_ror:1 row_mask:0xf bank_mask:0xf
	v_mul_f32_dpp v150, v106, v184 row_ror:1 row_mask:0xf bank_mask:0xf
	v_mul_f32_dpp v151, v107, v185 row_ror:1 row_mask:0xf bank_mask:0xf
	v_fmac_f32_e32 v148, v16, v186
	v_fmac_f32_e32 v149, v17, v187
	v_fmac_f32_e32 v150, v18, v188
	v_fmac_f32_e32 v151, v19, v189
	v_fmac_f32_dpp v148, v108, v190 row_ror:15 row_mask:0xf bank_mask:0xf
	v_fmac_f32_dpp v149, v109, v191 row_ror:15 row_mask:0xf bank_mask:0xf
	v_fmac_f32_dpp v150, v110, v192 row_ror:15 row_mask:0xf bank_mask:0xf
	v_fmac_f32_dpp v151, v111, v193 row_ror:15 row_mask:0xf bank_mask:0xf
	v_add_f32_e32 v148, v194, v148
	v_add_f32_e32 v149, v195, v149
	v_add_f32_e32 v150, v196, v150
	v_add_f32_e32 v151, v197, v151
	v_fma_f32 v210, |v148|, s10, 1.0
	v_fma_f32 v211, |v149|, s10, 1.0
	v_fma_f32 v212, |v150|, s10, 1.0
	v_fma_f32 v213, |v151|, s10, 1.0
	v_rcp_f32_e32 v210, v210
	v_rcp_f32_e32 v211, v211
	v_rcp_f32_e32 v212, v212
	v_rcp_f32_e32 v213, v213
	v_mul_f32_e32 v218, v148, v148
	v_mul_f32_e32 v219, v149, v149
	v_mul_f32_e32 v220, v150, v150
	v_mul_f32_e32 v221, v151, v151
	v_fmaak_f32 v214, v210, v134, 0xbf3a00e3
	v_fmaak_f32 v215, v211, v134, 0xbf3a00e3
	v_fmaak_f32 v216, v212, v134, 0xbf3a00e3
	v_fmaak_f32 v217, v213, v134, 0xbf3a00e3
	v_fmaak_f32 v214, v214, v210, 0x3f35f0e3
	v_fmaak_f32 v215, v215, v211, 0x3f35f0e3
	v_fmaak_f32 v216, v216, v212, 0x3f35f0e3
	v_fmaak_f32 v217, v217, v213, 0x3f35f0e3
	v_fmaak_f32 v214, v214, v210, 0xbe11a98e
	v_fmaak_f32 v215, v215, v211, 0xbe11a98e
	v_fmaak_f32 v216, v216, v212, 0xbe11a98e
	v_fmaak_f32 v217, v217, v213, 0xbe11a98e
	v_fmaak_f32 v214, v214, v210, 0x3e027906
	v_fmaak_f32 v215, v215, v211, 0x3e027906
	v_fmaak_f32 v216, v216, v212, 0x3e027906
	v_fmaak_f32 v217, v217, v213, 0x3e027906
	v_mul_f32_e32 v214, v214, v210
	v_mul_f32_e32 v215, v215, v211
	v_mul_f32_e32 v216, v216, v212
	v_mul_f32_e32 v217, v217, v213
	v_mul_f32_e32 v218, 0xbf38aa3b, v218
	v_mul_f32_e32 v219, 0xbf38aa3b, v219
	v_mul_f32_e32 v220, 0xbf38aa3b, v220
	v_mul_f32_e32 v221, 0xbf38aa3b, v221
	v_exp_f32_e32 v218, v218
	v_exp_f32_e32 v219, v219
	v_exp_f32_e32 v220, v220
	v_exp_f32_e32 v221, v221
	v_cmp_gt_f32_e64 s[18:19], 0, v148
	v_cmp_gt_f32_e64 s[20:21], 0, v149
	v_cmp_gt_f32_e64 s[44:45], 0, v150
	v_cmp_gt_f32_e64 s[46:47], 0, v151
	v_mul_f32_e32 v218, v218, v214
	v_mul_f32_e32 v219, v219, v215
	v_mul_f32_e32 v220, v220, v216
	v_mul_f32_e32 v221, v221, v217
	v_mul_f32_e32 v222, v148, v218
	v_mul_f32_e32 v223, v149, v219
	v_mul_f32_e32 v224, v150, v220
	v_mul_f32_e32 v225, v151, v221
	v_fma_f32 v210, -v148, v218, v148
	v_fma_f32 v211, -v149, v219, v149
	v_fma_f32 v212, -v150, v220, v150
	v_fma_f32 v213, -v151, v221, v151
	v_cndmask_b32_e64 v222, v210, v222, s[18:19]
	v_cndmask_b32_e64 v223, v211, v223, s[20:21]
	v_cndmask_b32_e64 v224, v212, v224, s[44:45]
	v_cndmask_b32_e64 v225, v213, v225, s[46:47]
	v_mul_f32_e32 v144, v144, v222
	v_mul_f32_e32 v145, v145, v223
	v_mul_f32_e32 v146, v146, v224
	v_mul_f32_e32 v147, v147, v225
	v_cvt_pk_bf16_f32 v154, v144, v145
	v_cvt_pk_bf16_f32 v155, v146, v147
	s_mov_b32 s14, 0xc6000
	v_lshl_add_u64 v[198:199], v[132:133], 0, s[14:15]
	v_permlane16_swap_b32_e32 v152, v154
	v_permlane16_swap_b32_e32 v153, v155
	global_store_dwordx4 v[198:199], v[152:155], off
	v_cndmask_b32_e64 v104, v12, v20, s[16:17]
	v_cndmask_b32_e64 v105, v13, v21, s[16:17]
	v_cndmask_b32_e64 v106, v14, v22, s[16:17]
	v_cndmask_b32_e64 v107, v15, v23, s[16:17]
	v_cndmask_b32_e64 v108, v12, v4, s[4:5]
	v_cndmask_b32_e64 v109, v13, v5, s[4:5]
	v_cndmask_b32_e64 v110, v14, v6, s[4:5]
	v_cndmask_b32_e64 v111, v15, v7, s[4:5]
	v_mul_f32_dpp v144, v104, v160 row_ror:1 row_mask:0xf bank_mask:0xf
	v_mul_f32_dpp v145, v105, v161 row_ror:1 row_mask:0xf bank_mask:0xf
	v_mul_f32_dpp v146, v106, v162 row_ror:1 row_mask:0xf bank_mask:0xf
	v_mul_f32_dpp v147, v107, v163 row_ror:1 row_mask:0xf bank_mask:0xf
	v_fmac_f32_e32 v144, v12, v164
	v_fmac_f32_e32 v145, v13, v165
	v_fmac_f32_e32 v146, v14, v166
	v_fmac_f32_e32 v147, v15, v167
	v_fmac_f32_dpp v144, v108, v168 row_ror:15 row_mask:0xf bank_mask:0xf
	v_fmac_f32_dpp v145, v109, v169 row_ror:15 row_mask:0xf bank_mask:0xf
	v_fmac_f32_dpp v146, v110, v170 row_ror:15 row_mask:0xf bank_mask:0xf
	v_fmac_f32_dpp v147, v111, v171 row_ror:15 row_mask:0xf bank_mask:0xf
	v_add_f32_e32 v144, v172, v144
	v_add_f32_e32 v145, v173, v145
	v_add_f32_e32 v146, v174, v146
	v_add_f32_e32 v147, v175, v147
	v_cndmask_b32_e64 v104, v8, v16, s[16:17]
	v_cndmask_b32_e64 v105, v9, v17, s[16:17]
	v_cndmask_b32_e64 v106, v10, v18, s[16:17]
	v_cndmask_b32_e64 v107, v11, v19, s[16:17]
	v_cndmask_b32_e64 v108, v8, v0, s[4:5]
	v_cndmask_b32_e64 v109, v9, v1, s[4:5]
	v_cndmask_b32_e64 v110, v10, v2, s[4:5]
	v_cndmask_b32_e64 v111, v11, v3, s[4:5]
	v_mul_f32_dpp v148, v104, v182 row_ror:1 row_mask:0xf bank_mask:0xf
	v_mul_f32_dpp v149, v105, v183 row_ror:1 row_mask:0xf bank_mask:0xf
	v_mul_f32_dpp v150, v106, v184 row_ror:1 row_mask:0xf bank_mask:0xf
	v_mul_f32_dpp v151, v107, v185 row_ror:1 row_mask:0xf bank_mask:0xf
	v_fmac_f32_e32 v148, v8, v186
	v_fmac_f32_e32 v149, v9, v187
	v_fmac_f32_e32 v150, v10, v188
	v_fmac_f32_e32 v151, v11, v189
	v_fmac_f32_dpp v148, v108, v190 row_ror:15 row_mask:0xf bank_mask:0xf
	v_fmac_f32_dpp v149, v109, v191 row_ror:15 row_mask:0xf bank_mask:0xf
	v_fmac_f32_dpp v150, v110, v192 row_ror:15 row_mask:0xf bank_mask:0xf
	v_fmac_f32_dpp v151, v111, v193 row_ror:15 row_mask:0xf bank_mask:0xf
	v_add_f32_e32 v148, v194, v148
	v_add_f32_e32 v149, v195, v149
	v_add_f32_e32 v150, v196, v150
	v_add_f32_e32 v151, v197, v151
	v_fma_f32 v210, |v148|, s10, 1.0
	v_fma_f32 v211, |v149|, s10, 1.0
	v_fma_f32 v212, |v150|, s10, 1.0
	v_fma_f32 v213, |v151|, s10, 1.0
	v_rcp_f32_e32 v210, v210
	v_rcp_f32_e32 v211, v211
	v_rcp_f32_e32 v212, v212
	v_rcp_f32_e32 v213, v213
	v_mul_f32_e32 v218, v148, v148
	v_mul_f32_e32 v219, v149, v149
	v_mul_f32_e32 v220, v150, v150
	v_mul_f32_e32 v221, v151, v151
	v_fmaak_f32 v214, v210, v134, 0xbf3a00e3
	v_fmaak_f32 v215, v211, v134, 0xbf3a00e3
	v_fmaak_f32 v216, v212, v134, 0xbf3a00e3
	v_fmaak_f32 v217, v213, v134, 0xbf3a00e3
	v_fmaak_f32 v214, v214, v210, 0x3f35f0e3
	v_fmaak_f32 v215, v215, v211, 0x3f35f0e3
	v_fmaak_f32 v216, v216, v212, 0x3f35f0e3
	v_fmaak_f32 v217, v217, v213, 0x3f35f0e3
	v_fmaak_f32 v214, v214, v210, 0xbe11a98e
	v_fmaak_f32 v215, v215, v211, 0xbe11a98e
	v_fmaak_f32 v216, v216, v212, 0xbe11a98e
	v_fmaak_f32 v217, v217, v213, 0xbe11a98e
	v_fmaak_f32 v214, v214, v210, 0x3e027906
	v_fmaak_f32 v215, v215, v211, 0x3e027906
	v_fmaak_f32 v216, v216, v212, 0x3e027906
	v_fmaak_f32 v217, v217, v213, 0x3e027906
	v_mul_f32_e32 v214, v214, v210
	v_mul_f32_e32 v215, v215, v211
	v_mul_f32_e32 v216, v216, v212
	v_mul_f32_e32 v217, v217, v213
	v_mul_f32_e32 v218, 0xbf38aa3b, v218
	v_mul_f32_e32 v219, 0xbf38aa3b, v219
	v_mul_f32_e32 v220, 0xbf38aa3b, v220
	v_mul_f32_e32 v221, 0xbf38aa3b, v221
	v_exp_f32_e32 v218, v218
	v_exp_f32_e32 v219, v219
	v_exp_f32_e32 v220, v220
	v_exp_f32_e32 v221, v221
	v_cmp_gt_f32_e64 s[18:19], 0, v148
	v_cmp_gt_f32_e64 s[20:21], 0, v149
	v_cmp_gt_f32_e64 s[44:45], 0, v150
	v_cmp_gt_f32_e64 s[46:47], 0, v151
	v_mul_f32_e32 v218, v218, v214
	v_mul_f32_e32 v219, v219, v215
	v_mul_f32_e32 v220, v220, v216
	v_mul_f32_e32 v221, v221, v217
	v_mul_f32_e32 v222, v148, v218
	v_mul_f32_e32 v223, v149, v219
	v_mul_f32_e32 v224, v150, v220
	v_mul_f32_e32 v225, v151, v221
	v_fma_f32 v210, -v148, v218, v148
	v_fma_f32 v211, -v149, v219, v149
	v_fma_f32 v212, -v150, v220, v150
	v_fma_f32 v213, -v151, v221, v151
	v_cndmask_b32_e64 v222, v210, v222, s[18:19]
	v_cndmask_b32_e64 v223, v211, v223, s[20:21]
	v_cndmask_b32_e64 v224, v212, v224, s[44:45]
	v_cndmask_b32_e64 v225, v213, v225, s[46:47]
	v_mul_f32_e32 v144, v144, v222
	v_mul_f32_e32 v145, v145, v223
	v_mul_f32_e32 v146, v146, v224
	v_mul_f32_e32 v147, v147, v225
	v_cvt_pk_bf16_f32 v142, v144, v145
	v_cvt_pk_bf16_f32 v143, v146, v147
	s_mov_b32 s14, 0xdc000
	v_lshl_add_u64 v[198:199], v[132:133], 0, s[14:15]
	v_permlane16_swap_b32_e32 v140, v142
	v_permlane16_swap_b32_e32 v141, v143
	global_store_dwordx4 v[198:199], v[140:143], off
	s_waitcnt lgkmcnt(0)
	v_cndmask_b32_e64 v104, v4, v12, s[16:17]
	v_cndmask_b32_e64 v105, v5, v13, s[16:17]
	v_cndmask_b32_e64 v106, v6, v14, s[16:17]
	v_cndmask_b32_e64 v107, v7, v15, s[16:17]
	v_cndmask_b32_e64 v108, v4, v120, s[4:5]
	v_cndmask_b32_e64 v109, v5, v121, s[4:5]
	v_cndmask_b32_e64 v110, v6, v122, s[4:5]
	v_cndmask_b32_e64 v111, v7, v123, s[4:5]
	v_mul_f32_dpp v144, v104, v160 row_ror:1 row_mask:0xf bank_mask:0xf
	v_mul_f32_dpp v145, v105, v161 row_ror:1 row_mask:0xf bank_mask:0xf
	v_mul_f32_dpp v146, v106, v162 row_ror:1 row_mask:0xf bank_mask:0xf
	v_mul_f32_dpp v147, v107, v163 row_ror:1 row_mask:0xf bank_mask:0xf
	v_fmac_f32_e32 v144, v4, v164
	v_fmac_f32_e32 v145, v5, v165
	v_fmac_f32_e32 v146, v6, v166
	v_fmac_f32_e32 v147, v7, v167
	v_fmac_f32_dpp v144, v108, v168 row_ror:15 row_mask:0xf bank_mask:0xf
	v_fmac_f32_dpp v145, v109, v169 row_ror:15 row_mask:0xf bank_mask:0xf
	v_fmac_f32_dpp v146, v110, v170 row_ror:15 row_mask:0xf bank_mask:0xf
	v_fmac_f32_dpp v147, v111, v171 row_ror:15 row_mask:0xf bank_mask:0xf
	v_add_f32_e32 v144, v172, v144
	v_add_f32_e32 v145, v173, v145
	v_add_f32_e32 v146, v174, v146
	v_add_f32_e32 v147, v175, v147
	v_cndmask_b32_e64 v104, v0, v8, s[16:17]
	v_cndmask_b32_e64 v105, v1, v9, s[16:17]
	v_cndmask_b32_e64 v106, v2, v10, s[16:17]
	v_cndmask_b32_e64 v107, v3, v11, s[16:17]
	v_cndmask_b32_e64 v108, v0, v124, s[4:5]
	v_cndmask_b32_e64 v109, v1, v125, s[4:5]
	v_cndmask_b32_e64 v110, v2, v126, s[4:5]
	v_cndmask_b32_e64 v111, v3, v127, s[4:5]
	v_mul_f32_dpp v148, v104, v182 row_ror:1 row_mask:0xf bank_mask:0xf
	v_mul_f32_dpp v149, v105, v183 row_ror:1 row_mask:0xf bank_mask:0xf
	v_mul_f32_dpp v150, v106, v184 row_ror:1 row_mask:0xf bank_mask:0xf
	v_mul_f32_dpp v151, v107, v185 row_ror:1 row_mask:0xf bank_mask:0xf
	v_fmac_f32_e32 v148, v0, v186
	v_fmac_f32_e32 v149, v1, v187
	v_fmac_f32_e32 v150, v2, v188
	v_fmac_f32_e32 v151, v3, v189
	v_fmac_f32_dpp v148, v108, v190 row_ror:15 row_mask:0xf bank_mask:0xf
	v_fmac_f32_dpp v149, v109, v191 row_ror:15 row_mask:0xf bank_mask:0xf
	v_fmac_f32_dpp v150, v110, v192 row_ror:15 row_mask:0xf bank_mask:0xf
	v_fmac_f32_dpp v151, v111, v193 row_ror:15 row_mask:0xf bank_mask:0xf
	v_add_f32_e32 v148, v194, v148
	v_add_f32_e32 v149, v195, v149
	v_add_f32_e32 v150, v196, v150
	v_add_f32_e32 v151, v197, v151
	v_fma_f32 v210, |v148|, s10, 1.0
	v_fma_f32 v211, |v149|, s10, 1.0
	v_fma_f32 v212, |v150|, s10, 1.0
	v_fma_f32 v213, |v151|, s10, 1.0
	v_rcp_f32_e32 v210, v210
	v_rcp_f32_e32 v211, v211
	v_rcp_f32_e32 v212, v212
	v_rcp_f32_e32 v213, v213
	v_mul_f32_e32 v218, v148, v148
	v_mul_f32_e32 v219, v149, v149
	v_mul_f32_e32 v220, v150, v150
	v_mul_f32_e32 v221, v151, v151
	v_fmaak_f32 v214, v210, v134, 0xbf3a00e3
	v_fmaak_f32 v215, v211, v134, 0xbf3a00e3
	v_fmaak_f32 v216, v212, v134, 0xbf3a00e3
	v_fmaak_f32 v217, v213, v134, 0xbf3a00e3
	v_fmaak_f32 v214, v214, v210, 0x3f35f0e3
	v_fmaak_f32 v215, v215, v211, 0x3f35f0e3
	v_fmaak_f32 v216, v216, v212, 0x3f35f0e3
	v_fmaak_f32 v217, v217, v213, 0x3f35f0e3
	v_fmaak_f32 v214, v214, v210, 0xbe11a98e
	v_fmaak_f32 v215, v215, v211, 0xbe11a98e
	v_fmaak_f32 v216, v216, v212, 0xbe11a98e
	v_fmaak_f32 v217, v217, v213, 0xbe11a98e
	v_fmaak_f32 v214, v214, v210, 0x3e027906
	v_fmaak_f32 v215, v215, v211, 0x3e027906
	v_fmaak_f32 v216, v216, v212, 0x3e027906
	v_fmaak_f32 v217, v217, v213, 0x3e027906
	v_mul_f32_e32 v214, v214, v210
	v_mul_f32_e32 v215, v215, v211
	v_mul_f32_e32 v216, v216, v212
	v_mul_f32_e32 v217, v217, v213
	v_mul_f32_e32 v218, 0xbf38aa3b, v218
	v_mul_f32_e32 v219, 0xbf38aa3b, v219
	v_mul_f32_e32 v220, 0xbf38aa3b, v220
	v_mul_f32_e32 v221, 0xbf38aa3b, v221
	v_exp_f32_e32 v218, v218
	v_exp_f32_e32 v219, v219
	v_exp_f32_e32 v220, v220
	v_exp_f32_e32 v221, v221
	v_cmp_gt_f32_e64 s[18:19], 0, v148
	v_cmp_gt_f32_e64 s[20:21], 0, v149
	v_cmp_gt_f32_e64 s[44:45], 0, v150
	v_cmp_gt_f32_e64 s[46:47], 0, v151
	v_mul_f32_e32 v218, v218, v214
	v_mul_f32_e32 v219, v219, v215
	v_mul_f32_e32 v220, v220, v216
	v_mul_f32_e32 v221, v221, v217
	v_mul_f32_e32 v222, v148, v218
	v_mul_f32_e32 v223, v149, v219
	v_mul_f32_e32 v224, v150, v220
	v_mul_f32_e32 v225, v151, v221
	v_fma_f32 v210, -v148, v218, v148
	v_fma_f32 v211, -v149, v219, v149
	v_fma_f32 v212, -v150, v220, v150
	v_fma_f32 v213, -v151, v221, v151
	v_cndmask_b32_e64 v222, v210, v222, s[18:19]
	v_cndmask_b32_e64 v223, v211, v223, s[20:21]
	v_cndmask_b32_e64 v224, v212, v224, s[44:45]
	v_cndmask_b32_e64 v225, v213, v225, s[46:47]
	v_mul_f32_e32 v144, v144, v222
	v_mul_f32_e32 v145, v145, v223
	v_mul_f32_e32 v146, v146, v224
	v_mul_f32_e32 v147, v147, v225
	v_cvt_pk_bf16_f32 v138, v144, v145
	v_cvt_pk_bf16_f32 v139, v146, v147
	s_mov_b32 s14, 0xf2000
	v_lshl_add_u64 v[198:199], v[132:133], 0, s[14:15]
	v_permlane16_swap_b32_e32 v136, v138
	v_permlane16_swap_b32_e32 v137, v139
	s_and_b64 s[18:19], s[16:17], s[6:7]
	s_andn2_b64 s[18:19], exec, s[18:19]
	s_and_saveexec_b64 s[20:21], s[18:19]
	global_store_dwordx4 v[198:199], v[136:139], off
	s_mov_b64 exec, s[20:21]
	s_andn2_b64 vcc, exec, s[42:43]
	s_mov_b64 s[0:1], -1
	s_cbranch_vccnz .LBB0_883
	s_branch .LBB0_1029
